# block-major selected attention: union list of blocks per wave, 4 queries x 4 heads per MFMA column group, K/V of each block loaded once per wave, K double-buffered
# speedup vs baseline: 1.0544x; 1.0235x over previous
.LBB0_1549:
.LBB0_1550:
	s_and_b64 s[16:17], s[12:13], s[14:15]
	s_andn2_b64 s[18:19], s[14:15], s[12:13]
	s_andn2_b64 s[70:71], s[12:13], s[14:15]
	s_nor_b64 s[76:77], s[12:13], s[14:15]
	v_readfirstlane_b32 s46, v70
	v_readfirstlane_b32 s47, v71
	v_readfirstlane_b32 s62, v72
	v_readfirstlane_b32 s63, v73
	v_and_b32_e32 v254, 15, v181
	v_lshrrev_b32_e32 v255, 4, v181
	v_lshrrev_b32_e32 v254, 2, v254
	v_lshlrev_b32_e32 v255, 2, v255
	v_readlane_b32 s23, v243, 32
	v_sub_u32_e32 v83, v254, v255
	v_lshlrev_b32_e32 v82, 4, v181
	s_add_i32 s23, s23, s97
	v_add_u32_e32 v191, s23, v254
	v_mad_u64_u32 v[252:253], s[50:51], v191, v212, v[68:69]
	global_load_dwordx4 v[20:23], v[252:253], off
	global_load_dwordx4 v[24:27], v[252:253], off offset:64
	v_add_u32_e32 v255, 4, v191
	v_mad_u64_u32 v[252:253], s[50:51], v255, v212, v[68:69]
	global_load_dwordx4 v[28:31], v[252:253], off
	global_load_dwordx4 v[32:35], v[252:253], off offset:64
	v_add_u32_e32 v255, 8, v191
	v_mad_u64_u32 v[252:253], s[50:51], v255, v212, v[68:69]
	global_load_dwordx4 v[36:39], v[252:253], off
	global_load_dwordx4 v[40:43], v[252:253], off offset:64
	v_add_u32_e32 v255, 12, v191
	v_mad_u64_u32 v[252:253], s[50:51], v255, v212, v[68:69]
	global_load_dwordx4 v[44:47], v[252:253], off
	global_load_dwordx4 v[48:51], v[252:253], off offset:64
	v_and_b32_e32 v254, 15, v181
	v_lshrrev_b32_e32 v255, 4, v181
	v_lshlrev_b32_e32 v104, 6, v254
	v_lshl_add_u32 v104, v255, 2, v104
	v_add_u32_e32 v104, s96, v104
	v_lshl_add_u32 v105, v254, 2, s96
	ds_read_b32 v12, v104 offset:16384
	ds_read_b32 v13, v104 offset:16400
	ds_read_b32 v14, v104 offset:16416
	ds_read_b32 v15, v104 offset:16432
	ds_read_b32 v16, v105 offset:17408
	v_lshl_add_u32 v105, v181, 2, s96
	v_mov_b32_e32 v17, 1
	v_lshlrev_b32_e32 v17, v254, v17
	s_waitcnt lgkmcnt(0)
	v_mul_f32_e32 v81, 0x3fb8aa3b, v81
	ds_write_b32 v105, v11 offset:16384
	ds_write_b32 v105, v11 offset:16640
	ds_write_b32 v105, v11 offset:16896
	ds_write_b32 v105, v11 offset:17152
	v_cmp_lt_i32_e32 vcc, v255, v16
	v_and_b32_e32 v12, 0xff, v12
	v_lshl_add_u32 v12, v12, 2, s96
	v_cndmask_b32_e32 v18, 0, v17, vcc
	ds_or_b32 v12, v18 offset:16384
	v_add_u32_e32 v18, 4, v255
	v_cmp_lt_i32_e32 vcc, v18, v16
	v_and_b32_e32 v13, 0xff, v13
	v_lshl_add_u32 v13, v13, 2, s96
	v_cndmask_b32_e32 v18, 0, v17, vcc
	ds_or_b32 v13, v18 offset:16384
	v_add_u32_e32 v18, 8, v255
	v_cmp_lt_i32_e32 vcc, v18, v16
	v_and_b32_e32 v14, 0xff, v14
	v_lshl_add_u32 v14, v14, 2, s96
	v_cndmask_b32_e32 v18, 0, v17, vcc
	ds_or_b32 v14, v18 offset:16384
	v_add_u32_e32 v18, 12, v255
	v_cmp_lt_i32_e32 vcc, v18, v16
	v_and_b32_e32 v15, 0xff, v15
	v_lshl_add_u32 v15, v15, 2, s96
	v_cndmask_b32_e32 v18, 0, v17, vcc
	ds_or_b32 v15, v18 offset:16384
	s_waitcnt lgkmcnt(0)
	ds_read_b32 v12, v105 offset:16384
	ds_read_b32 v13, v105 offset:16640
	ds_read_b32 v14, v105 offset:16896
	ds_read_b32 v15, v105 offset:17152
	s_mov_b32 s25, 0
	s_waitcnt lgkmcnt(0)
	v_cmp_ne_u32_e64 s[4:5], 0, v12
	v_lshlrev_b32_e32 v16, 16, v12
	v_add_u32_e32 v17, 0, v181
	v_or_b32_e32 v16, v16, v17
	v_mbcnt_lo_u32_b32 v17, s4, 0
	v_mbcnt_hi_u32_b32 v17, s5, v17
	v_add_u32_e32 v17, s25, v17
	v_lshl_add_u32 v17, v17, 2, s96
	v_add_u32_e32 v17, 0x4000, v17
	v_add_u32_e32 v18, 0x4400, v105
	s_bcnt1_i32_b64 s13, s[4:5]
	v_cndmask_b32_e64 v17, v18, v17, s[4:5]
	s_add_i32 s25, s25, s13
	ds_write_b32 v17, v16
	v_cmp_ne_u32_e64 s[4:5], 0, v13
	v_lshlrev_b32_e32 v16, 16, v13
	v_add_u32_e32 v17, 64, v181
	v_or_b32_e32 v16, v16, v17
	v_mbcnt_lo_u32_b32 v17, s4, 0
	v_mbcnt_hi_u32_b32 v17, s5, v17
	v_add_u32_e32 v17, s25, v17
	v_lshl_add_u32 v17, v17, 2, s96
	v_add_u32_e32 v17, 0x4000, v17
	v_add_u32_e32 v18, 0x4400, v105
	s_bcnt1_i32_b64 s13, s[4:5]
	v_cndmask_b32_e64 v17, v18, v17, s[4:5]
	s_add_i32 s25, s25, s13
	ds_write_b32 v17, v16
	v_cmp_ne_u32_e64 s[4:5], 0, v14
	v_lshlrev_b32_e32 v16, 16, v14
	v_add_u32_e32 v17, 128, v181
	v_or_b32_e32 v16, v16, v17
	v_mbcnt_lo_u32_b32 v17, s4, 0
	v_mbcnt_hi_u32_b32 v17, s5, v17
	v_add_u32_e32 v17, s25, v17
	v_lshl_add_u32 v17, v17, 2, s96
	v_add_u32_e32 v17, 0x4000, v17
	v_add_u32_e32 v18, 0x4400, v105
	s_bcnt1_i32_b64 s13, s[4:5]
	v_cndmask_b32_e64 v17, v18, v17, s[4:5]
	s_add_i32 s25, s25, s13
	ds_write_b32 v17, v16
	v_cmp_ne_u32_e64 s[4:5], 0, v15
	v_lshlrev_b32_e32 v16, 16, v15
	v_add_u32_e32 v17, 192, v181
	v_or_b32_e32 v16, v16, v17
	v_mbcnt_lo_u32_b32 v17, s4, 0
	v_mbcnt_hi_u32_b32 v17, s5, v17
	v_add_u32_e32 v17, s25, v17
	v_lshl_add_u32 v17, v17, 2, s96
	v_add_u32_e32 v17, 0x4000, v17
	v_add_u32_e32 v18, 0x4400, v105
	s_bcnt1_i32_b64 s13, s[4:5]
	v_cndmask_b32_e64 v17, v18, v17, s[4:5]
	s_add_i32 s25, s25, s13
	ds_write_b32 v17, v16
	s_waitcnt vmcnt(0)
	v_lshlrev_b32_e32 v252, 16, v20
	v_and_b32_e32 v68, 0xffff0000, v20
	v_mul_f32_e32 v252, 0x41000000, v252
	v_mul_f32_e32 v68, 0x41000000, v68
	v_lshlrev_b32_e32 v254, 16, v21
	v_and_b32_e32 v255, 0xffff0000, v21
	v_cvt_pk_fp8_f32 v100, v252, v68
	v_mul_f32_e32 v254, 0x41000000, v254
	v_mul_f32_e32 v255, 0x41000000, v255
	s_nop 0
	v_cvt_pk_fp8_f32 v100, v254, v255 op_sel:[0,0,1]
	v_lshlrev_b32_e32 v252, 16, v22
	v_and_b32_e32 v68, 0xffff0000, v22
	v_mul_f32_e32 v252, 0x41000000, v252
	v_mul_f32_e32 v68, 0x41000000, v68
	v_lshlrev_b32_e32 v254, 16, v23
	v_and_b32_e32 v255, 0xffff0000, v23
	v_cvt_pk_fp8_f32 v101, v252, v68
	v_mul_f32_e32 v254, 0x41000000, v254
	v_mul_f32_e32 v255, 0x41000000, v255
	s_nop 0
	v_cvt_pk_fp8_f32 v101, v254, v255 op_sel:[0,0,1]
	v_lshlrev_b32_e32 v252, 16, v24
	v_and_b32_e32 v68, 0xffff0000, v24
	v_mul_f32_e32 v252, 0x41000000, v252
	v_mul_f32_e32 v68, 0x41000000, v68
	v_lshlrev_b32_e32 v254, 16, v25
	v_and_b32_e32 v255, 0xffff0000, v25
	v_cvt_pk_fp8_f32 v102, v252, v68
	v_mul_f32_e32 v254, 0x41000000, v254
	v_mul_f32_e32 v255, 0x41000000, v255
	s_nop 0
	v_cvt_pk_fp8_f32 v102, v254, v255 op_sel:[0,0,1]
	v_lshlrev_b32_e32 v252, 16, v26
	v_and_b32_e32 v68, 0xffff0000, v26
	v_mul_f32_e32 v252, 0x41000000, v252
	v_mul_f32_e32 v68, 0x41000000, v68
	v_lshlrev_b32_e32 v254, 16, v27
	v_and_b32_e32 v255, 0xffff0000, v27
	v_cvt_pk_fp8_f32 v103, v252, v68
	v_mul_f32_e32 v254, 0x41000000, v254
	v_mul_f32_e32 v255, 0x41000000, v255
	s_nop 0
	v_cvt_pk_fp8_f32 v103, v254, v255 op_sel:[0,0,1]
	v_lshlrev_b32_e32 v252, 16, v28
	v_and_b32_e32 v68, 0xffff0000, v28
	v_mul_f32_e32 v252, 0x41000000, v252
	v_mul_f32_e32 v68, 0x41000000, v68
	v_lshlrev_b32_e32 v254, 16, v29
	v_and_b32_e32 v255, 0xffff0000, v29
	v_cvt_pk_fp8_f32 v106, v252, v68
	v_mul_f32_e32 v254, 0x41000000, v254
	v_mul_f32_e32 v255, 0x41000000, v255
	s_nop 0
	v_cvt_pk_fp8_f32 v106, v254, v255 op_sel:[0,0,1]
	v_lshlrev_b32_e32 v252, 16, v30
	v_and_b32_e32 v68, 0xffff0000, v30
	v_mul_f32_e32 v252, 0x41000000, v252
	v_mul_f32_e32 v68, 0x41000000, v68
	v_lshlrev_b32_e32 v254, 16, v31
	v_and_b32_e32 v255, 0xffff0000, v31
	v_cvt_pk_fp8_f32 v107, v252, v68
	v_mul_f32_e32 v254, 0x41000000, v254
	v_mul_f32_e32 v255, 0x41000000, v255
	s_nop 0
	v_cvt_pk_fp8_f32 v107, v254, v255 op_sel:[0,0,1]
	v_lshlrev_b32_e32 v252, 16, v32
	v_and_b32_e32 v68, 0xffff0000, v32
	v_mul_f32_e32 v252, 0x41000000, v252
	v_mul_f32_e32 v68, 0x41000000, v68
	v_lshlrev_b32_e32 v254, 16, v33
	v_and_b32_e32 v255, 0xffff0000, v33
	v_cvt_pk_fp8_f32 v108, v252, v68
	v_mul_f32_e32 v254, 0x41000000, v254
	v_mul_f32_e32 v255, 0x41000000, v255
	s_nop 0
	v_cvt_pk_fp8_f32 v108, v254, v255 op_sel:[0,0,1]
	v_lshlrev_b32_e32 v252, 16, v34
	v_and_b32_e32 v68, 0xffff0000, v34
	v_mul_f32_e32 v252, 0x41000000, v252
	v_mul_f32_e32 v68, 0x41000000, v68
	v_lshlrev_b32_e32 v254, 16, v35
	v_and_b32_e32 v255, 0xffff0000, v35
	v_cvt_pk_fp8_f32 v109, v252, v68
	v_mul_f32_e32 v254, 0x41000000, v254
	v_mul_f32_e32 v255, 0x41000000, v255
	s_nop 0
	v_cvt_pk_fp8_f32 v109, v254, v255 op_sel:[0,0,1]
	v_lshlrev_b32_e32 v252, 16, v36
	v_and_b32_e32 v68, 0xffff0000, v36
	v_mul_f32_e32 v252, 0x41000000, v252
	v_mul_f32_e32 v68, 0x41000000, v68
	v_lshlrev_b32_e32 v254, 16, v37
	v_and_b32_e32 v255, 0xffff0000, v37
	v_cvt_pk_fp8_f32 v110, v252, v68
	v_mul_f32_e32 v254, 0x41000000, v254
	v_mul_f32_e32 v255, 0x41000000, v255
	s_nop 0
	v_cvt_pk_fp8_f32 v110, v254, v255 op_sel:[0,0,1]
	v_lshlrev_b32_e32 v252, 16, v38
	v_and_b32_e32 v68, 0xffff0000, v38
	v_mul_f32_e32 v252, 0x41000000, v252
	v_mul_f32_e32 v68, 0x41000000, v68
	v_lshlrev_b32_e32 v254, 16, v39
	v_and_b32_e32 v255, 0xffff0000, v39
	v_cvt_pk_fp8_f32 v111, v252, v68
	v_mul_f32_e32 v254, 0x41000000, v254
	v_mul_f32_e32 v255, 0x41000000, v255
	s_nop 0
	v_cvt_pk_fp8_f32 v111, v254, v255 op_sel:[0,0,1]
	v_lshlrev_b32_e32 v252, 16, v40
	v_and_b32_e32 v68, 0xffff0000, v40
	v_mul_f32_e32 v252, 0x41000000, v252
	v_mul_f32_e32 v68, 0x41000000, v68
	v_lshlrev_b32_e32 v254, 16, v41
	v_and_b32_e32 v255, 0xffff0000, v41
	v_cvt_pk_fp8_f32 v112, v252, v68
	v_mul_f32_e32 v254, 0x41000000, v254
	v_mul_f32_e32 v255, 0x41000000, v255
	s_nop 0
	v_cvt_pk_fp8_f32 v112, v254, v255 op_sel:[0,0,1]
	v_lshlrev_b32_e32 v252, 16, v42
	v_and_b32_e32 v68, 0xffff0000, v42
	v_mul_f32_e32 v252, 0x41000000, v252
	v_mul_f32_e32 v68, 0x41000000, v68
	v_lshlrev_b32_e32 v254, 16, v43
	v_and_b32_e32 v255, 0xffff0000, v43
	v_cvt_pk_fp8_f32 v113, v252, v68
	v_mul_f32_e32 v254, 0x41000000, v254
	v_mul_f32_e32 v255, 0x41000000, v255
	s_nop 0
	v_cvt_pk_fp8_f32 v113, v254, v255 op_sel:[0,0,1]
	v_lshlrev_b32_e32 v252, 16, v44
	v_and_b32_e32 v68, 0xffff0000, v44
	v_mul_f32_e32 v252, 0x41000000, v252
	v_mul_f32_e32 v68, 0x41000000, v68
	v_lshlrev_b32_e32 v254, 16, v45
	v_and_b32_e32 v255, 0xffff0000, v45
	v_cvt_pk_fp8_f32 v114, v252, v68
	v_mul_f32_e32 v254, 0x41000000, v254
	v_mul_f32_e32 v255, 0x41000000, v255
	s_nop 0
	v_cvt_pk_fp8_f32 v114, v254, v255 op_sel:[0,0,1]
	v_lshlrev_b32_e32 v252, 16, v46
	v_and_b32_e32 v68, 0xffff0000, v46
	v_mul_f32_e32 v252, 0x41000000, v252
	v_mul_f32_e32 v68, 0x41000000, v68
	v_lshlrev_b32_e32 v254, 16, v47
	v_and_b32_e32 v255, 0xffff0000, v47
	v_cvt_pk_fp8_f32 v115, v252, v68
	v_mul_f32_e32 v254, 0x41000000, v254
	v_mul_f32_e32 v255, 0x41000000, v255
	s_nop 0
	v_cvt_pk_fp8_f32 v115, v254, v255 op_sel:[0,0,1]
	v_lshlrev_b32_e32 v252, 16, v48
	v_and_b32_e32 v68, 0xffff0000, v48
	v_mul_f32_e32 v252, 0x41000000, v252
	v_mul_f32_e32 v68, 0x41000000, v68
	v_lshlrev_b32_e32 v254, 16, v49
	v_and_b32_e32 v255, 0xffff0000, v49
	v_cvt_pk_fp8_f32 v116, v252, v68
	v_mul_f32_e32 v254, 0x41000000, v254
	v_mul_f32_e32 v255, 0x41000000, v255
	s_nop 0
	v_cvt_pk_fp8_f32 v116, v254, v255 op_sel:[0,0,1]
	v_lshlrev_b32_e32 v252, 16, v50
	v_and_b32_e32 v68, 0xffff0000, v50
	v_mul_f32_e32 v252, 0x41000000, v252
	v_mul_f32_e32 v68, 0x41000000, v68
	v_lshlrev_b32_e32 v254, 16, v51
	v_and_b32_e32 v255, 0xffff0000, v51
	v_cvt_pk_fp8_f32 v117, v252, v68
	v_mul_f32_e32 v254, 0x41000000, v254
	v_mul_f32_e32 v255, 0x41000000, v255
	s_nop 0
	v_cvt_pk_fp8_f32 v117, v254, v255 op_sel:[0,0,1]
	v_mov_b64_e32 v[20:21], 0
	v_mov_b64_e32 v[22:23], 0
	v_mov_b64_e32 v[24:25], 0
	v_mov_b64_e32 v[26:27], 0
	v_mov_b64_e32 v[28:29], 0
	v_mov_b64_e32 v[30:31], 0
	v_mov_b64_e32 v[32:33], 0
	v_mov_b64_e32 v[34:35], 0
	v_mov_b32_e32 v174, 0
	v_mov_b32_e32 v70, 0
	v_mov_b64_e32 v[36:37], 0
	v_mov_b64_e32 v[38:39], 0
	v_mov_b64_e32 v[40:41], 0
	v_mov_b64_e32 v[42:43], 0
	v_mov_b64_e32 v[44:45], 0
	v_mov_b64_e32 v[46:47], 0
	v_mov_b64_e32 v[48:49], 0
	v_mov_b64_e32 v[50:51], 0
	v_mov_b32_e32 v175, 0
	v_mov_b32_e32 v71, 0
	v_mov_b64_e32 v[52:53], 0
	v_mov_b64_e32 v[54:55], 0
	v_mov_b64_e32 v[56:57], 0
	v_mov_b64_e32 v[58:59], 0
	v_mov_b64_e32 v[60:61], 0
	v_mov_b64_e32 v[62:63], 0
	v_mov_b64_e32 v[64:65], 0
	v_mov_b64_e32 v[66:67], 0
	v_mov_b32_e32 v202, 0
	v_mov_b32_e32 v72, 0
	v_mov_b64_e32 v[84:85], 0
	v_mov_b64_e32 v[86:87], 0
	v_mov_b64_e32 v[88:89], 0
	v_mov_b64_e32 v[90:91], 0
	v_mov_b64_e32 v[92:93], 0
	v_mov_b64_e32 v[94:95], 0
	v_mov_b64_e32 v[96:97], 0
	v_mov_b64_e32 v[98:99], 0
	v_mov_b32_e32 v203, 0
	v_mov_b32_e32 v73, 0
	v_mov_b32_e32 v69, 0xff800000
	v_mov_b32_e32 v253, 0xff800000
	s_waitcnt lgkmcnt(0)
	s_mov_b32 s35, 0
	s_lshl_b32 s13, s35, 2
	s_add_i32 s13, s13, s96
	v_mov_b32_e32 v191, s13
	ds_read_b32 v191, v191 offset:16384
	s_add_i32 s14, s25, -1
	s_min_i32 s14, s14, 1
	s_waitcnt lgkmcnt(0)
	v_readfirstlane_b32 s13, v191
	s_and_b32 s54, s13, 0xffff
	s_lshr_b32 s48, s13, 16
	s_lshl_b32 s13, s14, 2
	s_add_i32 s13, s13, s96
	v_mov_b32_e32 v191, s13
	ds_read_b32 v191, v191 offset:16384
	s_lshl_b32 s12, s54, 12
	s_add_u32 s30, s46, s12
	s_addc_u32 s31, s47, 0
	global_load_dwordx4 v[2:5], v82, s[30:31]
	global_load_dwordx4 v[6:9], v82, s[30:31] offset:1024
	global_load_dwordx4 v[12:15], v82, s[30:31] offset:2048
	global_load_dwordx4 v[16:19], v82, s[30:31] offset:3072
	s_waitcnt lgkmcnt(0)
	v_readfirstlane_b32 s13, v191
	s_and_b32 s15, s13, 0xffff
	s_lshr_b32 s27, s13, 16
.Lbm2_blkA:
	s_lshl_b32 s12, s54, 12
	s_add_u32 s30, s62, s12
	s_addc_u32 s31, s63, 0
	global_load_dwordx4 v[118:121], v82, s[30:31]
	global_load_dwordx4 v[122:125], v82, s[30:31] offset:1024
	global_load_dwordx4 v[126:129], v82, s[30:31] offset:2048
	global_load_dwordx4 v[130:133], v82, s[30:31] offset:3072
	s_lshl_b32 s12, s15, 12
	s_add_u32 s30, s46, s12
	s_addc_u32 s31, s47, 0
	global_load_dwordx4 v[176:179], v82, s[30:31]
	global_load_dwordx4 v[204:207], v82, s[30:31] offset:1024
	global_load_dwordx4 v[208:211], v82, s[30:31] offset:2048
	global_load_dwordx4 v[248:251], v82, s[30:31] offset:3072
	s_add_i32 s14, s35, 2
	s_add_i32 s13, s25, -1
	s_min_i32 s14, s14, s13
	s_lshl_b32 s13, s14, 2
	s_add_i32 s13, s13, s96
	v_mov_b32_e32 v191, s13
	ds_read_b32 v191, v191 offset:16384
	s_cmp_ge_i32 s54, s21
	s_cselect_b32 s14, 1, 0
	s_bfe_u32 s29, s48, 0x40000
	s_cmp_eq_u32 s29, 0
	s_cbranch_scc1 .Lbm2_Ag0_skip
	s_waitcnt vmcnt(8)
	v_mfma_f32_16x16x32_fp8_fp8 v[76:79], v[2:3], v[100:101], 0
	v_mfma_f32_16x16x32_fp8_fp8 v[182:185], v[6:7], v[100:101], 0
	v_mfma_f32_16x16x32_fp8_fp8 v[186:189], v[12:13], v[100:101], 0
	v_mfma_f32_16x16x32_fp8_fp8 v[244:247], v[16:17], v[100:101], 0
	v_mfma_f32_16x16x32_fp8_fp8 v[76:79], v[4:5], v[102:103], v[76:79]
	v_mfma_f32_16x16x32_fp8_fp8 v[182:185], v[8:9], v[102:103], v[182:185]
	v_mfma_f32_16x16x32_fp8_fp8 v[186:189], v[14:15], v[102:103], v[186:189]
	v_mfma_f32_16x16x32_fp8_fp8 v[244:247], v[18:19], v[102:103], v[244:247]
	s_mov_b64 s[4:5], 0
	s_bitcmp1_b32 s29, 0
	s_cselect_b64 s[50:51], s[16:17], 0
	s_or_b64 s[4:5], s[4:5], s[50:51]
	s_bitcmp1_b32 s29, 1
	s_cselect_b64 s[50:51], s[18:19], 0
	s_or_b64 s[4:5], s[4:5], s[50:51]
	s_bitcmp1_b32 s29, 2
	s_cselect_b64 s[50:51], s[70:71], 0
	s_or_b64 s[4:5], s[4:5], s[50:51]
	s_bitcmp1_b32 s29, 3
	s_cselect_b64 s[50:51], s[76:77], 0
	s_or_b64 s[4:5], s[4:5], s[50:51]
	s_cmp_eq_u32 s14, 1
	s_cbranch_scc1 .Lbm2_Ag0_near
	v_add_f32_e32 v190, v81, v174
	v_cndmask_b32_e64 v190, v69, v190, s[4:5]
	v_fmamk_f32 v76, v76, 0x3e38aa3b, v190
	v_fmamk_f32 v77, v77, 0x3e38aa3b, v190
	v_fmamk_f32 v78, v78, 0x3e38aa3b, v190
	v_fmamk_f32 v79, v79, 0x3e38aa3b, v190
	v_fmamk_f32 v182, v182, 0x3e38aa3b, v190
	v_fmamk_f32 v183, v183, 0x3e38aa3b, v190
	v_fmamk_f32 v184, v184, 0x3e38aa3b, v190
	v_fmamk_f32 v185, v185, 0x3e38aa3b, v190
	v_fmamk_f32 v186, v186, 0x3e38aa3b, v190
	v_fmamk_f32 v187, v187, 0x3e38aa3b, v190
	v_fmamk_f32 v188, v188, 0x3e38aa3b, v190
	v_fmamk_f32 v189, v189, 0x3e38aa3b, v190
	v_fmamk_f32 v244, v244, 0x3e38aa3b, v190
	v_fmamk_f32 v245, v245, 0x3e38aa3b, v190
	v_fmamk_f32 v246, v246, 0x3e38aa3b, v190
	v_fmamk_f32 v247, v247, 0x3e38aa3b, v190
.Lbm2_Ag0_max:
	v_max3_f32 v104, v76, v77, v78
	v_max3_f32 v105, v79, v182, v183
	v_max3_f32 v104, v104, v184, v185
	v_max3_f32 v105, v105, v186, v187
	v_max3_f32 v104, v104, v188, v189
	v_max3_f32 v105, v105, v244, v245
	v_max3_f32 v104, v104, v246, v247
	v_max_f32_e32 v104, v104, v105
	v_mov_b32_e32 v105, v104
	s_nop 1
	v_permlane16_swap_b32_e32 v104, v105
	s_nop 0
	v_max_f32_e32 v104, v104, v105
	v_mov_b32_e32 v105, v104
	s_nop 1
	v_permlane32_swap_b32_e32 v104, v105
	s_nop 0
	v_max_f32_e32 v104, v104, v105
	v_cmp_gt_f32_e32 vcc, v104, v253
	s_cbranch_vccnz .Lbm2_Ag0_resc
.Lbm2_Ag0_exp:
	v_exp_f32_e32 v76, v76
	v_exp_f32_e32 v77, v77
	v_exp_f32_e32 v78, v78
	v_exp_f32_e32 v79, v79
	v_exp_f32_e32 v182, v182
	v_exp_f32_e32 v183, v183
	v_exp_f32_e32 v184, v184
	v_exp_f32_e32 v185, v185
	v_exp_f32_e32 v186, v186
	v_exp_f32_e32 v187, v187
	v_exp_f32_e32 v188, v188
	v_exp_f32_e32 v189, v189
	v_exp_f32_e32 v244, v244
	v_exp_f32_e32 v245, v245
	v_exp_f32_e32 v246, v246
	v_exp_f32_e32 v247, v247
	s_nop 0
	v_add_f32_e32 v252, v76, v77
	v_add_f32_e32 v68, v78, v79
	v_add_f32_e32 v254, v182, v183
	v_add_f32_e32 v255, v184, v185
	v_add_f32_e32 v252, v252, v68
	v_add_f32_e32 v254, v254, v255
	v_add_f32_e32 v68, v186, v187
	v_add_f32_e32 v255, v188, v189
	v_add_f32_e32 v252, v252, v254
	v_add_f32_e32 v68, v68, v255
	v_add_f32_e32 v254, v244, v245
	v_add_f32_e32 v255, v246, v247
	v_add_f32_e32 v252, v252, v68
	v_add_f32_e32 v254, v254, v255
	v_add_f32_e32 v252, v252, v254
	v_add_f32_e32 v70, v70, v252
	v_cvt_pk_fp8_f32 v76, v76, v77
	s_nop 0
	v_cvt_pk_fp8_f32 v76, v78, v79 op_sel:[0,0,1]
	v_cvt_pk_fp8_f32 v77, v182, v183
	s_nop 0
	v_cvt_pk_fp8_f32 v77, v184, v185 op_sel:[0,0,1]
	v_cvt_pk_fp8_f32 v78, v186, v187
	s_nop 0
	v_cvt_pk_fp8_f32 v78, v188, v189 op_sel:[0,0,1]
	v_cvt_pk_fp8_f32 v79, v244, v245
	s_nop 0
	v_cvt_pk_fp8_f32 v79, v246, v247 op_sel:[0,0,1]
	s_waitcnt vmcnt(4)
	s_nop 1
	v_mfma_f32_16x16x32_fp8_fp8 v[20:23], v[118:119], v[76:77], v[20:23]
	v_mfma_f32_16x16x32_fp8_fp8 v[24:27], v[120:121], v[76:77], v[24:27]
	v_mfma_f32_16x16x32_fp8_fp8 v[28:31], v[122:123], v[76:77], v[28:31]
	v_mfma_f32_16x16x32_fp8_fp8 v[32:35], v[124:125], v[76:77], v[32:35]
	v_mfma_f32_16x16x32_fp8_fp8 v[20:23], v[126:127], v[78:79], v[20:23]
	v_mfma_f32_16x16x32_fp8_fp8 v[24:27], v[128:129], v[78:79], v[24:27]
	v_mfma_f32_16x16x32_fp8_fp8 v[28:31], v[130:131], v[78:79], v[28:31]
	v_mfma_f32_16x16x32_fp8_fp8 v[32:35], v[132:133], v[78:79], v[32:35]
	s_branch .Lbm2_Ag0_skip
.Lbm2_Ag0_resc:
	v_max_f32_e32 v254, 0, v104
	v_max_f32_e32 v255, v104, v253
	v_exp_f32_e64 v254, -v254
	v_sub_f32_e32 v174, v174, v255
	v_sub_f32_e32 v76, v76, v255
	v_sub_f32_e32 v77, v77, v255
	v_sub_f32_e32 v78, v78, v255
	v_sub_f32_e32 v79, v79, v255
	v_sub_f32_e32 v182, v182, v255
	v_sub_f32_e32 v183, v183, v255
	v_sub_f32_e32 v184, v184, v255
	v_sub_f32_e32 v185, v185, v255
	v_sub_f32_e32 v186, v186, v255
	v_sub_f32_e32 v187, v187, v255
	v_sub_f32_e32 v188, v188, v255
	v_sub_f32_e32 v189, v189, v255
	v_sub_f32_e32 v244, v244, v255
	v_sub_f32_e32 v245, v245, v255
	v_sub_f32_e32 v246, v246, v255
	v_sub_f32_e32 v247, v247, v255
	v_mul_f32_e32 v70, v70, v254
	v_pk_mul_f32 v[20:21], v[20:21], v[254:255] op_sel_hi:[1,0]
	v_pk_mul_f32 v[22:23], v[22:23], v[254:255] op_sel_hi:[1,0]
	v_pk_mul_f32 v[24:25], v[24:25], v[254:255] op_sel_hi:[1,0]
	v_pk_mul_f32 v[26:27], v[26:27], v[254:255] op_sel_hi:[1,0]
	v_pk_mul_f32 v[28:29], v[28:29], v[254:255] op_sel_hi:[1,0]
	v_pk_mul_f32 v[30:31], v[30:31], v[254:255] op_sel_hi:[1,0]
	v_pk_mul_f32 v[32:33], v[32:33], v[254:255] op_sel_hi:[1,0]
	v_pk_mul_f32 v[34:35], v[34:35], v[254:255] op_sel_hi:[1,0]
	s_branch .Lbm2_Ag0_exp
.Lbm2_Ag0_near:
	s_lshl_b32 s13, s54, 6
	s_sub_i32 s13, s97, s13
	v_add_u32_e32 v104, s13, v83
	v_cndmask_b32_e64 v190, v69, v174, s[4:5]
	v_mov_b32_e32 v252, v104
	v_min_u32_e32 v254, 0x7f, v252
	v_lshl_add_u32 v254, v254, 2, v80
	ds_read_b32 v254, v254
	v_subrev_u32_e32 v68, 1, v104
	v_min_u32_e32 v255, 0x7f, v68
	v_lshl_add_u32 v255, v255, 2, v80
	ds_read_b32 v255, v255
	s_waitcnt lgkmcnt(0)
	v_fmamk_f32 v254, v254, 0x3fb8aa3b, v190
	v_cmp_le_i32_e32 vcc, 0, v252
	v_fmamk_f32 v76, v76, 0x3e38aa3b, v254
	s_nop 0
	v_cndmask_b32_e32 v76, v69, v76, vcc
	v_fmamk_f32 v255, v255, 0x3fb8aa3b, v190
	v_cmp_le_i32_e32 vcc, 0, v68
	v_fmamk_f32 v77, v77, 0x3e38aa3b, v255
	s_nop 0
	v_cndmask_b32_e32 v77, v69, v77, vcc
	v_subrev_u32_e32 v252, 2, v104
	v_min_u32_e32 v254, 0x7f, v252
	v_lshl_add_u32 v254, v254, 2, v80
	ds_read_b32 v254, v254
	v_subrev_u32_e32 v68, 3, v104
	v_min_u32_e32 v255, 0x7f, v68
	v_lshl_add_u32 v255, v255, 2, v80
	ds_read_b32 v255, v255
	s_waitcnt lgkmcnt(0)
	v_fmamk_f32 v254, v254, 0x3fb8aa3b, v190
	v_cmp_le_i32_e32 vcc, 0, v252
	v_fmamk_f32 v78, v78, 0x3e38aa3b, v254
	s_nop 0
	v_cndmask_b32_e32 v78, v69, v78, vcc
	v_fmamk_f32 v255, v255, 0x3fb8aa3b, v190
	v_cmp_le_i32_e32 vcc, 0, v68
	v_fmamk_f32 v79, v79, 0x3e38aa3b, v255
	s_nop 0
	v_cndmask_b32_e32 v79, v69, v79, vcc
	v_subrev_u32_e32 v252, 16, v104
	v_min_u32_e32 v254, 0x7f, v252
	v_lshl_add_u32 v254, v254, 2, v80
	ds_read_b32 v254, v254
	v_subrev_u32_e32 v68, 17, v104
	v_min_u32_e32 v255, 0x7f, v68
	v_lshl_add_u32 v255, v255, 2, v80
	ds_read_b32 v255, v255
	s_waitcnt lgkmcnt(0)
	v_fmamk_f32 v254, v254, 0x3fb8aa3b, v190
	v_cmp_le_i32_e32 vcc, 0, v252
	v_fmamk_f32 v182, v182, 0x3e38aa3b, v254
	s_nop 0
	v_cndmask_b32_e32 v182, v69, v182, vcc
	v_fmamk_f32 v255, v255, 0x3fb8aa3b, v190
	v_cmp_le_i32_e32 vcc, 0, v68
	v_fmamk_f32 v183, v183, 0x3e38aa3b, v255
	s_nop 0
	v_cndmask_b32_e32 v183, v69, v183, vcc
	v_subrev_u32_e32 v252, 18, v104
	v_min_u32_e32 v254, 0x7f, v252
	v_lshl_add_u32 v254, v254, 2, v80
	ds_read_b32 v254, v254
	v_subrev_u32_e32 v68, 19, v104
	v_min_u32_e32 v255, 0x7f, v68
	v_lshl_add_u32 v255, v255, 2, v80
	ds_read_b32 v255, v255
	s_waitcnt lgkmcnt(0)
	v_fmamk_f32 v254, v254, 0x3fb8aa3b, v190
	v_cmp_le_i32_e32 vcc, 0, v252
	v_fmamk_f32 v184, v184, 0x3e38aa3b, v254
	s_nop 0
	v_cndmask_b32_e32 v184, v69, v184, vcc
	v_fmamk_f32 v255, v255, 0x3fb8aa3b, v190
	v_cmp_le_i32_e32 vcc, 0, v68
	v_fmamk_f32 v185, v185, 0x3e38aa3b, v255
	s_nop 0
	v_cndmask_b32_e32 v185, v69, v185, vcc
	v_subrev_u32_e32 v252, 32, v104
	v_min_u32_e32 v254, 0x7f, v252
	v_lshl_add_u32 v254, v254, 2, v80
	ds_read_b32 v254, v254
	v_subrev_u32_e32 v68, 33, v104
	v_min_u32_e32 v255, 0x7f, v68
	v_lshl_add_u32 v255, v255, 2, v80
	ds_read_b32 v255, v255
	s_waitcnt lgkmcnt(0)
	v_fmamk_f32 v254, v254, 0x3fb8aa3b, v190
	v_cmp_le_i32_e32 vcc, 0, v252
	v_fmamk_f32 v186, v186, 0x3e38aa3b, v254
	s_nop 0
	v_cndmask_b32_e32 v186, v69, v186, vcc
	v_fmamk_f32 v255, v255, 0x3fb8aa3b, v190
	v_cmp_le_i32_e32 vcc, 0, v68
	v_fmamk_f32 v187, v187, 0x3e38aa3b, v255
	s_nop 0
	v_cndmask_b32_e32 v187, v69, v187, vcc
	v_subrev_u32_e32 v252, 34, v104
	v_min_u32_e32 v254, 0x7f, v252
	v_lshl_add_u32 v254, v254, 2, v80
	ds_read_b32 v254, v254
	v_subrev_u32_e32 v68, 35, v104
	v_min_u32_e32 v255, 0x7f, v68
	v_lshl_add_u32 v255, v255, 2, v80
	ds_read_b32 v255, v255
	s_waitcnt lgkmcnt(0)
	v_fmamk_f32 v254, v254, 0x3fb8aa3b, v190
	v_cmp_le_i32_e32 vcc, 0, v252
	v_fmamk_f32 v188, v188, 0x3e38aa3b, v254
	s_nop 0
	v_cndmask_b32_e32 v188, v69, v188, vcc
	v_fmamk_f32 v255, v255, 0x3fb8aa3b, v190
	v_cmp_le_i32_e32 vcc, 0, v68
	v_fmamk_f32 v189, v189, 0x3e38aa3b, v255
	s_nop 0
	v_cndmask_b32_e32 v189, v69, v189, vcc
	v_subrev_u32_e32 v252, 48, v104
	v_min_u32_e32 v254, 0x7f, v252
	v_lshl_add_u32 v254, v254, 2, v80
	ds_read_b32 v254, v254
	v_subrev_u32_e32 v68, 49, v104
	v_min_u32_e32 v255, 0x7f, v68
	v_lshl_add_u32 v255, v255, 2, v80
	ds_read_b32 v255, v255
	s_waitcnt lgkmcnt(0)
	v_fmamk_f32 v254, v254, 0x3fb8aa3b, v190
	v_cmp_le_i32_e32 vcc, 0, v252
	v_fmamk_f32 v244, v244, 0x3e38aa3b, v254
	s_nop 0
	v_cndmask_b32_e32 v244, v69, v244, vcc
	v_fmamk_f32 v255, v255, 0x3fb8aa3b, v190
	v_cmp_le_i32_e32 vcc, 0, v68
	v_fmamk_f32 v245, v245, 0x3e38aa3b, v255
	s_nop 0
	v_cndmask_b32_e32 v245, v69, v245, vcc
	v_subrev_u32_e32 v252, 50, v104
	v_min_u32_e32 v254, 0x7f, v252
	v_lshl_add_u32 v254, v254, 2, v80
	ds_read_b32 v254, v254
	v_subrev_u32_e32 v68, 51, v104
	v_min_u32_e32 v255, 0x7f, v68
	v_lshl_add_u32 v255, v255, 2, v80
	ds_read_b32 v255, v255
	s_waitcnt lgkmcnt(0)
	v_fmamk_f32 v254, v254, 0x3fb8aa3b, v190
	v_cmp_le_i32_e32 vcc, 0, v252
	v_fmamk_f32 v246, v246, 0x3e38aa3b, v254
	s_nop 0
	v_cndmask_b32_e32 v246, v69, v246, vcc
	v_fmamk_f32 v255, v255, 0x3fb8aa3b, v190
	v_cmp_le_i32_e32 vcc, 0, v68
	v_fmamk_f32 v247, v247, 0x3e38aa3b, v255
	s_nop 0
	v_cndmask_b32_e32 v247, v69, v247, vcc
	s_branch .Lbm2_Ag0_max
.Lbm2_Ag0_skip:
	s_bfe_u32 s29, s48, 0x40004
	s_cmp_eq_u32 s29, 0
	s_cbranch_scc1 .Lbm2_Ag1_skip
	s_waitcnt vmcnt(8)
	v_mfma_f32_16x16x32_fp8_fp8 v[76:79], v[2:3], v[106:107], 0
	v_mfma_f32_16x16x32_fp8_fp8 v[182:185], v[6:7], v[106:107], 0
	v_mfma_f32_16x16x32_fp8_fp8 v[186:189], v[12:13], v[106:107], 0
	v_mfma_f32_16x16x32_fp8_fp8 v[244:247], v[16:17], v[106:107], 0
	v_mfma_f32_16x16x32_fp8_fp8 v[76:79], v[4:5], v[108:109], v[76:79]
	v_mfma_f32_16x16x32_fp8_fp8 v[182:185], v[8:9], v[108:109], v[182:185]
	v_mfma_f32_16x16x32_fp8_fp8 v[186:189], v[14:15], v[108:109], v[186:189]
	v_mfma_f32_16x16x32_fp8_fp8 v[244:247], v[18:19], v[108:109], v[244:247]
	s_mov_b64 s[4:5], 0
	s_bitcmp1_b32 s29, 0
	s_cselect_b64 s[50:51], s[16:17], 0
	s_or_b64 s[4:5], s[4:5], s[50:51]
	s_bitcmp1_b32 s29, 1
	s_cselect_b64 s[50:51], s[18:19], 0
	s_or_b64 s[4:5], s[4:5], s[50:51]
	s_bitcmp1_b32 s29, 2
	s_cselect_b64 s[50:51], s[70:71], 0
	s_or_b64 s[4:5], s[4:5], s[50:51]
	s_bitcmp1_b32 s29, 3
	s_cselect_b64 s[50:51], s[76:77], 0
	s_or_b64 s[4:5], s[4:5], s[50:51]
	s_cmp_eq_u32 s14, 1
	s_cbranch_scc1 .Lbm2_Ag1_near
	v_add_f32_e32 v190, v81, v175
	v_cndmask_b32_e64 v190, v69, v190, s[4:5]
	v_fmamk_f32 v76, v76, 0x3e38aa3b, v190
	v_fmamk_f32 v77, v77, 0x3e38aa3b, v190
	v_fmamk_f32 v78, v78, 0x3e38aa3b, v190
	v_fmamk_f32 v79, v79, 0x3e38aa3b, v190
	v_fmamk_f32 v182, v182, 0x3e38aa3b, v190
	v_fmamk_f32 v183, v183, 0x3e38aa3b, v190
	v_fmamk_f32 v184, v184, 0x3e38aa3b, v190
	v_fmamk_f32 v185, v185, 0x3e38aa3b, v190
	v_fmamk_f32 v186, v186, 0x3e38aa3b, v190
	v_fmamk_f32 v187, v187, 0x3e38aa3b, v190
	v_fmamk_f32 v188, v188, 0x3e38aa3b, v190
	v_fmamk_f32 v189, v189, 0x3e38aa3b, v190
	v_fmamk_f32 v244, v244, 0x3e38aa3b, v190
	v_fmamk_f32 v245, v245, 0x3e38aa3b, v190
	v_fmamk_f32 v246, v246, 0x3e38aa3b, v190
	v_fmamk_f32 v247, v247, 0x3e38aa3b, v190

.Lbm2_Ag1_exp:
	v_exp_f32_e32 v76, v76
	v_exp_f32_e32 v77, v77
	v_exp_f32_e32 v78, v78
	v_exp_f32_e32 v79, v79
	v_exp_f32_e32 v182, v182
	v_exp_f32_e32 v183, v183
	v_exp_f32_e32 v184, v184
	v_exp_f32_e32 v185, v185
	v_exp_f32_e32 v186, v186
	v_exp_f32_e32 v187, v187
	v_exp_f32_e32 v188, v188
	v_exp_f32_e32 v189, v189
	v_exp_f32_e32 v244, v244
	v_exp_f32_e32 v245, v245
	v_exp_f32_e32 v246, v246
	v_exp_f32_e32 v247, v247
	s_nop 0
	v_add_f32_e32 v252, v76, v77
	v_add_f32_e32 v68, v78, v79
	v_add_f32_e32 v254, v182, v183
	v_add_f32_e32 v255, v184, v185
	v_add_f32_e32 v252, v252, v68
	v_add_f32_e32 v254, v254, v255
	v_add_f32_e32 v68, v186, v187
	v_add_f32_e32 v255, v188, v189
	v_add_f32_e32 v252, v252, v254
	v_add_f32_e32 v68, v68, v255
	v_add_f32_e32 v254, v244, v245
	v_add_f32_e32 v255, v246, v247
	v_add_f32_e32 v252, v252, v68
	v_add_f32_e32 v254, v254, v255
	v_add_f32_e32 v252, v252, v254
	v_add_f32_e32 v71, v71, v252
	v_cvt_pk_fp8_f32 v76, v76, v77
	s_nop 0
	v_cvt_pk_fp8_f32 v76, v78, v79 op_sel:[0,0,1]
	v_cvt_pk_fp8_f32 v77, v182, v183
	s_nop 0
	v_cvt_pk_fp8_f32 v77, v184, v185 op_sel:[0,0,1]
	v_cvt_pk_fp8_f32 v78, v186, v187
	s_nop 0
	v_cvt_pk_fp8_f32 v78, v188, v189 op_sel:[0,0,1]
	v_cvt_pk_fp8_f32 v79, v244, v245
	s_nop 0
	v_cvt_pk_fp8_f32 v79, v246, v247 op_sel:[0,0,1]
	s_waitcnt vmcnt(4)
	s_nop 1
	v_mfma_f32_16x16x32_fp8_fp8 v[36:39], v[118:119], v[76:77], v[36:39]
	v_mfma_f32_16x16x32_fp8_fp8 v[40:43], v[120:121], v[76:77], v[40:43]
	v_mfma_f32_16x16x32_fp8_fp8 v[44:47], v[122:123], v[76:77], v[44:47]
	v_mfma_f32_16x16x32_fp8_fp8 v[48:51], v[124:125], v[76:77], v[48:51]
	v_mfma_f32_16x16x32_fp8_fp8 v[36:39], v[126:127], v[78:79], v[36:39]
	v_mfma_f32_16x16x32_fp8_fp8 v[40:43], v[128:129], v[78:79], v[40:43]
	v_mfma_f32_16x16x32_fp8_fp8 v[44:47], v[130:131], v[78:79], v[44:47]
	v_mfma_f32_16x16x32_fp8_fp8 v[48:51], v[132:133], v[78:79], v[48:51]
	s_branch .Lbm2_Ag1_skip
.Lbm2_Ag1_resc:
	v_max_f32_e32 v254, 0, v104
	v_max_f32_e32 v255, v104, v253
	v_exp_f32_e64 v254, -v254
	v_sub_f32_e32 v175, v175, v255
	v_sub_f32_e32 v76, v76, v255
	v_sub_f32_e32 v77, v77, v255
	v_sub_f32_e32 v78, v78, v255
	v_sub_f32_e32 v79, v79, v255
	v_sub_f32_e32 v182, v182, v255
	v_sub_f32_e32 v183, v183, v255
	v_sub_f32_e32 v184, v184, v255
	v_sub_f32_e32 v185, v185, v255
	v_sub_f32_e32 v186, v186, v255
	v_sub_f32_e32 v187, v187, v255
	v_sub_f32_e32 v188, v188, v255
	v_sub_f32_e32 v189, v189, v255
	v_sub_f32_e32 v244, v244, v255
	v_sub_f32_e32 v245, v245, v255
	v_sub_f32_e32 v246, v246, v255
	v_sub_f32_e32 v247, v247, v255
	v_mul_f32_e32 v71, v71, v254
	v_pk_mul_f32 v[36:37], v[36:37], v[254:255] op_sel_hi:[1,0]
	v_pk_mul_f32 v[38:39], v[38:39], v[254:255] op_sel_hi:[1,0]
	v_pk_mul_f32 v[40:41], v[40:41], v[254:255] op_sel_hi:[1,0]
	v_pk_mul_f32 v[42:43], v[42:43], v[254:255] op_sel_hi:[1,0]
	v_pk_mul_f32 v[44:45], v[44:45], v[254:255] op_sel_hi:[1,0]
	v_pk_mul_f32 v[46:47], v[46:47], v[254:255] op_sel_hi:[1,0]
	v_pk_mul_f32 v[48:49], v[48:49], v[254:255] op_sel_hi:[1,0]
	v_pk_mul_f32 v[50:51], v[50:51], v[254:255] op_sel_hi:[1,0]
	s_branch .Lbm2_Ag1_exp
.Lbm2_Ag1_near:
	s_lshl_b32 s13, s54, 6
	s_sub_i32 s13, s97, s13
	s_add_i32 s13, s13, 4
	v_add_u32_e32 v104, s13, v83
	v_cndmask_b32_e64 v190, v69, v175, s[4:5]
	v_mov_b32_e32 v252, v104
	v_min_u32_e32 v254, 0x7f, v252
	v_lshl_add_u32 v254, v254, 2, v80
	ds_read_b32 v254, v254
	v_subrev_u32_e32 v68, 1, v104
	v_min_u32_e32 v255, 0x7f, v68
	v_lshl_add_u32 v255, v255, 2, v80
	ds_read_b32 v255, v255
	s_waitcnt lgkmcnt(0)
	v_fmamk_f32 v254, v254, 0x3fb8aa3b, v190
	v_cmp_le_i32_e32 vcc, 0, v252
	v_fmamk_f32 v76, v76, 0x3e38aa3b, v254
	s_nop 0
	v_cndmask_b32_e32 v76, v69, v76, vcc
	v_fmamk_f32 v255, v255, 0x3fb8aa3b, v190
	v_cmp_le_i32_e32 vcc, 0, v68
	v_fmamk_f32 v77, v77, 0x3e38aa3b, v255
	s_nop 0
	v_cndmask_b32_e32 v77, v69, v77, vcc
	v_subrev_u32_e32 v252, 2, v104
	v_min_u32_e32 v254, 0x7f, v252
	v_lshl_add_u32 v254, v254, 2, v80
	ds_read_b32 v254, v254
	v_subrev_u32_e32 v68, 3, v104
	v_min_u32_e32 v255, 0x7f, v68
	v_lshl_add_u32 v255, v255, 2, v80
	ds_read_b32 v255, v255
	s_waitcnt lgkmcnt(0)
	v_fmamk_f32 v254, v254, 0x3fb8aa3b, v190
	v_cmp_le_i32_e32 vcc, 0, v252
	v_fmamk_f32 v78, v78, 0x3e38aa3b, v254
	s_nop 0
	v_cndmask_b32_e32 v78, v69, v78, vcc
	v_fmamk_f32 v255, v255, 0x3fb8aa3b, v190
	v_cmp_le_i32_e32 vcc, 0, v68
	v_fmamk_f32 v79, v79, 0x3e38aa3b, v255
	s_nop 0
	v_cndmask_b32_e32 v79, v69, v79, vcc
	v_subrev_u32_e32 v252, 16, v104
	v_min_u32_e32 v254, 0x7f, v252
	v_lshl_add_u32 v254, v254, 2, v80
	ds_read_b32 v254, v254
	v_subrev_u32_e32 v68, 17, v104
	v_min_u32_e32 v255, 0x7f, v68
	v_lshl_add_u32 v255, v255, 2, v80
	ds_read_b32 v255, v255
	s_waitcnt lgkmcnt(0)
	v_fmamk_f32 v254, v254, 0x3fb8aa3b, v190
	v_cmp_le_i32_e32 vcc, 0, v252
	v_fmamk_f32 v182, v182, 0x3e38aa3b, v254
	s_nop 0
	v_cndmask_b32_e32 v182, v69, v182, vcc
	v_fmamk_f32 v255, v255, 0x3fb8aa3b, v190
	v_cmp_le_i32_e32 vcc, 0, v68
	v_fmamk_f32 v183, v183, 0x3e38aa3b, v255
	s_nop 0
	v_cndmask_b32_e32 v183, v69, v183, vcc
	v_subrev_u32_e32 v252, 18, v104
	v_min_u32_e32 v254, 0x7f, v252
	v_lshl_add_u32 v254, v254, 2, v80
	ds_read_b32 v254, v254
	v_subrev_u32_e32 v68, 19, v104
	v_min_u32_e32 v255, 0x7f, v68
	v_lshl_add_u32 v255, v255, 2, v80
	ds_read_b32 v255, v255
	s_waitcnt lgkmcnt(0)
	v_fmamk_f32 v254, v254, 0x3fb8aa3b, v190
	v_cmp_le_i32_e32 vcc, 0, v252
	v_fmamk_f32 v184, v184, 0x3e38aa3b, v254
	s_nop 0
	v_cndmask_b32_e32 v184, v69, v184, vcc
	v_fmamk_f32 v255, v255, 0x3fb8aa3b, v190
	v_cmp_le_i32_e32 vcc, 0, v68
	v_fmamk_f32 v185, v185, 0x3e38aa3b, v255
	s_nop 0
	v_cndmask_b32_e32 v185, v69, v185, vcc
	v_subrev_u32_e32 v252, 32, v104
	v_min_u32_e32 v254, 0x7f, v252
	v_lshl_add_u32 v254, v254, 2, v80
	ds_read_b32 v254, v254
	v_subrev_u32_e32 v68, 33, v104
	v_min_u32_e32 v255, 0x7f, v68
	v_lshl_add_u32 v255, v255, 2, v80
	ds_read_b32 v255, v255
	s_waitcnt lgkmcnt(0)
	v_fmamk_f32 v254, v254, 0x3fb8aa3b, v190
	v_cmp_le_i32_e32 vcc, 0, v252
	v_fmamk_f32 v186, v186, 0x3e38aa3b, v254
	s_nop 0
	v_cndmask_b32_e32 v186, v69, v186, vcc
	v_fmamk_f32 v255, v255, 0x3fb8aa3b, v190
	v_cmp_le_i32_e32 vcc, 0, v68
	v_fmamk_f32 v187, v187, 0x3e38aa3b, v255
	s_nop 0
	v_cndmask_b32_e32 v187, v69, v187, vcc
	v_subrev_u32_e32 v252, 34, v104
	v_min_u32_e32 v254, 0x7f, v252
	v_lshl_add_u32 v254, v254, 2, v80
	ds_read_b32 v254, v254
	v_subrev_u32_e32 v68, 35, v104
	v_min_u32_e32 v255, 0x7f, v68
	v_lshl_add_u32 v255, v255, 2, v80
	ds_read_b32 v255, v255
	s_waitcnt lgkmcnt(0)
	v_fmamk_f32 v254, v254, 0x3fb8aa3b, v190
	v_cmp_le_i32_e32 vcc, 0, v252
	v_fmamk_f32 v188, v188, 0x3e38aa3b, v254
	s_nop 0
	v_cndmask_b32_e32 v188, v69, v188, vcc
	v_fmamk_f32 v255, v255, 0x3fb8aa3b, v190
	v_cmp_le_i32_e32 vcc, 0, v68
	v_fmamk_f32 v189, v189, 0x3e38aa3b, v255
	s_nop 0
	v_cndmask_b32_e32 v189, v69, v189, vcc
	v_subrev_u32_e32 v252, 48, v104
	v_min_u32_e32 v254, 0x7f, v252
	v_lshl_add_u32 v254, v254, 2, v80
	ds_read_b32 v254, v254
	v_subrev_u32_e32 v68, 49, v104
	v_min_u32_e32 v255, 0x7f, v68
	v_lshl_add_u32 v255, v255, 2, v80
	ds_read_b32 v255, v255
	s_waitcnt lgkmcnt(0)
	v_fmamk_f32 v254, v254, 0x3fb8aa3b, v190
	v_cmp_le_i32_e32 vcc, 0, v252
	v_fmamk_f32 v244, v244, 0x3e38aa3b, v254
	s_nop 0
	v_cndmask_b32_e32 v244, v69, v244, vcc
	v_fmamk_f32 v255, v255, 0x3fb8aa3b, v190
	v_cmp_le_i32_e32 vcc, 0, v68
	v_fmamk_f32 v245, v245, 0x3e38aa3b, v255
	s_nop 0
	v_cndmask_b32_e32 v245, v69, v245, vcc
	v_subrev_u32_e32 v252, 50, v104
	v_min_u32_e32 v254, 0x7f, v252
	v_lshl_add_u32 v254, v254, 2, v80
	ds_read_b32 v254, v254
	v_subrev_u32_e32 v68, 51, v104
	v_min_u32_e32 v255, 0x7f, v68
	v_lshl_add_u32 v255, v255, 2, v80
	ds_read_b32 v255, v255
	s_waitcnt lgkmcnt(0)
	v_fmamk_f32 v254, v254, 0x3fb8aa3b, v190
	v_cmp_le_i32_e32 vcc, 0, v252
	v_fmamk_f32 v246, v246, 0x3e38aa3b, v254
	s_nop 0
	v_cndmask_b32_e32 v246, v69, v246, vcc
	v_fmamk_f32 v255, v255, 0x3fb8aa3b, v190
	v_cmp_le_i32_e32 vcc, 0, v68
	v_fmamk_f32 v247, v247, 0x3e38aa3b, v255
	s_nop 0
	v_cndmask_b32_e32 v247, v69, v247, vcc
	s_branch .Lbm2_Ag1_max
.Lbm2_Ag1_skip:
	s_bfe_u32 s29, s48, 0x40008
	s_cmp_eq_u32 s29, 0
	s_cbranch_scc1 .Lbm2_Ag2_skip
	s_waitcnt vmcnt(8)
	v_mfma_f32_16x16x32_fp8_fp8 v[76:79], v[2:3], v[110:111], 0
	v_mfma_f32_16x16x32_fp8_fp8 v[182:185], v[6:7], v[110:111], 0
	v_mfma_f32_16x16x32_fp8_fp8 v[186:189], v[12:13], v[110:111], 0
	v_mfma_f32_16x16x32_fp8_fp8 v[244:247], v[16:17], v[110:111], 0
	v_mfma_f32_16x16x32_fp8_fp8 v[76:79], v[4:5], v[112:113], v[76:79]
	v_mfma_f32_16x16x32_fp8_fp8 v[182:185], v[8:9], v[112:113], v[182:185]
	v_mfma_f32_16x16x32_fp8_fp8 v[186:189], v[14:15], v[112:113], v[186:189]
	v_mfma_f32_16x16x32_fp8_fp8 v[244:247], v[18:19], v[112:113], v[244:247]
	s_mov_b64 s[4:5], 0
	s_bitcmp1_b32 s29, 0
	s_cselect_b64 s[50:51], s[16:17], 0
	s_or_b64 s[4:5], s[4:5], s[50:51]
	s_bitcmp1_b32 s29, 1
	s_cselect_b64 s[50:51], s[18:19], 0
	s_or_b64 s[4:5], s[4:5], s[50:51]
	s_bitcmp1_b32 s29, 2
	s_cselect_b64 s[50:51], s[70:71], 0
	s_or_b64 s[4:5], s[4:5], s[50:51]
	s_bitcmp1_b32 s29, 3
	s_cselect_b64 s[50:51], s[76:77], 0
	s_or_b64 s[4:5], s[4:5], s[50:51]
	s_cmp_eq_u32 s14, 1
	s_cbranch_scc1 .Lbm2_Ag2_near
	v_add_f32_e32 v190, v81, v202
	v_cndmask_b32_e64 v190, v69, v190, s[4:5]
	v_fmamk_f32 v76, v76, 0x3e38aa3b, v190
	v_fmamk_f32 v77, v77, 0x3e38aa3b, v190
	v_fmamk_f32 v78, v78, 0x3e38aa3b, v190
	v_fmamk_f32 v79, v79, 0x3e38aa3b, v190
	v_fmamk_f32 v182, v182, 0x3e38aa3b, v190
	v_fmamk_f32 v183, v183, 0x3e38aa3b, v190
	v_fmamk_f32 v184, v184, 0x3e38aa3b, v190
	v_fmamk_f32 v185, v185, 0x3e38aa3b, v190
	v_fmamk_f32 v186, v186, 0x3e38aa3b, v190
	v_fmamk_f32 v187, v187, 0x3e38aa3b, v190
	v_fmamk_f32 v188, v188, 0x3e38aa3b, v190
	v_fmamk_f32 v189, v189, 0x3e38aa3b, v190
	v_fmamk_f32 v244, v244, 0x3e38aa3b, v190
	v_fmamk_f32 v245, v245, 0x3e38aa3b, v190
	v_fmamk_f32 v246, v246, 0x3e38aa3b, v190
	v_fmamk_f32 v247, v247, 0x3e38aa3b, v190

.Lbm2_Ag2_exp:
	v_exp_f32_e32 v76, v76
	v_exp_f32_e32 v77, v77
	v_exp_f32_e32 v78, v78
	v_exp_f32_e32 v79, v79
	v_exp_f32_e32 v182, v182
	v_exp_f32_e32 v183, v183
	v_exp_f32_e32 v184, v184
	v_exp_f32_e32 v185, v185
	v_exp_f32_e32 v186, v186
	v_exp_f32_e32 v187, v187
	v_exp_f32_e32 v188, v188
	v_exp_f32_e32 v189, v189
	v_exp_f32_e32 v244, v244
	v_exp_f32_e32 v245, v245
	v_exp_f32_e32 v246, v246
	v_exp_f32_e32 v247, v247
	s_nop 0
	v_add_f32_e32 v252, v76, v77
	v_add_f32_e32 v68, v78, v79
	v_add_f32_e32 v254, v182, v183
	v_add_f32_e32 v255, v184, v185
	v_add_f32_e32 v252, v252, v68
	v_add_f32_e32 v254, v254, v255
	v_add_f32_e32 v68, v186, v187
	v_add_f32_e32 v255, v188, v189
	v_add_f32_e32 v252, v252, v254
	v_add_f32_e32 v68, v68, v255
	v_add_f32_e32 v254, v244, v245
	v_add_f32_e32 v255, v246, v247
	v_add_f32_e32 v252, v252, v68
	v_add_f32_e32 v254, v254, v255
	v_add_f32_e32 v252, v252, v254
	v_add_f32_e32 v72, v72, v252
	v_cvt_pk_fp8_f32 v76, v76, v77
	s_nop 0
	v_cvt_pk_fp8_f32 v76, v78, v79 op_sel:[0,0,1]
	v_cvt_pk_fp8_f32 v77, v182, v183
	s_nop 0
	v_cvt_pk_fp8_f32 v77, v184, v185 op_sel:[0,0,1]
	v_cvt_pk_fp8_f32 v78, v186, v187
	s_nop 0
	v_cvt_pk_fp8_f32 v78, v188, v189 op_sel:[0,0,1]
	v_cvt_pk_fp8_f32 v79, v244, v245
	s_nop 0
	v_cvt_pk_fp8_f32 v79, v246, v247 op_sel:[0,0,1]
	s_waitcnt vmcnt(4)
	s_nop 1
	v_mfma_f32_16x16x32_fp8_fp8 v[52:55], v[118:119], v[76:77], v[52:55]
	v_mfma_f32_16x16x32_fp8_fp8 v[56:59], v[120:121], v[76:77], v[56:59]
	v_mfma_f32_16x16x32_fp8_fp8 v[60:63], v[122:123], v[76:77], v[60:63]
	v_mfma_f32_16x16x32_fp8_fp8 v[64:67], v[124:125], v[76:77], v[64:67]
	v_mfma_f32_16x16x32_fp8_fp8 v[52:55], v[126:127], v[78:79], v[52:55]
	v_mfma_f32_16x16x32_fp8_fp8 v[56:59], v[128:129], v[78:79], v[56:59]
	v_mfma_f32_16x16x32_fp8_fp8 v[60:63], v[130:131], v[78:79], v[60:63]
	v_mfma_f32_16x16x32_fp8_fp8 v[64:67], v[132:133], v[78:79], v[64:67]
	s_branch .Lbm2_Ag2_skip
.Lbm2_Ag2_resc:
	v_max_f32_e32 v254, 0, v104
	v_max_f32_e32 v255, v104, v253
	v_exp_f32_e64 v254, -v254
	v_sub_f32_e32 v202, v202, v255
	v_sub_f32_e32 v76, v76, v255
	v_sub_f32_e32 v77, v77, v255
	v_sub_f32_e32 v78, v78, v255
	v_sub_f32_e32 v79, v79, v255
	v_sub_f32_e32 v182, v182, v255
	v_sub_f32_e32 v183, v183, v255
	v_sub_f32_e32 v184, v184, v255
	v_sub_f32_e32 v185, v185, v255
	v_sub_f32_e32 v186, v186, v255
	v_sub_f32_e32 v187, v187, v255
	v_sub_f32_e32 v188, v188, v255
	v_sub_f32_e32 v189, v189, v255
	v_sub_f32_e32 v244, v244, v255
	v_sub_f32_e32 v245, v245, v255
	v_sub_f32_e32 v246, v246, v255
	v_sub_f32_e32 v247, v247, v255
	v_mul_f32_e32 v72, v72, v254
	v_pk_mul_f32 v[52:53], v[52:53], v[254:255] op_sel_hi:[1,0]
	v_pk_mul_f32 v[54:55], v[54:55], v[254:255] op_sel_hi:[1,0]
	v_pk_mul_f32 v[56:57], v[56:57], v[254:255] op_sel_hi:[1,0]
	v_pk_mul_f32 v[58:59], v[58:59], v[254:255] op_sel_hi:[1,0]
	v_pk_mul_f32 v[60:61], v[60:61], v[254:255] op_sel_hi:[1,0]
	v_pk_mul_f32 v[62:63], v[62:63], v[254:255] op_sel_hi:[1,0]
	v_pk_mul_f32 v[64:65], v[64:65], v[254:255] op_sel_hi:[1,0]
	v_pk_mul_f32 v[66:67], v[66:67], v[254:255] op_sel_hi:[1,0]
	s_branch .Lbm2_Ag2_exp
.Lbm2_Ag2_near:
	s_lshl_b32 s13, s54, 6
	s_sub_i32 s13, s97, s13
	s_add_i32 s13, s13, 8
	v_add_u32_e32 v104, s13, v83
	v_cndmask_b32_e64 v190, v69, v202, s[4:5]
	v_mov_b32_e32 v252, v104
	v_min_u32_e32 v254, 0x7f, v252
	v_lshl_add_u32 v254, v254, 2, v80
	ds_read_b32 v254, v254
	v_subrev_u32_e32 v68, 1, v104
	v_min_u32_e32 v255, 0x7f, v68
	v_lshl_add_u32 v255, v255, 2, v80
	ds_read_b32 v255, v255
	s_waitcnt lgkmcnt(0)
	v_fmamk_f32 v254, v254, 0x3fb8aa3b, v190
	v_cmp_le_i32_e32 vcc, 0, v252
	v_fmamk_f32 v76, v76, 0x3e38aa3b, v254
	s_nop 0
	v_cndmask_b32_e32 v76, v69, v76, vcc
	v_fmamk_f32 v255, v255, 0x3fb8aa3b, v190
	v_cmp_le_i32_e32 vcc, 0, v68
	v_fmamk_f32 v77, v77, 0x3e38aa3b, v255
	s_nop 0
	v_cndmask_b32_e32 v77, v69, v77, vcc
	v_subrev_u32_e32 v252, 2, v104
	v_min_u32_e32 v254, 0x7f, v252
	v_lshl_add_u32 v254, v254, 2, v80
	ds_read_b32 v254, v254
	v_subrev_u32_e32 v68, 3, v104
	v_min_u32_e32 v255, 0x7f, v68
	v_lshl_add_u32 v255, v255, 2, v80
	ds_read_b32 v255, v255
	s_waitcnt lgkmcnt(0)
	v_fmamk_f32 v254, v254, 0x3fb8aa3b, v190
	v_cmp_le_i32_e32 vcc, 0, v252
	v_fmamk_f32 v78, v78, 0x3e38aa3b, v254
	s_nop 0
	v_cndmask_b32_e32 v78, v69, v78, vcc
	v_fmamk_f32 v255, v255, 0x3fb8aa3b, v190
	v_cmp_le_i32_e32 vcc, 0, v68
	v_fmamk_f32 v79, v79, 0x3e38aa3b, v255
	s_nop 0
	v_cndmask_b32_e32 v79, v69, v79, vcc
	v_subrev_u32_e32 v252, 16, v104
	v_min_u32_e32 v254, 0x7f, v252
	v_lshl_add_u32 v254, v254, 2, v80
	ds_read_b32 v254, v254
	v_subrev_u32_e32 v68, 17, v104
	v_min_u32_e32 v255, 0x7f, v68
	v_lshl_add_u32 v255, v255, 2, v80
	ds_read_b32 v255, v255
	s_waitcnt lgkmcnt(0)
	v_fmamk_f32 v254, v254, 0x3fb8aa3b, v190
	v_cmp_le_i32_e32 vcc, 0, v252
	v_fmamk_f32 v182, v182, 0x3e38aa3b, v254
	s_nop 0
	v_cndmask_b32_e32 v182, v69, v182, vcc
	v_fmamk_f32 v255, v255, 0x3fb8aa3b, v190
	v_cmp_le_i32_e32 vcc, 0, v68
	v_fmamk_f32 v183, v183, 0x3e38aa3b, v255
	s_nop 0
	v_cndmask_b32_e32 v183, v69, v183, vcc
	v_subrev_u32_e32 v252, 18, v104
	v_min_u32_e32 v254, 0x7f, v252
	v_lshl_add_u32 v254, v254, 2, v80
	ds_read_b32 v254, v254
	v_subrev_u32_e32 v68, 19, v104
	v_min_u32_e32 v255, 0x7f, v68
	v_lshl_add_u32 v255, v255, 2, v80
	ds_read_b32 v255, v255
	s_waitcnt lgkmcnt(0)
	v_fmamk_f32 v254, v254, 0x3fb8aa3b, v190
	v_cmp_le_i32_e32 vcc, 0, v252
	v_fmamk_f32 v184, v184, 0x3e38aa3b, v254
	s_nop 0
	v_cndmask_b32_e32 v184, v69, v184, vcc
	v_fmamk_f32 v255, v255, 0x3fb8aa3b, v190
	v_cmp_le_i32_e32 vcc, 0, v68
	v_fmamk_f32 v185, v185, 0x3e38aa3b, v255
	s_nop 0
	v_cndmask_b32_e32 v185, v69, v185, vcc
	v_subrev_u32_e32 v252, 32, v104
	v_min_u32_e32 v254, 0x7f, v252
	v_lshl_add_u32 v254, v254, 2, v80
	ds_read_b32 v254, v254
	v_subrev_u32_e32 v68, 33, v104
	v_min_u32_e32 v255, 0x7f, v68
	v_lshl_add_u32 v255, v255, 2, v80
	ds_read_b32 v255, v255
	s_waitcnt lgkmcnt(0)
	v_fmamk_f32 v254, v254, 0x3fb8aa3b, v190
	v_cmp_le_i32_e32 vcc, 0, v252
	v_fmamk_f32 v186, v186, 0x3e38aa3b, v254
	s_nop 0
	v_cndmask_b32_e32 v186, v69, v186, vcc
	v_fmamk_f32 v255, v255, 0x3fb8aa3b, v190
	v_cmp_le_i32_e32 vcc, 0, v68
	v_fmamk_f32 v187, v187, 0x3e38aa3b, v255
	s_nop 0
	v_cndmask_b32_e32 v187, v69, v187, vcc
	v_subrev_u32_e32 v252, 34, v104
	v_min_u32_e32 v254, 0x7f, v252
	v_lshl_add_u32 v254, v254, 2, v80
	ds_read_b32 v254, v254
	v_subrev_u32_e32 v68, 35, v104
	v_min_u32_e32 v255, 0x7f, v68
	v_lshl_add_u32 v255, v255, 2, v80
	ds_read_b32 v255, v255
	s_waitcnt lgkmcnt(0)
	v_fmamk_f32 v254, v254, 0x3fb8aa3b, v190
	v_cmp_le_i32_e32 vcc, 0, v252
	v_fmamk_f32 v188, v188, 0x3e38aa3b, v254
	s_nop 0
	v_cndmask_b32_e32 v188, v69, v188, vcc
	v_fmamk_f32 v255, v255, 0x3fb8aa3b, v190
	v_cmp_le_i32_e32 vcc, 0, v68
	v_fmamk_f32 v189, v189, 0x3e38aa3b, v255
	s_nop 0
	v_cndmask_b32_e32 v189, v69, v189, vcc
	v_subrev_u32_e32 v252, 48, v104
	v_min_u32_e32 v254, 0x7f, v252
	v_lshl_add_u32 v254, v254, 2, v80
	ds_read_b32 v254, v254
	v_subrev_u32_e32 v68, 49, v104
	v_min_u32_e32 v255, 0x7f, v68
	v_lshl_add_u32 v255, v255, 2, v80
	ds_read_b32 v255, v255
	s_waitcnt lgkmcnt(0)
	v_fmamk_f32 v254, v254, 0x3fb8aa3b, v190
	v_cmp_le_i32_e32 vcc, 0, v252
	v_fmamk_f32 v244, v244, 0x3e38aa3b, v254
	s_nop 0
	v_cndmask_b32_e32 v244, v69, v244, vcc
	v_fmamk_f32 v255, v255, 0x3fb8aa3b, v190
	v_cmp_le_i32_e32 vcc, 0, v68
	v_fmamk_f32 v245, v245, 0x3e38aa3b, v255
	s_nop 0
	v_cndmask_b32_e32 v245, v69, v245, vcc
	v_subrev_u32_e32 v252, 50, v104
	v_min_u32_e32 v254, 0x7f, v252
	v_lshl_add_u32 v254, v254, 2, v80
	ds_read_b32 v254, v254
	v_subrev_u32_e32 v68, 51, v104
	v_min_u32_e32 v255, 0x7f, v68
	v_lshl_add_u32 v255, v255, 2, v80
	ds_read_b32 v255, v255
	s_waitcnt lgkmcnt(0)
	v_fmamk_f32 v254, v254, 0x3fb8aa3b, v190
	v_cmp_le_i32_e32 vcc, 0, v252
	v_fmamk_f32 v246, v246, 0x3e38aa3b, v254
	s_nop 0
	v_cndmask_b32_e32 v246, v69, v246, vcc
	v_fmamk_f32 v255, v255, 0x3fb8aa3b, v190
	v_cmp_le_i32_e32 vcc, 0, v68
	v_fmamk_f32 v247, v247, 0x3e38aa3b, v255
	s_nop 0
	v_cndmask_b32_e32 v247, v69, v247, vcc
	s_branch .Lbm2_Ag2_max
.Lbm2_Ag2_skip:
	s_bfe_u32 s29, s48, 0x4000c
	s_cmp_eq_u32 s29, 0
	s_cbranch_scc1 .Lbm2_Ag3_skip
	s_waitcnt vmcnt(8)
	v_mfma_f32_16x16x32_fp8_fp8 v[76:79], v[2:3], v[114:115], 0
	v_mfma_f32_16x16x32_fp8_fp8 v[182:185], v[6:7], v[114:115], 0
	v_mfma_f32_16x16x32_fp8_fp8 v[186:189], v[12:13], v[114:115], 0
	v_mfma_f32_16x16x32_fp8_fp8 v[244:247], v[16:17], v[114:115], 0
	v_mfma_f32_16x16x32_fp8_fp8 v[76:79], v[4:5], v[116:117], v[76:79]
	v_mfma_f32_16x16x32_fp8_fp8 v[182:185], v[8:9], v[116:117], v[182:185]
	v_mfma_f32_16x16x32_fp8_fp8 v[186:189], v[14:15], v[116:117], v[186:189]
	v_mfma_f32_16x16x32_fp8_fp8 v[244:247], v[18:19], v[116:117], v[244:247]
	s_mov_b64 s[4:5], 0
	s_bitcmp1_b32 s29, 0
	s_cselect_b64 s[50:51], s[16:17], 0
	s_or_b64 s[4:5], s[4:5], s[50:51]
	s_bitcmp1_b32 s29, 1
	s_cselect_b64 s[50:51], s[18:19], 0
	s_or_b64 s[4:5], s[4:5], s[50:51]
	s_bitcmp1_b32 s29, 2
	s_cselect_b64 s[50:51], s[70:71], 0
	s_or_b64 s[4:5], s[4:5], s[50:51]
	s_bitcmp1_b32 s29, 3
	s_cselect_b64 s[50:51], s[76:77], 0
	s_or_b64 s[4:5], s[4:5], s[50:51]
	s_cmp_eq_u32 s14, 1
	s_cbranch_scc1 .Lbm2_Ag3_near
	v_add_f32_e32 v190, v81, v203
	v_cndmask_b32_e64 v190, v69, v190, s[4:5]
	v_fmamk_f32 v76, v76, 0x3e38aa3b, v190
	v_fmamk_f32 v77, v77, 0x3e38aa3b, v190
	v_fmamk_f32 v78, v78, 0x3e38aa3b, v190
	v_fmamk_f32 v79, v79, 0x3e38aa3b, v190
	v_fmamk_f32 v182, v182, 0x3e38aa3b, v190
	v_fmamk_f32 v183, v183, 0x3e38aa3b, v190
	v_fmamk_f32 v184, v184, 0x3e38aa3b, v190
	v_fmamk_f32 v185, v185, 0x3e38aa3b, v190
	v_fmamk_f32 v186, v186, 0x3e38aa3b, v190
	v_fmamk_f32 v187, v187, 0x3e38aa3b, v190
	v_fmamk_f32 v188, v188, 0x3e38aa3b, v190
	v_fmamk_f32 v189, v189, 0x3e38aa3b, v190
	v_fmamk_f32 v244, v244, 0x3e38aa3b, v190
	v_fmamk_f32 v245, v245, 0x3e38aa3b, v190
	v_fmamk_f32 v246, v246, 0x3e38aa3b, v190
	v_fmamk_f32 v247, v247, 0x3e38aa3b, v190

.Lbm2_Ag3_exp:
	v_exp_f32_e32 v76, v76
	v_exp_f32_e32 v77, v77
	v_exp_f32_e32 v78, v78
	v_exp_f32_e32 v79, v79
	v_exp_f32_e32 v182, v182
	v_exp_f32_e32 v183, v183
	v_exp_f32_e32 v184, v184
	v_exp_f32_e32 v185, v185
	v_exp_f32_e32 v186, v186
	v_exp_f32_e32 v187, v187
	v_exp_f32_e32 v188, v188
	v_exp_f32_e32 v189, v189
	v_exp_f32_e32 v244, v244
	v_exp_f32_e32 v245, v245
	v_exp_f32_e32 v246, v246
	v_exp_f32_e32 v247, v247
	s_nop 0
	v_add_f32_e32 v252, v76, v77
	v_add_f32_e32 v68, v78, v79
	v_add_f32_e32 v254, v182, v183
	v_add_f32_e32 v255, v184, v185
	v_add_f32_e32 v252, v252, v68
	v_add_f32_e32 v254, v254, v255
	v_add_f32_e32 v68, v186, v187
	v_add_f32_e32 v255, v188, v189
	v_add_f32_e32 v252, v252, v254
	v_add_f32_e32 v68, v68, v255
	v_add_f32_e32 v254, v244, v245
	v_add_f32_e32 v255, v246, v247
	v_add_f32_e32 v252, v252, v68
	v_add_f32_e32 v254, v254, v255
	v_add_f32_e32 v252, v252, v254
	v_add_f32_e32 v73, v73, v252
	v_cvt_pk_fp8_f32 v76, v76, v77
	s_nop 0
	v_cvt_pk_fp8_f32 v76, v78, v79 op_sel:[0,0,1]
	v_cvt_pk_fp8_f32 v77, v182, v183
	s_nop 0
	v_cvt_pk_fp8_f32 v77, v184, v185 op_sel:[0,0,1]
	v_cvt_pk_fp8_f32 v78, v186, v187
	s_nop 0
	v_cvt_pk_fp8_f32 v78, v188, v189 op_sel:[0,0,1]
	v_cvt_pk_fp8_f32 v79, v244, v245
	s_nop 0
	v_cvt_pk_fp8_f32 v79, v246, v247 op_sel:[0,0,1]
	s_waitcnt vmcnt(4)
	s_nop 1
	v_mfma_f32_16x16x32_fp8_fp8 v[84:87], v[118:119], v[76:77], v[84:87]
	v_mfma_f32_16x16x32_fp8_fp8 v[88:91], v[120:121], v[76:77], v[88:91]
	v_mfma_f32_16x16x32_fp8_fp8 v[92:95], v[122:123], v[76:77], v[92:95]
	v_mfma_f32_16x16x32_fp8_fp8 v[96:99], v[124:125], v[76:77], v[96:99]
	v_mfma_f32_16x16x32_fp8_fp8 v[84:87], v[126:127], v[78:79], v[84:87]
	v_mfma_f32_16x16x32_fp8_fp8 v[88:91], v[128:129], v[78:79], v[88:91]
	v_mfma_f32_16x16x32_fp8_fp8 v[92:95], v[130:131], v[78:79], v[92:95]
	v_mfma_f32_16x16x32_fp8_fp8 v[96:99], v[132:133], v[78:79], v[96:99]
	s_branch .Lbm2_Ag3_skip
.Lbm2_Ag3_resc:
	v_max_f32_e32 v254, 0, v104
	v_max_f32_e32 v255, v104, v253
	v_exp_f32_e64 v254, -v254
	v_sub_f32_e32 v203, v203, v255
	v_sub_f32_e32 v76, v76, v255
	v_sub_f32_e32 v77, v77, v255
	v_sub_f32_e32 v78, v78, v255
	v_sub_f32_e32 v79, v79, v255
	v_sub_f32_e32 v182, v182, v255
	v_sub_f32_e32 v183, v183, v255
	v_sub_f32_e32 v184, v184, v255
	v_sub_f32_e32 v185, v185, v255
	v_sub_f32_e32 v186, v186, v255
	v_sub_f32_e32 v187, v187, v255
	v_sub_f32_e32 v188, v188, v255
	v_sub_f32_e32 v189, v189, v255
	v_sub_f32_e32 v244, v244, v255
	v_sub_f32_e32 v245, v245, v255
	v_sub_f32_e32 v246, v246, v255
	v_sub_f32_e32 v247, v247, v255
	v_mul_f32_e32 v73, v73, v254
	v_pk_mul_f32 v[84:85], v[84:85], v[254:255] op_sel_hi:[1,0]
	v_pk_mul_f32 v[86:87], v[86:87], v[254:255] op_sel_hi:[1,0]
	v_pk_mul_f32 v[88:89], v[88:89], v[254:255] op_sel_hi:[1,0]
	v_pk_mul_f32 v[90:91], v[90:91], v[254:255] op_sel_hi:[1,0]
	v_pk_mul_f32 v[92:93], v[92:93], v[254:255] op_sel_hi:[1,0]
	v_pk_mul_f32 v[94:95], v[94:95], v[254:255] op_sel_hi:[1,0]
	v_pk_mul_f32 v[96:97], v[96:97], v[254:255] op_sel_hi:[1,0]
	v_pk_mul_f32 v[98:99], v[98:99], v[254:255] op_sel_hi:[1,0]
	s_branch .Lbm2_Ag3_exp
.Lbm2_Ag3_near:
	s_lshl_b32 s13, s54, 6
	s_sub_i32 s13, s97, s13
	s_add_i32 s13, s13, 12
	v_add_u32_e32 v104, s13, v83
	v_cndmask_b32_e64 v190, v69, v203, s[4:5]
	v_mov_b32_e32 v252, v104
	v_min_u32_e32 v254, 0x7f, v252
	v_lshl_add_u32 v254, v254, 2, v80
	ds_read_b32 v254, v254
	v_subrev_u32_e32 v68, 1, v104
	v_min_u32_e32 v255, 0x7f, v68
	v_lshl_add_u32 v255, v255, 2, v80
	ds_read_b32 v255, v255
	s_waitcnt lgkmcnt(0)
	v_fmamk_f32 v254, v254, 0x3fb8aa3b, v190
	v_cmp_le_i32_e32 vcc, 0, v252
	v_fmamk_f32 v76, v76, 0x3e38aa3b, v254
	s_nop 0
	v_cndmask_b32_e32 v76, v69, v76, vcc
	v_fmamk_f32 v255, v255, 0x3fb8aa3b, v190
	v_cmp_le_i32_e32 vcc, 0, v68
	v_fmamk_f32 v77, v77, 0x3e38aa3b, v255
	s_nop 0
	v_cndmask_b32_e32 v77, v69, v77, vcc
	v_subrev_u32_e32 v252, 2, v104
	v_min_u32_e32 v254, 0x7f, v252
	v_lshl_add_u32 v254, v254, 2, v80
	ds_read_b32 v254, v254
	v_subrev_u32_e32 v68, 3, v104
	v_min_u32_e32 v255, 0x7f, v68
	v_lshl_add_u32 v255, v255, 2, v80
	ds_read_b32 v255, v255
	s_waitcnt lgkmcnt(0)
	v_fmamk_f32 v254, v254, 0x3fb8aa3b, v190
	v_cmp_le_i32_e32 vcc, 0, v252
	v_fmamk_f32 v78, v78, 0x3e38aa3b, v254
	s_nop 0
	v_cndmask_b32_e32 v78, v69, v78, vcc
	v_fmamk_f32 v255, v255, 0x3fb8aa3b, v190
	v_cmp_le_i32_e32 vcc, 0, v68
	v_fmamk_f32 v79, v79, 0x3e38aa3b, v255
	s_nop 0
	v_cndmask_b32_e32 v79, v69, v79, vcc
	v_subrev_u32_e32 v252, 16, v104
	v_min_u32_e32 v254, 0x7f, v252
	v_lshl_add_u32 v254, v254, 2, v80
	ds_read_b32 v254, v254
	v_subrev_u32_e32 v68, 17, v104
	v_min_u32_e32 v255, 0x7f, v68
	v_lshl_add_u32 v255, v255, 2, v80
	ds_read_b32 v255, v255
	s_waitcnt lgkmcnt(0)
	v_fmamk_f32 v254, v254, 0x3fb8aa3b, v190
	v_cmp_le_i32_e32 vcc, 0, v252
	v_fmamk_f32 v182, v182, 0x3e38aa3b, v254
	s_nop 0
	v_cndmask_b32_e32 v182, v69, v182, vcc
	v_fmamk_f32 v255, v255, 0x3fb8aa3b, v190
	v_cmp_le_i32_e32 vcc, 0, v68
	v_fmamk_f32 v183, v183, 0x3e38aa3b, v255
	s_nop 0
	v_cndmask_b32_e32 v183, v69, v183, vcc
	v_subrev_u32_e32 v252, 18, v104
	v_min_u32_e32 v254, 0x7f, v252
	v_lshl_add_u32 v254, v254, 2, v80
	ds_read_b32 v254, v254
	v_subrev_u32_e32 v68, 19, v104
	v_min_u32_e32 v255, 0x7f, v68
	v_lshl_add_u32 v255, v255, 2, v80
	ds_read_b32 v255, v255
	s_waitcnt lgkmcnt(0)
	v_fmamk_f32 v254, v254, 0x3fb8aa3b, v190
	v_cmp_le_i32_e32 vcc, 0, v252
	v_fmamk_f32 v184, v184, 0x3e38aa3b, v254
	s_nop 0
	v_cndmask_b32_e32 v184, v69, v184, vcc
	v_fmamk_f32 v255, v255, 0x3fb8aa3b, v190
	v_cmp_le_i32_e32 vcc, 0, v68
	v_fmamk_f32 v185, v185, 0x3e38aa3b, v255
	s_nop 0
	v_cndmask_b32_e32 v185, v69, v185, vcc
	v_subrev_u32_e32 v252, 32, v104
	v_min_u32_e32 v254, 0x7f, v252
	v_lshl_add_u32 v254, v254, 2, v80
	ds_read_b32 v254, v254
	v_subrev_u32_e32 v68, 33, v104
	v_min_u32_e32 v255, 0x7f, v68
	v_lshl_add_u32 v255, v255, 2, v80
	ds_read_b32 v255, v255
	s_waitcnt lgkmcnt(0)
	v_fmamk_f32 v254, v254, 0x3fb8aa3b, v190
	v_cmp_le_i32_e32 vcc, 0, v252
	v_fmamk_f32 v186, v186, 0x3e38aa3b, v254
	s_nop 0
	v_cndmask_b32_e32 v186, v69, v186, vcc
	v_fmamk_f32 v255, v255, 0x3fb8aa3b, v190
	v_cmp_le_i32_e32 vcc, 0, v68
	v_fmamk_f32 v187, v187, 0x3e38aa3b, v255
	s_nop 0
	v_cndmask_b32_e32 v187, v69, v187, vcc
	v_subrev_u32_e32 v252, 34, v104
	v_min_u32_e32 v254, 0x7f, v252
	v_lshl_add_u32 v254, v254, 2, v80
	ds_read_b32 v254, v254
	v_subrev_u32_e32 v68, 35, v104
	v_min_u32_e32 v255, 0x7f, v68
	v_lshl_add_u32 v255, v255, 2, v80
	ds_read_b32 v255, v255
	s_waitcnt lgkmcnt(0)
	v_fmamk_f32 v254, v254, 0x3fb8aa3b, v190
	v_cmp_le_i32_e32 vcc, 0, v252
	v_fmamk_f32 v188, v188, 0x3e38aa3b, v254
	s_nop 0
	v_cndmask_b32_e32 v188, v69, v188, vcc
	v_fmamk_f32 v255, v255, 0x3fb8aa3b, v190
	v_cmp_le_i32_e32 vcc, 0, v68
	v_fmamk_f32 v189, v189, 0x3e38aa3b, v255
	s_nop 0
	v_cndmask_b32_e32 v189, v69, v189, vcc
	v_subrev_u32_e32 v252, 48, v104
	v_min_u32_e32 v254, 0x7f, v252
	v_lshl_add_u32 v254, v254, 2, v80
	ds_read_b32 v254, v254
	v_subrev_u32_e32 v68, 49, v104
	v_min_u32_e32 v255, 0x7f, v68
	v_lshl_add_u32 v255, v255, 2, v80
	ds_read_b32 v255, v255
	s_waitcnt lgkmcnt(0)
	v_fmamk_f32 v254, v254, 0x3fb8aa3b, v190
	v_cmp_le_i32_e32 vcc, 0, v252
	v_fmamk_f32 v244, v244, 0x3e38aa3b, v254
	s_nop 0
	v_cndmask_b32_e32 v244, v69, v244, vcc
	v_fmamk_f32 v255, v255, 0x3fb8aa3b, v190
	v_cmp_le_i32_e32 vcc, 0, v68
	v_fmamk_f32 v245, v245, 0x3e38aa3b, v255
	s_nop 0
	v_cndmask_b32_e32 v245, v69, v245, vcc
	v_subrev_u32_e32 v252, 50, v104
	v_min_u32_e32 v254, 0x7f, v252
	v_lshl_add_u32 v254, v254, 2, v80
	ds_read_b32 v254, v254
	v_subrev_u32_e32 v68, 51, v104
	v_min_u32_e32 v255, 0x7f, v68
	v_lshl_add_u32 v255, v255, 2, v80
	ds_read_b32 v255, v255
	s_waitcnt lgkmcnt(0)
	v_fmamk_f32 v254, v254, 0x3fb8aa3b, v190
	v_cmp_le_i32_e32 vcc, 0, v252
	v_fmamk_f32 v246, v246, 0x3e38aa3b, v254
	s_nop 0
	v_cndmask_b32_e32 v246, v69, v246, vcc
	v_fmamk_f32 v255, v255, 0x3fb8aa3b, v190
	v_cmp_le_i32_e32 vcc, 0, v68
	v_fmamk_f32 v247, v247, 0x3e38aa3b, v255
	s_nop 0
	v_cndmask_b32_e32 v247, v69, v247, vcc
	s_branch .Lbm2_Ag3_max
.Lbm2_Ag3_skip:
	v_mov_b32_e32 v253, 0
	s_mov_b32 s54, s15
	s_mov_b32 s48, s27
	s_waitcnt lgkmcnt(0)
	v_readfirstlane_b32 s13, v191
	s_add_i32 s35, s35, 1
	s_and_b32 s15, s13, 0xffff
	s_lshr_b32 s27, s13, 16
	s_cmp_lt_i32 s35, s25
	s_cbranch_scc1 .Lbm2_blkB
	s_branch .Lbm2_done
.Lbm2_blkB:
	s_lshl_b32 s12, s54, 12
	s_add_u32 s30, s62, s12
	s_addc_u32 s31, s63, 0
	global_load_dwordx4 v[118:121], v82, s[30:31]
	global_load_dwordx4 v[122:125], v82, s[30:31] offset:1024
	global_load_dwordx4 v[126:129], v82, s[30:31] offset:2048
	global_load_dwordx4 v[130:133], v82, s[30:31] offset:3072
	s_lshl_b32 s12, s15, 12
	s_add_u32 s30, s46, s12
	s_addc_u32 s31, s47, 0
	global_load_dwordx4 v[2:5], v82, s[30:31]
	global_load_dwordx4 v[6:9], v82, s[30:31] offset:1024
	global_load_dwordx4 v[12:15], v82, s[30:31] offset:2048
	global_load_dwordx4 v[16:19], v82, s[30:31] offset:3072
	s_add_i32 s14, s35, 2
	s_add_i32 s13, s25, -1
	s_min_i32 s14, s14, s13
	s_lshl_b32 s13, s14, 2
	s_add_i32 s13, s13, s96
	v_mov_b32_e32 v191, s13
	ds_read_b32 v191, v191 offset:16384
	s_cmp_ge_i32 s54, s21
	s_cselect_b32 s14, 1, 0
	s_bfe_u32 s29, s48, 0x40000
	s_cmp_eq_u32 s29, 0
	s_cbranch_scc1 .Lbm2_Bg0_skip
	s_waitcnt vmcnt(8)
	v_mfma_f32_16x16x32_fp8_fp8 v[76:79], v[176:177], v[100:101], 0
	v_mfma_f32_16x16x32_fp8_fp8 v[182:185], v[204:205], v[100:101], 0
	v_mfma_f32_16x16x32_fp8_fp8 v[186:189], v[208:209], v[100:101], 0
	v_mfma_f32_16x16x32_fp8_fp8 v[244:247], v[248:249], v[100:101], 0
	v_mfma_f32_16x16x32_fp8_fp8 v[76:79], v[178:179], v[102:103], v[76:79]
	v_mfma_f32_16x16x32_fp8_fp8 v[182:185], v[206:207], v[102:103], v[182:185]
	v_mfma_f32_16x16x32_fp8_fp8 v[186:189], v[210:211], v[102:103], v[186:189]
	v_mfma_f32_16x16x32_fp8_fp8 v[244:247], v[250:251], v[102:103], v[244:247]
	s_mov_b64 s[4:5], 0
	s_bitcmp1_b32 s29, 0
	s_cselect_b64 s[50:51], s[16:17], 0
	s_or_b64 s[4:5], s[4:5], s[50:51]
	s_bitcmp1_b32 s29, 1
	s_cselect_b64 s[50:51], s[18:19], 0
	s_or_b64 s[4:5], s[4:5], s[50:51]
	s_bitcmp1_b32 s29, 2
	s_cselect_b64 s[50:51], s[70:71], 0
	s_or_b64 s[4:5], s[4:5], s[50:51]
	s_bitcmp1_b32 s29, 3
	s_cselect_b64 s[50:51], s[76:77], 0
	s_or_b64 s[4:5], s[4:5], s[50:51]
	s_cmp_eq_u32 s14, 1
	s_cbranch_scc1 .Lbm2_Bg0_near
	v_add_f32_e32 v190, v81, v174
	v_cndmask_b32_e64 v190, v69, v190, s[4:5]
	v_fmamk_f32 v76, v76, 0x3e38aa3b, v190
	v_fmamk_f32 v77, v77, 0x3e38aa3b, v190
	v_fmamk_f32 v78, v78, 0x3e38aa3b, v190
	v_fmamk_f32 v79, v79, 0x3e38aa3b, v190
	v_fmamk_f32 v182, v182, 0x3e38aa3b, v190
	v_fmamk_f32 v183, v183, 0x3e38aa3b, v190
	v_fmamk_f32 v184, v184, 0x3e38aa3b, v190
	v_fmamk_f32 v185, v185, 0x3e38aa3b, v190
	v_fmamk_f32 v186, v186, 0x3e38aa3b, v190
	v_fmamk_f32 v187, v187, 0x3e38aa3b, v190
	v_fmamk_f32 v188, v188, 0x3e38aa3b, v190
	v_fmamk_f32 v189, v189, 0x3e38aa3b, v190
	v_fmamk_f32 v244, v244, 0x3e38aa3b, v190
	v_fmamk_f32 v245, v245, 0x3e38aa3b, v190
	v_fmamk_f32 v246, v246, 0x3e38aa3b, v190
	v_fmamk_f32 v247, v247, 0x3e38aa3b, v190

.Lbm2_Bg0_skip:
	s_bfe_u32 s29, s48, 0x40004
	s_cmp_eq_u32 s29, 0
	s_cbranch_scc1 .Lbm2_Bg1_skip
	s_waitcnt vmcnt(8)
	v_mfma_f32_16x16x32_fp8_fp8 v[76:79], v[176:177], v[106:107], 0
	v_mfma_f32_16x16x32_fp8_fp8 v[182:185], v[204:205], v[106:107], 0
	v_mfma_f32_16x16x32_fp8_fp8 v[186:189], v[208:209], v[106:107], 0
	v_mfma_f32_16x16x32_fp8_fp8 v[244:247], v[248:249], v[106:107], 0
	v_mfma_f32_16x16x32_fp8_fp8 v[76:79], v[178:179], v[108:109], v[76:79]
	v_mfma_f32_16x16x32_fp8_fp8 v[182:185], v[206:207], v[108:109], v[182:185]
	v_mfma_f32_16x16x32_fp8_fp8 v[186:189], v[210:211], v[108:109], v[186:189]
	v_mfma_f32_16x16x32_fp8_fp8 v[244:247], v[250:251], v[108:109], v[244:247]
	s_mov_b64 s[4:5], 0
	s_bitcmp1_b32 s29, 0
	s_cselect_b64 s[50:51], s[16:17], 0
	s_or_b64 s[4:5], s[4:5], s[50:51]
	s_bitcmp1_b32 s29, 1
	s_cselect_b64 s[50:51], s[18:19], 0
	s_or_b64 s[4:5], s[4:5], s[50:51]
	s_bitcmp1_b32 s29, 2
	s_cselect_b64 s[50:51], s[70:71], 0
	s_or_b64 s[4:5], s[4:5], s[50:51]
	s_bitcmp1_b32 s29, 3
	s_cselect_b64 s[50:51], s[76:77], 0
	s_or_b64 s[4:5], s[4:5], s[50:51]
	s_cmp_eq_u32 s14, 1
	s_cbranch_scc1 .Lbm2_Bg1_near
	v_add_f32_e32 v190, v81, v175
	v_cndmask_b32_e64 v190, v69, v190, s[4:5]
	v_fmamk_f32 v76, v76, 0x3e38aa3b, v190
	v_fmamk_f32 v77, v77, 0x3e38aa3b, v190
	v_fmamk_f32 v78, v78, 0x3e38aa3b, v190
	v_fmamk_f32 v79, v79, 0x3e38aa3b, v190
	v_fmamk_f32 v182, v182, 0x3e38aa3b, v190
	v_fmamk_f32 v183, v183, 0x3e38aa3b, v190
	v_fmamk_f32 v184, v184, 0x3e38aa3b, v190
	v_fmamk_f32 v185, v185, 0x3e38aa3b, v190
	v_fmamk_f32 v186, v186, 0x3e38aa3b, v190
	v_fmamk_f32 v187, v187, 0x3e38aa3b, v190
	v_fmamk_f32 v188, v188, 0x3e38aa3b, v190
	v_fmamk_f32 v189, v189, 0x3e38aa3b, v190
	v_fmamk_f32 v244, v244, 0x3e38aa3b, v190
	v_fmamk_f32 v245, v245, 0x3e38aa3b, v190
	v_fmamk_f32 v246, v246, 0x3e38aa3b, v190
	v_fmamk_f32 v247, v247, 0x3e38aa3b, v190

.Lbm2_Bg1_skip:
	s_bfe_u32 s29, s48, 0x40008
	s_cmp_eq_u32 s29, 0
	s_cbranch_scc1 .Lbm2_Bg2_skip
	s_waitcnt vmcnt(8)
	v_mfma_f32_16x16x32_fp8_fp8 v[76:79], v[176:177], v[110:111], 0
	v_mfma_f32_16x16x32_fp8_fp8 v[182:185], v[204:205], v[110:111], 0
	v_mfma_f32_16x16x32_fp8_fp8 v[186:189], v[208:209], v[110:111], 0
	v_mfma_f32_16x16x32_fp8_fp8 v[244:247], v[248:249], v[110:111], 0
	v_mfma_f32_16x16x32_fp8_fp8 v[76:79], v[178:179], v[112:113], v[76:79]
	v_mfma_f32_16x16x32_fp8_fp8 v[182:185], v[206:207], v[112:113], v[182:185]
	v_mfma_f32_16x16x32_fp8_fp8 v[186:189], v[210:211], v[112:113], v[186:189]
	v_mfma_f32_16x16x32_fp8_fp8 v[244:247], v[250:251], v[112:113], v[244:247]
	s_mov_b64 s[4:5], 0
	s_bitcmp1_b32 s29, 0
	s_cselect_b64 s[50:51], s[16:17], 0
	s_or_b64 s[4:5], s[4:5], s[50:51]
	s_bitcmp1_b32 s29, 1
	s_cselect_b64 s[50:51], s[18:19], 0
	s_or_b64 s[4:5], s[4:5], s[50:51]
	s_bitcmp1_b32 s29, 2
	s_cselect_b64 s[50:51], s[70:71], 0
	s_or_b64 s[4:5], s[4:5], s[50:51]
	s_bitcmp1_b32 s29, 3
	s_cselect_b64 s[50:51], s[76:77], 0
	s_or_b64 s[4:5], s[4:5], s[50:51]
	s_cmp_eq_u32 s14, 1
	s_cbranch_scc1 .Lbm2_Bg2_near
	v_add_f32_e32 v190, v81, v202
	v_cndmask_b32_e64 v190, v69, v190, s[4:5]
	v_fmamk_f32 v76, v76, 0x3e38aa3b, v190
	v_fmamk_f32 v77, v77, 0x3e38aa3b, v190
	v_fmamk_f32 v78, v78, 0x3e38aa3b, v190
	v_fmamk_f32 v79, v79, 0x3e38aa3b, v190
	v_fmamk_f32 v182, v182, 0x3e38aa3b, v190
	v_fmamk_f32 v183, v183, 0x3e38aa3b, v190
	v_fmamk_f32 v184, v184, 0x3e38aa3b, v190
	v_fmamk_f32 v185, v185, 0x3e38aa3b, v190
	v_fmamk_f32 v186, v186, 0x3e38aa3b, v190
	v_fmamk_f32 v187, v187, 0x3e38aa3b, v190
	v_fmamk_f32 v188, v188, 0x3e38aa3b, v190
	v_fmamk_f32 v189, v189, 0x3e38aa3b, v190
	v_fmamk_f32 v244, v244, 0x3e38aa3b, v190
	v_fmamk_f32 v245, v245, 0x3e38aa3b, v190
	v_fmamk_f32 v246, v246, 0x3e38aa3b, v190
	v_fmamk_f32 v247, v247, 0x3e38aa3b, v190

.Lbm2_Bg2_skip:
	s_bfe_u32 s29, s48, 0x4000c
	s_cmp_eq_u32 s29, 0
	s_cbranch_scc1 .Lbm2_Bg3_skip
	s_waitcnt vmcnt(8)
	v_mfma_f32_16x16x32_fp8_fp8 v[76:79], v[176:177], v[114:115], 0
	v_mfma_f32_16x16x32_fp8_fp8 v[182:185], v[204:205], v[114:115], 0
	v_mfma_f32_16x16x32_fp8_fp8 v[186:189], v[208:209], v[114:115], 0
	v_mfma_f32_16x16x32_fp8_fp8 v[244:247], v[248:249], v[114:115], 0
	v_mfma_f32_16x16x32_fp8_fp8 v[76:79], v[178:179], v[116:117], v[76:79]
	v_mfma_f32_16x16x32_fp8_fp8 v[182:185], v[206:207], v[116:117], v[182:185]
	v_mfma_f32_16x16x32_fp8_fp8 v[186:189], v[210:211], v[116:117], v[186:189]
	v_mfma_f32_16x16x32_fp8_fp8 v[244:247], v[250:251], v[116:117], v[244:247]
	s_mov_b64 s[4:5], 0
	s_bitcmp1_b32 s29, 0
	s_cselect_b64 s[50:51], s[16:17], 0
	s_or_b64 s[4:5], s[4:5], s[50:51]
	s_bitcmp1_b32 s29, 1
	s_cselect_b64 s[50:51], s[18:19], 0
	s_or_b64 s[4:5], s[4:5], s[50:51]
	s_bitcmp1_b32 s29, 2
	s_cselect_b64 s[50:51], s[70:71], 0
	s_or_b64 s[4:5], s[4:5], s[50:51]
	s_bitcmp1_b32 s29, 3
	s_cselect_b64 s[50:51], s[76:77], 0
	s_or_b64 s[4:5], s[4:5], s[50:51]
	s_cmp_eq_u32 s14, 1
	s_cbranch_scc1 .Lbm2_Bg3_near
	v_add_f32_e32 v190, v81, v203
	v_cndmask_b32_e64 v190, v69, v190, s[4:5]
	v_fmamk_f32 v76, v76, 0x3e38aa3b, v190
	v_fmamk_f32 v77, v77, 0x3e38aa3b, v190
	v_fmamk_f32 v78, v78, 0x3e38aa3b, v190
	v_fmamk_f32 v79, v79, 0x3e38aa3b, v190
	v_fmamk_f32 v182, v182, 0x3e38aa3b, v190
	v_fmamk_f32 v183, v183, 0x3e38aa3b, v190
	v_fmamk_f32 v184, v184, 0x3e38aa3b, v190
	v_fmamk_f32 v185, v185, 0x3e38aa3b, v190
	v_fmamk_f32 v186, v186, 0x3e38aa3b, v190
	v_fmamk_f32 v187, v187, 0x3e38aa3b, v190
	v_fmamk_f32 v188, v188, 0x3e38aa3b, v190
	v_fmamk_f32 v189, v189, 0x3e38aa3b, v190
	v_fmamk_f32 v244, v244, 0x3e38aa3b, v190
	v_fmamk_f32 v245, v245, 0x3e38aa3b, v190
	v_fmamk_f32 v246, v246, 0x3e38aa3b, v190
	v_fmamk_f32 v247, v247, 0x3e38aa3b, v190

.Lbm2_done:
	s_waitcnt vmcnt(0)
	v_and_b32_e32 v252, 15, v181
	v_lshrrev_b32_e32 v68, 4, v181
	v_lshrrev_b32_e32 v191, 2, v252
	v_add_u32_e32 v191, s23, v191
	v_lshlrev_b32_e32 v252, 8, v252
	v_lshl_add_u32 v252, v68, 4, v252
	v_add_u32_e32 v190, s96, v252
	v_mad_u64_u32 v[252:253], s[50:51], v191, v213, v[74:75]
	global_load_dword v12, v[252:253], off offset:4
	v_add_u32_e32 v68, 4, v191
	v_mad_u64_u32 v[252:253], s[50:51], v68, v213, v[74:75]
	global_load_dword v13, v[252:253], off offset:4
	v_add_u32_e32 v68, 8, v191
	v_mad_u64_u32 v[252:253], s[50:51], v68, v213, v[74:75]
	global_load_dword v14, v[252:253], off offset:4
	v_add_u32_e32 v68, 12, v191
	v_mad_u64_u32 v[252:253], s[50:51], v68, v213, v[74:75]
	global_load_dword v15, v[252:253], off offset:4
	v_mov_b32_e32 v105, v70
	s_nop 1
	v_permlane16_swap_b32_e32 v70, v105
	s_nop 0
	v_add_f32_e32 v70, v70, v105
	v_mov_b32_e32 v105, v70
	s_nop 1
	v_permlane32_swap_b32_e32 v70, v105
	s_nop 0
	v_add_f32_e32 v70, v70, v105
	v_max_f32_e32 v70, 0xda24260, v70
	v_mov_b32_e32 v105, v71
	s_nop 1
	v_permlane16_swap_b32_e32 v71, v105
	s_nop 0
	v_add_f32_e32 v71, v71, v105
	v_mov_b32_e32 v105, v71
	s_nop 1
	v_permlane32_swap_b32_e32 v71, v105
	s_nop 0
	v_add_f32_e32 v71, v71, v105
	v_max_f32_e32 v71, 0xda24260, v71
	v_mov_b32_e32 v105, v72
	s_nop 1
	v_permlane16_swap_b32_e32 v72, v105
	s_nop 0
	v_add_f32_e32 v72, v72, v105
	v_mov_b32_e32 v105, v72
	s_nop 1
	v_permlane32_swap_b32_e32 v72, v105
	s_nop 0
	v_add_f32_e32 v72, v72, v105
	v_max_f32_e32 v72, 0xda24260, v72
	v_mov_b32_e32 v105, v73
	s_nop 1
	v_permlane16_swap_b32_e32 v73, v105
	s_nop 0
	v_add_f32_e32 v73, v73, v105
	v_mov_b32_e32 v105, v73
	s_nop 1
	v_permlane32_swap_b32_e32 v73, v105
	s_nop 0
	v_add_f32_e32 v73, v73, v105
	v_max_f32_e32 v73, 0xda24260, v73
	s_waitcnt vmcnt(0)
	v_div_scale_f32 v2, s[50:51], v70, v70, v12
	v_rcp_f32_e32 v3, v2
	s_nop 0
	v_fma_f32 v4, -v2, v3, 1.0
	v_fmac_f32_e32 v3, v4, v3
	v_div_scale_f32 v4, vcc, v12, v70, v12
	v_mul_f32_e32 v5, v4, v3
	v_fma_f32 v6, -v2, v5, v4
	v_fmac_f32_e32 v5, v6, v3
	v_fma_f32 v2, -v2, v5, v4
	v_div_fmas_f32 v2, v2, v3, v5
	v_div_fixup_f32 v254, v2, v70, v12
	ds_read_b128 v[16:19], v190 offset:0
	s_waitcnt lgkmcnt(0)
	v_pk_fma_f32 v[20:21], v[20:21], v[254:255], v[16:17] op_sel_hi:[1,0,1]
	v_pk_fma_f32 v[22:23], v[22:23], v[254:255], v[18:19] op_sel_hi:[1,0,1]
	ds_write_b128 v190, v[20:23] offset:0
	ds_read_b128 v[16:19], v190 offset:64
	s_waitcnt lgkmcnt(0)
	v_pk_fma_f32 v[24:25], v[24:25], v[254:255], v[16:17] op_sel_hi:[1,0,1]
	v_pk_fma_f32 v[26:27], v[26:27], v[254:255], v[18:19] op_sel_hi:[1,0,1]
	ds_write_b128 v190, v[24:27] offset:64
	ds_read_b128 v[16:19], v190 offset:128
	s_waitcnt lgkmcnt(0)
	v_pk_fma_f32 v[28:29], v[28:29], v[254:255], v[16:17] op_sel_hi:[1,0,1]
	v_pk_fma_f32 v[30:31], v[30:31], v[254:255], v[18:19] op_sel_hi:[1,0,1]
	ds_write_b128 v190, v[28:31] offset:128
	ds_read_b128 v[16:19], v190 offset:192
	s_waitcnt lgkmcnt(0)
	v_pk_fma_f32 v[32:33], v[32:33], v[254:255], v[16:17] op_sel_hi:[1,0,1]
	v_pk_fma_f32 v[34:35], v[34:35], v[254:255], v[18:19] op_sel_hi:[1,0,1]
	ds_write_b128 v190, v[32:35] offset:192
	v_div_scale_f32 v2, s[50:51], v71, v71, v13
	v_rcp_f32_e32 v3, v2
	s_nop 0
	v_fma_f32 v4, -v2, v3, 1.0
	v_fmac_f32_e32 v3, v4, v3
	v_div_scale_f32 v4, vcc, v13, v71, v13
	v_mul_f32_e32 v5, v4, v3
	v_fma_f32 v6, -v2, v5, v4
	v_fmac_f32_e32 v5, v6, v3
	v_fma_f32 v2, -v2, v5, v4
	v_div_fmas_f32 v2, v2, v3, v5
	v_div_fixup_f32 v254, v2, v71, v13
	ds_read_b128 v[16:19], v190 offset:4096
	s_waitcnt lgkmcnt(0)
	v_pk_fma_f32 v[36:37], v[36:37], v[254:255], v[16:17] op_sel_hi:[1,0,1]
	v_pk_fma_f32 v[38:39], v[38:39], v[254:255], v[18:19] op_sel_hi:[1,0,1]
	ds_write_b128 v190, v[36:39] offset:4096
	ds_read_b128 v[16:19], v190 offset:4160
	s_waitcnt lgkmcnt(0)
	v_pk_fma_f32 v[40:41], v[40:41], v[254:255], v[16:17] op_sel_hi:[1,0,1]
	v_pk_fma_f32 v[42:43], v[42:43], v[254:255], v[18:19] op_sel_hi:[1,0,1]
	ds_write_b128 v190, v[40:43] offset:4160
	ds_read_b128 v[16:19], v190 offset:4224
	s_waitcnt lgkmcnt(0)
	v_pk_fma_f32 v[44:45], v[44:45], v[254:255], v[16:17] op_sel_hi:[1,0,1]
	v_pk_fma_f32 v[46:47], v[46:47], v[254:255], v[18:19] op_sel_hi:[1,0,1]
	ds_write_b128 v190, v[44:47] offset:4224
	ds_read_b128 v[16:19], v190 offset:4288
	s_waitcnt lgkmcnt(0)
	v_pk_fma_f32 v[48:49], v[48:49], v[254:255], v[16:17] op_sel_hi:[1,0,1]
	v_pk_fma_f32 v[50:51], v[50:51], v[254:255], v[18:19] op_sel_hi:[1,0,1]
	ds_write_b128 v190, v[48:51] offset:4288
	v_div_scale_f32 v2, s[50:51], v72, v72, v14
	v_rcp_f32_e32 v3, v2
	s_nop 0
	v_fma_f32 v4, -v2, v3, 1.0
	v_fmac_f32_e32 v3, v4, v3
	v_div_scale_f32 v4, vcc, v14, v72, v14
	v_mul_f32_e32 v5, v4, v3
	v_fma_f32 v6, -v2, v5, v4
	v_fmac_f32_e32 v5, v6, v3
	v_fma_f32 v2, -v2, v5, v4
	v_div_fmas_f32 v2, v2, v3, v5
	v_div_fixup_f32 v254, v2, v72, v14
	ds_read_b128 v[16:19], v190 offset:8192
	s_waitcnt lgkmcnt(0)
	v_pk_fma_f32 v[52:53], v[52:53], v[254:255], v[16:17] op_sel_hi:[1,0,1]
	v_pk_fma_f32 v[54:55], v[54:55], v[254:255], v[18:19] op_sel_hi:[1,0,1]
	ds_write_b128 v190, v[52:55] offset:8192
	ds_read_b128 v[16:19], v190 offset:8256
	s_waitcnt lgkmcnt(0)
	v_pk_fma_f32 v[56:57], v[56:57], v[254:255], v[16:17] op_sel_hi:[1,0,1]
	v_pk_fma_f32 v[58:59], v[58:59], v[254:255], v[18:19] op_sel_hi:[1,0,1]
	ds_write_b128 v190, v[56:59] offset:8256
	ds_read_b128 v[16:19], v190 offset:8320
	s_waitcnt lgkmcnt(0)
	v_pk_fma_f32 v[60:61], v[60:61], v[254:255], v[16:17] op_sel_hi:[1,0,1]
	v_pk_fma_f32 v[62:63], v[62:63], v[254:255], v[18:19] op_sel_hi:[1,0,1]
	ds_write_b128 v190, v[60:63] offset:8320
	ds_read_b128 v[16:19], v190 offset:8384
	s_waitcnt lgkmcnt(0)
	v_pk_fma_f32 v[64:65], v[64:65], v[254:255], v[16:17] op_sel_hi:[1,0,1]
	v_pk_fma_f32 v[66:67], v[66:67], v[254:255], v[18:19] op_sel_hi:[1,0,1]
	ds_write_b128 v190, v[64:67] offset:8384
	v_div_scale_f32 v2, s[50:51], v73, v73, v15
	v_rcp_f32_e32 v3, v2
	s_nop 0
	v_fma_f32 v4, -v2, v3, 1.0
	v_fmac_f32_e32 v3, v4, v3
	v_div_scale_f32 v4, vcc, v15, v73, v15
	v_mul_f32_e32 v5, v4, v3
	v_fma_f32 v6, -v2, v5, v4
	v_fmac_f32_e32 v5, v6, v3
	v_fma_f32 v2, -v2, v5, v4
	v_div_fmas_f32 v2, v2, v3, v5
	v_div_fixup_f32 v254, v2, v73, v15
	ds_read_b128 v[16:19], v190 offset:12288
	s_waitcnt lgkmcnt(0)
	v_pk_fma_f32 v[84:85], v[84:85], v[254:255], v[16:17] op_sel_hi:[1,0,1]
	v_pk_fma_f32 v[86:87], v[86:87], v[254:255], v[18:19] op_sel_hi:[1,0,1]
	ds_write_b128 v190, v[84:87] offset:12288
	ds_read_b128 v[16:19], v190 offset:12352
	s_waitcnt lgkmcnt(0)
	v_pk_fma_f32 v[88:89], v[88:89], v[254:255], v[16:17] op_sel_hi:[1,0,1]
	v_pk_fma_f32 v[90:91], v[90:91], v[254:255], v[18:19] op_sel_hi:[1,0,1]
	ds_write_b128 v190, v[88:91] offset:12352
	ds_read_b128 v[16:19], v190 offset:12416
	s_waitcnt lgkmcnt(0)
	v_pk_fma_f32 v[92:93], v[92:93], v[254:255], v[16:17] op_sel_hi:[1,0,1]
	v_pk_fma_f32 v[94:95], v[94:95], v[254:255], v[18:19] op_sel_hi:[1,0,1]
	ds_write_b128 v190, v[92:95] offset:12416
	ds_read_b128 v[16:19], v190 offset:12480
	s_waitcnt lgkmcnt(0)
	v_pk_fma_f32 v[96:97], v[96:97], v[254:255], v[16:17] op_sel_hi:[1,0,1]
	v_pk_fma_f32 v[98:99], v[98:99], v[254:255], v[18:19] op_sel_hi:[1,0,1]
	ds_write_b128 v190, v[96:99] offset:12480
	v_mov_b32_e32 v174, 0x3727c5ac
	v_mov_b32_e32 v175, 0xe0000
	v_mov_b32_e32 v176, 0x200
	v_mov_b32_e32 v177, 0
	v_mov_b32_e32 v178, 0x1ff
	v_mov_b32_e32 v179, 0
	v_mov_b32_e32 v202, 0xe1000
	v_mov_b32_e32 v203, 0xffff
	v_mov_b32_e32 v204, 1
	v_mov_b32_e32 v205, 0x7f800000
	v_mov_b32_e32 v206, 0x7fc00000
	v_mov_b32_e32 v207, 0xff800000
	v_mov_b32_e32 v209, 0x1e000
	v_mov_b32_e32 v210, 0x24000
	v_mov_b32_e32 v211, 0x2a000
	v_mov_b32_e32 v208, v181
	s_waitcnt lgkmcnt(0)
	s_branch .LBB0_1588

.LBB0_2049:
.LBB0_2050:
	s_and_b64 s[10:11], s[6:7], s[8:9]
	s_andn2_b64 s[12:13], s[8:9], s[6:7]
	s_andn2_b64 s[54:55], s[6:7], s[8:9]
	s_nor_b64 s[70:71], s[6:7], s[8:9]
	v_readfirstlane_b32 s40, v70
	v_readfirstlane_b32 s41, v71
	v_readfirstlane_b32 s62, v72
	v_readfirstlane_b32 s63, v73
	v_and_b32_e32 v254, 15, v181
	v_lshrrev_b32_e32 v255, 4, v181
	v_lshrrev_b32_e32 v254, 2, v254
	v_lshlrev_b32_e32 v255, 2, v255
	v_readlane_b32 s23, v243, 32
	v_sub_u32_e32 v83, v254, v255
	v_lshlrev_b32_e32 v82, 4, v181
	s_add_i32 s23, s23, s47
	v_add_u32_e32 v191, s23, v254
	v_mad_u64_u32 v[252:253], s[6:7], v191, v212, v[68:69]
	global_load_dwordx4 v[20:23], v[252:253], off
	global_load_dwordx4 v[24:27], v[252:253], off offset:64
	v_add_u32_e32 v255, 4, v191
	v_mad_u64_u32 v[252:253], s[6:7], v255, v212, v[68:69]
	global_load_dwordx4 v[28:31], v[252:253], off
	global_load_dwordx4 v[32:35], v[252:253], off offset:64
	v_add_u32_e32 v255, 8, v191
	v_mad_u64_u32 v[252:253], s[6:7], v255, v212, v[68:69]
	global_load_dwordx4 v[36:39], v[252:253], off
	global_load_dwordx4 v[40:43], v[252:253], off offset:64
	v_add_u32_e32 v255, 12, v191
	v_mad_u64_u32 v[252:253], s[6:7], v255, v212, v[68:69]
	global_load_dwordx4 v[44:47], v[252:253], off
	global_load_dwordx4 v[48:51], v[252:253], off offset:64
	v_and_b32_e32 v254, 15, v181
	v_lshrrev_b32_e32 v255, 4, v181
	v_lshlrev_b32_e32 v104, 6, v254
	v_lshl_add_u32 v104, v255, 2, v104
	v_add_u32_e32 v104, s46, v104
	v_lshl_add_u32 v105, v254, 2, s46
	ds_read_b32 v12, v104 offset:16384
	ds_read_b32 v13, v104 offset:16400
	ds_read_b32 v14, v104 offset:16416
	ds_read_b32 v15, v104 offset:16432
	ds_read_b32 v16, v105 offset:17408
	v_lshl_add_u32 v105, v181, 2, s46
	v_mov_b32_e32 v17, 1
	v_lshlrev_b32_e32 v17, v254, v17
	s_waitcnt lgkmcnt(0)
	v_mul_f32_e32 v81, 0x3fb8aa3b, v81
	ds_write_b32 v105, v11 offset:16384
	ds_write_b32 v105, v11 offset:16640
	ds_write_b32 v105, v11 offset:16896
	ds_write_b32 v105, v11 offset:17152
	v_cmp_lt_i32_e32 vcc, v255, v16
	v_and_b32_e32 v12, 0xff, v12
	v_lshl_add_u32 v12, v12, 2, s46
	v_cndmask_b32_e32 v18, 0, v17, vcc
	ds_or_b32 v12, v18 offset:16384
	v_add_u32_e32 v18, 4, v255
	v_cmp_lt_i32_e32 vcc, v18, v16
	v_and_b32_e32 v13, 0xff, v13
	v_lshl_add_u32 v13, v13, 2, s46
	v_cndmask_b32_e32 v18, 0, v17, vcc
	ds_or_b32 v13, v18 offset:16384
	v_add_u32_e32 v18, 8, v255
	v_cmp_lt_i32_e32 vcc, v18, v16
	v_and_b32_e32 v14, 0xff, v14
	v_lshl_add_u32 v14, v14, 2, s46
	v_cndmask_b32_e32 v18, 0, v17, vcc
	ds_or_b32 v14, v18 offset:16384
	v_add_u32_e32 v18, 12, v255
	v_cmp_lt_i32_e32 vcc, v18, v16
	v_and_b32_e32 v15, 0xff, v15
	v_lshl_add_u32 v15, v15, 2, s46
	v_cndmask_b32_e32 v18, 0, v17, vcc
	ds_or_b32 v15, v18 offset:16384
	s_waitcnt lgkmcnt(0)
	ds_read_b32 v12, v105 offset:16384
	ds_read_b32 v13, v105 offset:16640
	ds_read_b32 v14, v105 offset:16896
	ds_read_b32 v15, v105 offset:17152
	s_mov_b32 s25, 0
	s_waitcnt lgkmcnt(0)
	v_cmp_ne_u32_e64 s[4:5], 0, v12
	v_lshlrev_b32_e32 v16, 16, v12
	v_add_u32_e32 v17, 0, v181
	v_or_b32_e32 v16, v16, v17
	v_mbcnt_lo_u32_b32 v17, s4, 0
	v_mbcnt_hi_u32_b32 v17, s5, v17
	v_add_u32_e32 v17, s25, v17
	v_lshl_add_u32 v17, v17, 2, s46
	v_add_u32_e32 v17, 0x4000, v17
	v_add_u32_e32 v18, 0x4400, v105
	s_bcnt1_i32_b64 s9, s[4:5]
	v_cndmask_b32_e64 v17, v18, v17, s[4:5]
	s_add_i32 s25, s25, s9
	ds_write_b32 v17, v16
	v_cmp_ne_u32_e64 s[4:5], 0, v13
	v_lshlrev_b32_e32 v16, 16, v13
	v_add_u32_e32 v17, 64, v181
	v_or_b32_e32 v16, v16, v17
	v_mbcnt_lo_u32_b32 v17, s4, 0
	v_mbcnt_hi_u32_b32 v17, s5, v17
	v_add_u32_e32 v17, s25, v17
	v_lshl_add_u32 v17, v17, 2, s46
	v_add_u32_e32 v17, 0x4000, v17
	v_add_u32_e32 v18, 0x4400, v105
	s_bcnt1_i32_b64 s9, s[4:5]
	v_cndmask_b32_e64 v17, v18, v17, s[4:5]
	s_add_i32 s25, s25, s9
	ds_write_b32 v17, v16
	v_cmp_ne_u32_e64 s[4:5], 0, v14
	v_lshlrev_b32_e32 v16, 16, v14
	v_add_u32_e32 v17, 128, v181
	v_or_b32_e32 v16, v16, v17
	v_mbcnt_lo_u32_b32 v17, s4, 0
	v_mbcnt_hi_u32_b32 v17, s5, v17
	v_add_u32_e32 v17, s25, v17
	v_lshl_add_u32 v17, v17, 2, s46
	v_add_u32_e32 v17, 0x4000, v17
	v_add_u32_e32 v18, 0x4400, v105
	s_bcnt1_i32_b64 s9, s[4:5]
	v_cndmask_b32_e64 v17, v18, v17, s[4:5]
	s_add_i32 s25, s25, s9
	ds_write_b32 v17, v16
	v_cmp_ne_u32_e64 s[4:5], 0, v15
	v_lshlrev_b32_e32 v16, 16, v15
	v_add_u32_e32 v17, 192, v181
	v_or_b32_e32 v16, v16, v17
	v_mbcnt_lo_u32_b32 v17, s4, 0
	v_mbcnt_hi_u32_b32 v17, s5, v17
	v_add_u32_e32 v17, s25, v17
	v_lshl_add_u32 v17, v17, 2, s46
	v_add_u32_e32 v17, 0x4000, v17
	v_add_u32_e32 v18, 0x4400, v105
	s_bcnt1_i32_b64 s9, s[4:5]
	v_cndmask_b32_e64 v17, v18, v17, s[4:5]
	s_add_i32 s25, s25, s9
	ds_write_b32 v17, v16
	s_waitcnt vmcnt(0)
	v_lshlrev_b32_e32 v252, 16, v20
	v_and_b32_e32 v68, 0xffff0000, v20
	v_mul_f32_e32 v252, 0x41000000, v252
	v_mul_f32_e32 v68, 0x41000000, v68
	v_lshlrev_b32_e32 v254, 16, v21
	v_and_b32_e32 v255, 0xffff0000, v21
	v_cvt_pk_fp8_f32 v100, v252, v68
	v_mul_f32_e32 v254, 0x41000000, v254
	v_mul_f32_e32 v255, 0x41000000, v255
	s_nop 0
	v_cvt_pk_fp8_f32 v100, v254, v255 op_sel:[0,0,1]
	v_lshlrev_b32_e32 v252, 16, v22
	v_and_b32_e32 v68, 0xffff0000, v22
	v_mul_f32_e32 v252, 0x41000000, v252
	v_mul_f32_e32 v68, 0x41000000, v68
	v_lshlrev_b32_e32 v254, 16, v23
	v_and_b32_e32 v255, 0xffff0000, v23
	v_cvt_pk_fp8_f32 v101, v252, v68
	v_mul_f32_e32 v254, 0x41000000, v254
	v_mul_f32_e32 v255, 0x41000000, v255
	s_nop 0
	v_cvt_pk_fp8_f32 v101, v254, v255 op_sel:[0,0,1]
	v_lshlrev_b32_e32 v252, 16, v24
	v_and_b32_e32 v68, 0xffff0000, v24
	v_mul_f32_e32 v252, 0x41000000, v252
	v_mul_f32_e32 v68, 0x41000000, v68
	v_lshlrev_b32_e32 v254, 16, v25
	v_and_b32_e32 v255, 0xffff0000, v25
	v_cvt_pk_fp8_f32 v102, v252, v68
	v_mul_f32_e32 v254, 0x41000000, v254
	v_mul_f32_e32 v255, 0x41000000, v255
	s_nop 0
	v_cvt_pk_fp8_f32 v102, v254, v255 op_sel:[0,0,1]
	v_lshlrev_b32_e32 v252, 16, v26
	v_and_b32_e32 v68, 0xffff0000, v26
	v_mul_f32_e32 v252, 0x41000000, v252
	v_mul_f32_e32 v68, 0x41000000, v68
	v_lshlrev_b32_e32 v254, 16, v27
	v_and_b32_e32 v255, 0xffff0000, v27
	v_cvt_pk_fp8_f32 v103, v252, v68
	v_mul_f32_e32 v254, 0x41000000, v254
	v_mul_f32_e32 v255, 0x41000000, v255
	s_nop 0
	v_cvt_pk_fp8_f32 v103, v254, v255 op_sel:[0,0,1]
	v_lshlrev_b32_e32 v252, 16, v28
	v_and_b32_e32 v68, 0xffff0000, v28
	v_mul_f32_e32 v252, 0x41000000, v252
	v_mul_f32_e32 v68, 0x41000000, v68
	v_lshlrev_b32_e32 v254, 16, v29
	v_and_b32_e32 v255, 0xffff0000, v29
	v_cvt_pk_fp8_f32 v106, v252, v68
	v_mul_f32_e32 v254, 0x41000000, v254
	v_mul_f32_e32 v255, 0x41000000, v255
	s_nop 0
	v_cvt_pk_fp8_f32 v106, v254, v255 op_sel:[0,0,1]
	v_lshlrev_b32_e32 v252, 16, v30
	v_and_b32_e32 v68, 0xffff0000, v30
	v_mul_f32_e32 v252, 0x41000000, v252
	v_mul_f32_e32 v68, 0x41000000, v68
	v_lshlrev_b32_e32 v254, 16, v31
	v_and_b32_e32 v255, 0xffff0000, v31
	v_cvt_pk_fp8_f32 v107, v252, v68
	v_mul_f32_e32 v254, 0x41000000, v254
	v_mul_f32_e32 v255, 0x41000000, v255
	s_nop 0
	v_cvt_pk_fp8_f32 v107, v254, v255 op_sel:[0,0,1]
	v_lshlrev_b32_e32 v252, 16, v32
	v_and_b32_e32 v68, 0xffff0000, v32
	v_mul_f32_e32 v252, 0x41000000, v252
	v_mul_f32_e32 v68, 0x41000000, v68
	v_lshlrev_b32_e32 v254, 16, v33
	v_and_b32_e32 v255, 0xffff0000, v33
	v_cvt_pk_fp8_f32 v108, v252, v68
	v_mul_f32_e32 v254, 0x41000000, v254
	v_mul_f32_e32 v255, 0x41000000, v255
	s_nop 0
	v_cvt_pk_fp8_f32 v108, v254, v255 op_sel:[0,0,1]
	v_lshlrev_b32_e32 v252, 16, v34
	v_and_b32_e32 v68, 0xffff0000, v34
	v_mul_f32_e32 v252, 0x41000000, v252
	v_mul_f32_e32 v68, 0x41000000, v68
	v_lshlrev_b32_e32 v254, 16, v35
	v_and_b32_e32 v255, 0xffff0000, v35
	v_cvt_pk_fp8_f32 v109, v252, v68
	v_mul_f32_e32 v254, 0x41000000, v254
	v_mul_f32_e32 v255, 0x41000000, v255
	s_nop 0
	v_cvt_pk_fp8_f32 v109, v254, v255 op_sel:[0,0,1]
	v_lshlrev_b32_e32 v252, 16, v36
	v_and_b32_e32 v68, 0xffff0000, v36
	v_mul_f32_e32 v252, 0x41000000, v252
	v_mul_f32_e32 v68, 0x41000000, v68
	v_lshlrev_b32_e32 v254, 16, v37
	v_and_b32_e32 v255, 0xffff0000, v37
	v_cvt_pk_fp8_f32 v110, v252, v68
	v_mul_f32_e32 v254, 0x41000000, v254
	v_mul_f32_e32 v255, 0x41000000, v255
	s_nop 0
	v_cvt_pk_fp8_f32 v110, v254, v255 op_sel:[0,0,1]
	v_lshlrev_b32_e32 v252, 16, v38
	v_and_b32_e32 v68, 0xffff0000, v38
	v_mul_f32_e32 v252, 0x41000000, v252
	v_mul_f32_e32 v68, 0x41000000, v68
	v_lshlrev_b32_e32 v254, 16, v39
	v_and_b32_e32 v255, 0xffff0000, v39
	v_cvt_pk_fp8_f32 v111, v252, v68
	v_mul_f32_e32 v254, 0x41000000, v254
	v_mul_f32_e32 v255, 0x41000000, v255
	s_nop 0
	v_cvt_pk_fp8_f32 v111, v254, v255 op_sel:[0,0,1]
	v_lshlrev_b32_e32 v252, 16, v40
	v_and_b32_e32 v68, 0xffff0000, v40
	v_mul_f32_e32 v252, 0x41000000, v252
	v_mul_f32_e32 v68, 0x41000000, v68
	v_lshlrev_b32_e32 v254, 16, v41
	v_and_b32_e32 v255, 0xffff0000, v41
	v_cvt_pk_fp8_f32 v112, v252, v68
	v_mul_f32_e32 v254, 0x41000000, v254
	v_mul_f32_e32 v255, 0x41000000, v255
	s_nop 0
	v_cvt_pk_fp8_f32 v112, v254, v255 op_sel:[0,0,1]
	v_lshlrev_b32_e32 v252, 16, v42
	v_and_b32_e32 v68, 0xffff0000, v42
	v_mul_f32_e32 v252, 0x41000000, v252
	v_mul_f32_e32 v68, 0x41000000, v68
	v_lshlrev_b32_e32 v254, 16, v43
	v_and_b32_e32 v255, 0xffff0000, v43
	v_cvt_pk_fp8_f32 v113, v252, v68
	v_mul_f32_e32 v254, 0x41000000, v254
	v_mul_f32_e32 v255, 0x41000000, v255
	s_nop 0
	v_cvt_pk_fp8_f32 v113, v254, v255 op_sel:[0,0,1]
	v_lshlrev_b32_e32 v252, 16, v44
	v_and_b32_e32 v68, 0xffff0000, v44
	v_mul_f32_e32 v252, 0x41000000, v252
	v_mul_f32_e32 v68, 0x41000000, v68
	v_lshlrev_b32_e32 v254, 16, v45
	v_and_b32_e32 v255, 0xffff0000, v45
	v_cvt_pk_fp8_f32 v114, v252, v68
	v_mul_f32_e32 v254, 0x41000000, v254
	v_mul_f32_e32 v255, 0x41000000, v255
	s_nop 0
	v_cvt_pk_fp8_f32 v114, v254, v255 op_sel:[0,0,1]
	v_lshlrev_b32_e32 v252, 16, v46
	v_and_b32_e32 v68, 0xffff0000, v46
	v_mul_f32_e32 v252, 0x41000000, v252
	v_mul_f32_e32 v68, 0x41000000, v68
	v_lshlrev_b32_e32 v254, 16, v47
	v_and_b32_e32 v255, 0xffff0000, v47
	v_cvt_pk_fp8_f32 v115, v252, v68
	v_mul_f32_e32 v254, 0x41000000, v254
	v_mul_f32_e32 v255, 0x41000000, v255
	s_nop 0
	v_cvt_pk_fp8_f32 v115, v254, v255 op_sel:[0,0,1]
	v_lshlrev_b32_e32 v252, 16, v48
	v_and_b32_e32 v68, 0xffff0000, v48
	v_mul_f32_e32 v252, 0x41000000, v252
	v_mul_f32_e32 v68, 0x41000000, v68
	v_lshlrev_b32_e32 v254, 16, v49
	v_and_b32_e32 v255, 0xffff0000, v49
	v_cvt_pk_fp8_f32 v116, v252, v68
	v_mul_f32_e32 v254, 0x41000000, v254
	v_mul_f32_e32 v255, 0x41000000, v255
	s_nop 0
	v_cvt_pk_fp8_f32 v116, v254, v255 op_sel:[0,0,1]
	v_lshlrev_b32_e32 v252, 16, v50
	v_and_b32_e32 v68, 0xffff0000, v50
	v_mul_f32_e32 v252, 0x41000000, v252
	v_mul_f32_e32 v68, 0x41000000, v68
	v_lshlrev_b32_e32 v254, 16, v51
	v_and_b32_e32 v255, 0xffff0000, v51
	v_cvt_pk_fp8_f32 v117, v252, v68
	v_mul_f32_e32 v254, 0x41000000, v254
	v_mul_f32_e32 v255, 0x41000000, v255
	s_nop 0
	v_cvt_pk_fp8_f32 v117, v254, v255 op_sel:[0,0,1]
	v_mov_b64_e32 v[20:21], 0
	v_mov_b64_e32 v[22:23], 0
	v_mov_b64_e32 v[24:25], 0
	v_mov_b64_e32 v[26:27], 0
	v_mov_b64_e32 v[28:29], 0
	v_mov_b64_e32 v[30:31], 0
	v_mov_b64_e32 v[32:33], 0
	v_mov_b64_e32 v[34:35], 0
	v_mov_b32_e32 v174, 0
	v_mov_b32_e32 v70, 0
	v_mov_b64_e32 v[36:37], 0
	v_mov_b64_e32 v[38:39], 0
	v_mov_b64_e32 v[40:41], 0
	v_mov_b64_e32 v[42:43], 0
	v_mov_b64_e32 v[44:45], 0
	v_mov_b64_e32 v[46:47], 0
	v_mov_b64_e32 v[48:49], 0
	v_mov_b64_e32 v[50:51], 0
	v_mov_b32_e32 v175, 0
	v_mov_b32_e32 v71, 0
	v_mov_b64_e32 v[52:53], 0
	v_mov_b64_e32 v[54:55], 0
	v_mov_b64_e32 v[56:57], 0
	v_mov_b64_e32 v[58:59], 0
	v_mov_b64_e32 v[60:61], 0
	v_mov_b64_e32 v[62:63], 0
	v_mov_b64_e32 v[64:65], 0
	v_mov_b64_e32 v[66:67], 0
	v_mov_b32_e32 v202, 0
	v_mov_b32_e32 v72, 0
	v_mov_b64_e32 v[84:85], 0
	v_mov_b64_e32 v[86:87], 0
	v_mov_b64_e32 v[88:89], 0
	v_mov_b64_e32 v[90:91], 0
	v_mov_b64_e32 v[92:93], 0
	v_mov_b64_e32 v[94:95], 0
	v_mov_b64_e32 v[96:97], 0
	v_mov_b64_e32 v[98:99], 0
	v_mov_b32_e32 v203, 0
	v_mov_b32_e32 v73, 0
	v_mov_b32_e32 v69, 0xff800000
	v_mov_b32_e32 v253, 0xff800000
	s_waitcnt lgkmcnt(0)
	s_mov_b32 s35, 0
	s_lshl_b32 s9, s35, 2
	s_add_i32 s9, s9, s46
	v_mov_b32_e32 v191, s9
	ds_read_b32 v191, v191 offset:16384
	s_add_i32 s50, s25, -1
	s_min_i32 s50, s50, 1
	s_waitcnt lgkmcnt(0)
	v_readfirstlane_b32 s9, v191
	s_and_b32 s38, s9, 0xffff
	s_lshr_b32 s48, s9, 16
	s_lshl_b32 s9, s50, 2
	s_add_i32 s9, s9, s46
	v_mov_b32_e32 v191, s9
	ds_read_b32 v191, v191 offset:16384
	s_lshl_b32 s29, s38, 12
	s_add_u32 s30, s40, s29
	s_addc_u32 s31, s41, 0
	global_load_dwordx4 v[2:5], v82, s[30:31]
	global_load_dwordx4 v[6:9], v82, s[30:31] offset:1024
	global_load_dwordx4 v[12:15], v82, s[30:31] offset:2048
	global_load_dwordx4 v[16:19], v82, s[30:31] offset:3072
	s_waitcnt lgkmcnt(0)
	v_readfirstlane_b32 s9, v191
	s_and_b32 s27, s9, 0xffff
	s_lshr_b32 s8, s9, 16
.Lbm3_blkA:
	s_lshl_b32 s29, s38, 12
	s_add_u32 s30, s62, s29
	s_addc_u32 s31, s63, 0
	global_load_dwordx4 v[118:121], v82, s[30:31]
	global_load_dwordx4 v[122:125], v82, s[30:31] offset:1024
	global_load_dwordx4 v[126:129], v82, s[30:31] offset:2048
	global_load_dwordx4 v[130:133], v82, s[30:31] offset:3072
	s_lshl_b32 s29, s27, 12
	s_add_u32 s30, s40, s29
	s_addc_u32 s31, s41, 0
	global_load_dwordx4 v[176:179], v82, s[30:31]
	global_load_dwordx4 v[204:207], v82, s[30:31] offset:1024
	global_load_dwordx4 v[208:211], v82, s[30:31] offset:2048
	global_load_dwordx4 v[248:251], v82, s[30:31] offset:3072
	s_add_i32 s50, s35, 2
	s_add_i32 s9, s25, -1
	s_min_i32 s50, s50, s9
	s_lshl_b32 s9, s50, 2
	s_add_i32 s9, s9, s46
	v_mov_b32_e32 v191, s9
	ds_read_b32 v191, v191 offset:16384
	s_cmp_ge_i32 s38, s21
	s_cselect_b32 s50, 1, 0
	s_bfe_u32 s29, s48, 0x40000
	s_cmp_eq_u32 s29, 0
	s_cbranch_scc1 .Lbm3_Ag0_skip
	s_waitcnt vmcnt(8)
	v_mfma_f32_16x16x32_fp8_fp8 v[76:79], v[2:3], v[100:101], 0
	v_mfma_f32_16x16x32_fp8_fp8 v[182:185], v[6:7], v[100:101], 0
	v_mfma_f32_16x16x32_fp8_fp8 v[186:189], v[12:13], v[100:101], 0
	v_mfma_f32_16x16x32_fp8_fp8 v[244:247], v[16:17], v[100:101], 0
	v_mfma_f32_16x16x32_fp8_fp8 v[76:79], v[4:5], v[102:103], v[76:79]
	v_mfma_f32_16x16x32_fp8_fp8 v[182:185], v[8:9], v[102:103], v[182:185]
	v_mfma_f32_16x16x32_fp8_fp8 v[186:189], v[14:15], v[102:103], v[186:189]
	v_mfma_f32_16x16x32_fp8_fp8 v[244:247], v[18:19], v[102:103], v[244:247]
	s_mov_b64 s[4:5], 0
	s_bitcmp1_b32 s29, 0
	s_cselect_b64 s[6:7], s[10:11], 0
	s_or_b64 s[4:5], s[4:5], s[6:7]
	s_bitcmp1_b32 s29, 1
	s_cselect_b64 s[6:7], s[12:13], 0
	s_or_b64 s[4:5], s[4:5], s[6:7]
	s_bitcmp1_b32 s29, 2
	s_cselect_b64 s[6:7], s[54:55], 0
	s_or_b64 s[4:5], s[4:5], s[6:7]
	s_bitcmp1_b32 s29, 3
	s_cselect_b64 s[6:7], s[70:71], 0
	s_or_b64 s[4:5], s[4:5], s[6:7]
	s_cmp_eq_u32 s50, 1
	s_cbranch_scc1 .Lbm3_Ag0_near
	v_add_f32_e32 v190, v81, v174
	v_cndmask_b32_e64 v190, v69, v190, s[4:5]
	v_fmamk_f32 v76, v76, 0x3e38aa3b, v190
	v_fmamk_f32 v77, v77, 0x3e38aa3b, v190
	v_fmamk_f32 v78, v78, 0x3e38aa3b, v190
	v_fmamk_f32 v79, v79, 0x3e38aa3b, v190
	v_fmamk_f32 v182, v182, 0x3e38aa3b, v190
	v_fmamk_f32 v183, v183, 0x3e38aa3b, v190
	v_fmamk_f32 v184, v184, 0x3e38aa3b, v190
	v_fmamk_f32 v185, v185, 0x3e38aa3b, v190
	v_fmamk_f32 v186, v186, 0x3e38aa3b, v190
	v_fmamk_f32 v187, v187, 0x3e38aa3b, v190
	v_fmamk_f32 v188, v188, 0x3e38aa3b, v190
	v_fmamk_f32 v189, v189, 0x3e38aa3b, v190
	v_fmamk_f32 v244, v244, 0x3e38aa3b, v190
	v_fmamk_f32 v245, v245, 0x3e38aa3b, v190
	v_fmamk_f32 v246, v246, 0x3e38aa3b, v190
	v_fmamk_f32 v247, v247, 0x3e38aa3b, v190

.Lbm3_Ag0_near:
	s_lshl_b32 s9, s38, 6
	s_sub_i32 s9, s47, s9
	v_add_u32_e32 v104, s9, v83
	v_cndmask_b32_e64 v190, v69, v174, s[4:5]
	v_mov_b32_e32 v252, v104
	v_min_u32_e32 v254, 0x7f, v252
	v_lshl_add_u32 v254, v254, 2, v80
	ds_read_b32 v254, v254
	v_subrev_u32_e32 v68, 1, v104
	v_min_u32_e32 v255, 0x7f, v68
	v_lshl_add_u32 v255, v255, 2, v80
	ds_read_b32 v255, v255
	s_waitcnt lgkmcnt(0)
	v_fmamk_f32 v254, v254, 0x3fb8aa3b, v190
	v_cmp_le_i32_e32 vcc, 0, v252
	v_fmamk_f32 v76, v76, 0x3e38aa3b, v254
	s_nop 0
	v_cndmask_b32_e32 v76, v69, v76, vcc
	v_fmamk_f32 v255, v255, 0x3fb8aa3b, v190
	v_cmp_le_i32_e32 vcc, 0, v68
	v_fmamk_f32 v77, v77, 0x3e38aa3b, v255
	s_nop 0
	v_cndmask_b32_e32 v77, v69, v77, vcc
	v_subrev_u32_e32 v252, 2, v104
	v_min_u32_e32 v254, 0x7f, v252
	v_lshl_add_u32 v254, v254, 2, v80
	ds_read_b32 v254, v254
	v_subrev_u32_e32 v68, 3, v104
	v_min_u32_e32 v255, 0x7f, v68
	v_lshl_add_u32 v255, v255, 2, v80
	ds_read_b32 v255, v255
	s_waitcnt lgkmcnt(0)
	v_fmamk_f32 v254, v254, 0x3fb8aa3b, v190
	v_cmp_le_i32_e32 vcc, 0, v252
	v_fmamk_f32 v78, v78, 0x3e38aa3b, v254
	s_nop 0
	v_cndmask_b32_e32 v78, v69, v78, vcc
	v_fmamk_f32 v255, v255, 0x3fb8aa3b, v190
	v_cmp_le_i32_e32 vcc, 0, v68
	v_fmamk_f32 v79, v79, 0x3e38aa3b, v255
	s_nop 0
	v_cndmask_b32_e32 v79, v69, v79, vcc
	v_subrev_u32_e32 v252, 16, v104
	v_min_u32_e32 v254, 0x7f, v252
	v_lshl_add_u32 v254, v254, 2, v80
	ds_read_b32 v254, v254
	v_subrev_u32_e32 v68, 17, v104
	v_min_u32_e32 v255, 0x7f, v68
	v_lshl_add_u32 v255, v255, 2, v80
	ds_read_b32 v255, v255
	s_waitcnt lgkmcnt(0)
	v_fmamk_f32 v254, v254, 0x3fb8aa3b, v190
	v_cmp_le_i32_e32 vcc, 0, v252
	v_fmamk_f32 v182, v182, 0x3e38aa3b, v254
	s_nop 0
	v_cndmask_b32_e32 v182, v69, v182, vcc
	v_fmamk_f32 v255, v255, 0x3fb8aa3b, v190
	v_cmp_le_i32_e32 vcc, 0, v68
	v_fmamk_f32 v183, v183, 0x3e38aa3b, v255
	s_nop 0
	v_cndmask_b32_e32 v183, v69, v183, vcc
	v_subrev_u32_e32 v252, 18, v104
	v_min_u32_e32 v254, 0x7f, v252
	v_lshl_add_u32 v254, v254, 2, v80
	ds_read_b32 v254, v254
	v_subrev_u32_e32 v68, 19, v104
	v_min_u32_e32 v255, 0x7f, v68
	v_lshl_add_u32 v255, v255, 2, v80
	ds_read_b32 v255, v255
	s_waitcnt lgkmcnt(0)
	v_fmamk_f32 v254, v254, 0x3fb8aa3b, v190
	v_cmp_le_i32_e32 vcc, 0, v252
	v_fmamk_f32 v184, v184, 0x3e38aa3b, v254
	s_nop 0
	v_cndmask_b32_e32 v184, v69, v184, vcc
	v_fmamk_f32 v255, v255, 0x3fb8aa3b, v190
	v_cmp_le_i32_e32 vcc, 0, v68
	v_fmamk_f32 v185, v185, 0x3e38aa3b, v255
	s_nop 0
	v_cndmask_b32_e32 v185, v69, v185, vcc
	v_subrev_u32_e32 v252, 32, v104
	v_min_u32_e32 v254, 0x7f, v252
	v_lshl_add_u32 v254, v254, 2, v80
	ds_read_b32 v254, v254
	v_subrev_u32_e32 v68, 33, v104
	v_min_u32_e32 v255, 0x7f, v68
	v_lshl_add_u32 v255, v255, 2, v80
	ds_read_b32 v255, v255
	s_waitcnt lgkmcnt(0)
	v_fmamk_f32 v254, v254, 0x3fb8aa3b, v190
	v_cmp_le_i32_e32 vcc, 0, v252
	v_fmamk_f32 v186, v186, 0x3e38aa3b, v254
	s_nop 0
	v_cndmask_b32_e32 v186, v69, v186, vcc
	v_fmamk_f32 v255, v255, 0x3fb8aa3b, v190
	v_cmp_le_i32_e32 vcc, 0, v68
	v_fmamk_f32 v187, v187, 0x3e38aa3b, v255
	s_nop 0
	v_cndmask_b32_e32 v187, v69, v187, vcc
	v_subrev_u32_e32 v252, 34, v104
	v_min_u32_e32 v254, 0x7f, v252
	v_lshl_add_u32 v254, v254, 2, v80
	ds_read_b32 v254, v254
	v_subrev_u32_e32 v68, 35, v104
	v_min_u32_e32 v255, 0x7f, v68
	v_lshl_add_u32 v255, v255, 2, v80
	ds_read_b32 v255, v255
	s_waitcnt lgkmcnt(0)
	v_fmamk_f32 v254, v254, 0x3fb8aa3b, v190
	v_cmp_le_i32_e32 vcc, 0, v252
	v_fmamk_f32 v188, v188, 0x3e38aa3b, v254
	s_nop 0
	v_cndmask_b32_e32 v188, v69, v188, vcc
	v_fmamk_f32 v255, v255, 0x3fb8aa3b, v190
	v_cmp_le_i32_e32 vcc, 0, v68
	v_fmamk_f32 v189, v189, 0x3e38aa3b, v255
	s_nop 0
	v_cndmask_b32_e32 v189, v69, v189, vcc
	v_subrev_u32_e32 v252, 48, v104
	v_min_u32_e32 v254, 0x7f, v252
	v_lshl_add_u32 v254, v254, 2, v80
	ds_read_b32 v254, v254
	v_subrev_u32_e32 v68, 49, v104
	v_min_u32_e32 v255, 0x7f, v68
	v_lshl_add_u32 v255, v255, 2, v80
	ds_read_b32 v255, v255
	s_waitcnt lgkmcnt(0)
	v_fmamk_f32 v254, v254, 0x3fb8aa3b, v190
	v_cmp_le_i32_e32 vcc, 0, v252
	v_fmamk_f32 v244, v244, 0x3e38aa3b, v254
	s_nop 0
	v_cndmask_b32_e32 v244, v69, v244, vcc
	v_fmamk_f32 v255, v255, 0x3fb8aa3b, v190
	v_cmp_le_i32_e32 vcc, 0, v68
	v_fmamk_f32 v245, v245, 0x3e38aa3b, v255
	s_nop 0
	v_cndmask_b32_e32 v245, v69, v245, vcc
	v_subrev_u32_e32 v252, 50, v104
	v_min_u32_e32 v254, 0x7f, v252
	v_lshl_add_u32 v254, v254, 2, v80
	ds_read_b32 v254, v254
	v_subrev_u32_e32 v68, 51, v104
	v_min_u32_e32 v255, 0x7f, v68
	v_lshl_add_u32 v255, v255, 2, v80
	ds_read_b32 v255, v255
	s_waitcnt lgkmcnt(0)
	v_fmamk_f32 v254, v254, 0x3fb8aa3b, v190
	v_cmp_le_i32_e32 vcc, 0, v252
	v_fmamk_f32 v246, v246, 0x3e38aa3b, v254
	s_nop 0
	v_cndmask_b32_e32 v246, v69, v246, vcc
	v_fmamk_f32 v255, v255, 0x3fb8aa3b, v190
	v_cmp_le_i32_e32 vcc, 0, v68
	v_fmamk_f32 v247, v247, 0x3e38aa3b, v255
	s_nop 0
	v_cndmask_b32_e32 v247, v69, v247, vcc
	s_branch .Lbm3_Ag0_max
.Lbm3_Ag0_skip:
	s_bfe_u32 s29, s48, 0x40004
	s_cmp_eq_u32 s29, 0
	s_cbranch_scc1 .Lbm3_Ag1_skip
	s_waitcnt vmcnt(8)
	v_mfma_f32_16x16x32_fp8_fp8 v[76:79], v[2:3], v[106:107], 0
	v_mfma_f32_16x16x32_fp8_fp8 v[182:185], v[6:7], v[106:107], 0
	v_mfma_f32_16x16x32_fp8_fp8 v[186:189], v[12:13], v[106:107], 0
	v_mfma_f32_16x16x32_fp8_fp8 v[244:247], v[16:17], v[106:107], 0
	v_mfma_f32_16x16x32_fp8_fp8 v[76:79], v[4:5], v[108:109], v[76:79]
	v_mfma_f32_16x16x32_fp8_fp8 v[182:185], v[8:9], v[108:109], v[182:185]
	v_mfma_f32_16x16x32_fp8_fp8 v[186:189], v[14:15], v[108:109], v[186:189]
	v_mfma_f32_16x16x32_fp8_fp8 v[244:247], v[18:19], v[108:109], v[244:247]
	s_mov_b64 s[4:5], 0
	s_bitcmp1_b32 s29, 0
	s_cselect_b64 s[6:7], s[10:11], 0
	s_or_b64 s[4:5], s[4:5], s[6:7]
	s_bitcmp1_b32 s29, 1
	s_cselect_b64 s[6:7], s[12:13], 0
	s_or_b64 s[4:5], s[4:5], s[6:7]
	s_bitcmp1_b32 s29, 2
	s_cselect_b64 s[6:7], s[54:55], 0
	s_or_b64 s[4:5], s[4:5], s[6:7]
	s_bitcmp1_b32 s29, 3
	s_cselect_b64 s[6:7], s[70:71], 0
	s_or_b64 s[4:5], s[4:5], s[6:7]
	s_cmp_eq_u32 s50, 1
	s_cbranch_scc1 .Lbm3_Ag1_near
	v_add_f32_e32 v190, v81, v175
	v_cndmask_b32_e64 v190, v69, v190, s[4:5]
	v_fmamk_f32 v76, v76, 0x3e38aa3b, v190
	v_fmamk_f32 v77, v77, 0x3e38aa3b, v190
	v_fmamk_f32 v78, v78, 0x3e38aa3b, v190
	v_fmamk_f32 v79, v79, 0x3e38aa3b, v190
	v_fmamk_f32 v182, v182, 0x3e38aa3b, v190
	v_fmamk_f32 v183, v183, 0x3e38aa3b, v190
	v_fmamk_f32 v184, v184, 0x3e38aa3b, v190
	v_fmamk_f32 v185, v185, 0x3e38aa3b, v190
	v_fmamk_f32 v186, v186, 0x3e38aa3b, v190
	v_fmamk_f32 v187, v187, 0x3e38aa3b, v190
	v_fmamk_f32 v188, v188, 0x3e38aa3b, v190
	v_fmamk_f32 v189, v189, 0x3e38aa3b, v190
	v_fmamk_f32 v244, v244, 0x3e38aa3b, v190
	v_fmamk_f32 v245, v245, 0x3e38aa3b, v190
	v_fmamk_f32 v246, v246, 0x3e38aa3b, v190
	v_fmamk_f32 v247, v247, 0x3e38aa3b, v190

.Lbm3_Ag1_near:
	s_lshl_b32 s9, s38, 6
	s_sub_i32 s9, s47, s9
	s_add_i32 s9, s9, 4
	v_add_u32_e32 v104, s9, v83
	v_cndmask_b32_e64 v190, v69, v175, s[4:5]
	v_mov_b32_e32 v252, v104
	v_min_u32_e32 v254, 0x7f, v252
	v_lshl_add_u32 v254, v254, 2, v80
	ds_read_b32 v254, v254
	v_subrev_u32_e32 v68, 1, v104
	v_min_u32_e32 v255, 0x7f, v68
	v_lshl_add_u32 v255, v255, 2, v80
	ds_read_b32 v255, v255
	s_waitcnt lgkmcnt(0)
	v_fmamk_f32 v254, v254, 0x3fb8aa3b, v190
	v_cmp_le_i32_e32 vcc, 0, v252
	v_fmamk_f32 v76, v76, 0x3e38aa3b, v254
	s_nop 0
	v_cndmask_b32_e32 v76, v69, v76, vcc
	v_fmamk_f32 v255, v255, 0x3fb8aa3b, v190
	v_cmp_le_i32_e32 vcc, 0, v68
	v_fmamk_f32 v77, v77, 0x3e38aa3b, v255
	s_nop 0
	v_cndmask_b32_e32 v77, v69, v77, vcc
	v_subrev_u32_e32 v252, 2, v104
	v_min_u32_e32 v254, 0x7f, v252
	v_lshl_add_u32 v254, v254, 2, v80
	ds_read_b32 v254, v254
	v_subrev_u32_e32 v68, 3, v104
	v_min_u32_e32 v255, 0x7f, v68
	v_lshl_add_u32 v255, v255, 2, v80
	ds_read_b32 v255, v255
	s_waitcnt lgkmcnt(0)
	v_fmamk_f32 v254, v254, 0x3fb8aa3b, v190
	v_cmp_le_i32_e32 vcc, 0, v252
	v_fmamk_f32 v78, v78, 0x3e38aa3b, v254
	s_nop 0
	v_cndmask_b32_e32 v78, v69, v78, vcc
	v_fmamk_f32 v255, v255, 0x3fb8aa3b, v190
	v_cmp_le_i32_e32 vcc, 0, v68
	v_fmamk_f32 v79, v79, 0x3e38aa3b, v255
	s_nop 0
	v_cndmask_b32_e32 v79, v69, v79, vcc
	v_subrev_u32_e32 v252, 16, v104
	v_min_u32_e32 v254, 0x7f, v252
	v_lshl_add_u32 v254, v254, 2, v80
	ds_read_b32 v254, v254
	v_subrev_u32_e32 v68, 17, v104
	v_min_u32_e32 v255, 0x7f, v68
	v_lshl_add_u32 v255, v255, 2, v80
	ds_read_b32 v255, v255
	s_waitcnt lgkmcnt(0)
	v_fmamk_f32 v254, v254, 0x3fb8aa3b, v190
	v_cmp_le_i32_e32 vcc, 0, v252
	v_fmamk_f32 v182, v182, 0x3e38aa3b, v254
	s_nop 0
	v_cndmask_b32_e32 v182, v69, v182, vcc
	v_fmamk_f32 v255, v255, 0x3fb8aa3b, v190
	v_cmp_le_i32_e32 vcc, 0, v68
	v_fmamk_f32 v183, v183, 0x3e38aa3b, v255
	s_nop 0
	v_cndmask_b32_e32 v183, v69, v183, vcc
	v_subrev_u32_e32 v252, 18, v104
	v_min_u32_e32 v254, 0x7f, v252
	v_lshl_add_u32 v254, v254, 2, v80
	ds_read_b32 v254, v254
	v_subrev_u32_e32 v68, 19, v104
	v_min_u32_e32 v255, 0x7f, v68
	v_lshl_add_u32 v255, v255, 2, v80
	ds_read_b32 v255, v255
	s_waitcnt lgkmcnt(0)
	v_fmamk_f32 v254, v254, 0x3fb8aa3b, v190
	v_cmp_le_i32_e32 vcc, 0, v252
	v_fmamk_f32 v184, v184, 0x3e38aa3b, v254
	s_nop 0
	v_cndmask_b32_e32 v184, v69, v184, vcc
	v_fmamk_f32 v255, v255, 0x3fb8aa3b, v190
	v_cmp_le_i32_e32 vcc, 0, v68
	v_fmamk_f32 v185, v185, 0x3e38aa3b, v255
	s_nop 0
	v_cndmask_b32_e32 v185, v69, v185, vcc
	v_subrev_u32_e32 v252, 32, v104
	v_min_u32_e32 v254, 0x7f, v252
	v_lshl_add_u32 v254, v254, 2, v80
	ds_read_b32 v254, v254
	v_subrev_u32_e32 v68, 33, v104
	v_min_u32_e32 v255, 0x7f, v68
	v_lshl_add_u32 v255, v255, 2, v80
	ds_read_b32 v255, v255
	s_waitcnt lgkmcnt(0)
	v_fmamk_f32 v254, v254, 0x3fb8aa3b, v190
	v_cmp_le_i32_e32 vcc, 0, v252
	v_fmamk_f32 v186, v186, 0x3e38aa3b, v254
	s_nop 0
	v_cndmask_b32_e32 v186, v69, v186, vcc
	v_fmamk_f32 v255, v255, 0x3fb8aa3b, v190
	v_cmp_le_i32_e32 vcc, 0, v68
	v_fmamk_f32 v187, v187, 0x3e38aa3b, v255
	s_nop 0
	v_cndmask_b32_e32 v187, v69, v187, vcc
	v_subrev_u32_e32 v252, 34, v104
	v_min_u32_e32 v254, 0x7f, v252
	v_lshl_add_u32 v254, v254, 2, v80
	ds_read_b32 v254, v254
	v_subrev_u32_e32 v68, 35, v104
	v_min_u32_e32 v255, 0x7f, v68
	v_lshl_add_u32 v255, v255, 2, v80
	ds_read_b32 v255, v255
	s_waitcnt lgkmcnt(0)
	v_fmamk_f32 v254, v254, 0x3fb8aa3b, v190
	v_cmp_le_i32_e32 vcc, 0, v252
	v_fmamk_f32 v188, v188, 0x3e38aa3b, v254
	s_nop 0
	v_cndmask_b32_e32 v188, v69, v188, vcc
	v_fmamk_f32 v255, v255, 0x3fb8aa3b, v190
	v_cmp_le_i32_e32 vcc, 0, v68
	v_fmamk_f32 v189, v189, 0x3e38aa3b, v255
	s_nop 0
	v_cndmask_b32_e32 v189, v69, v189, vcc
	v_subrev_u32_e32 v252, 48, v104
	v_min_u32_e32 v254, 0x7f, v252
	v_lshl_add_u32 v254, v254, 2, v80
	ds_read_b32 v254, v254
	v_subrev_u32_e32 v68, 49, v104
	v_min_u32_e32 v255, 0x7f, v68
	v_lshl_add_u32 v255, v255, 2, v80
	ds_read_b32 v255, v255
	s_waitcnt lgkmcnt(0)
	v_fmamk_f32 v254, v254, 0x3fb8aa3b, v190
	v_cmp_le_i32_e32 vcc, 0, v252
	v_fmamk_f32 v244, v244, 0x3e38aa3b, v254
	s_nop 0
	v_cndmask_b32_e32 v244, v69, v244, vcc
	v_fmamk_f32 v255, v255, 0x3fb8aa3b, v190
	v_cmp_le_i32_e32 vcc, 0, v68
	v_fmamk_f32 v245, v245, 0x3e38aa3b, v255
	s_nop 0
	v_cndmask_b32_e32 v245, v69, v245, vcc
	v_subrev_u32_e32 v252, 50, v104
	v_min_u32_e32 v254, 0x7f, v252
	v_lshl_add_u32 v254, v254, 2, v80
	ds_read_b32 v254, v254
	v_subrev_u32_e32 v68, 51, v104
	v_min_u32_e32 v255, 0x7f, v68
	v_lshl_add_u32 v255, v255, 2, v80
	ds_read_b32 v255, v255
	s_waitcnt lgkmcnt(0)
	v_fmamk_f32 v254, v254, 0x3fb8aa3b, v190
	v_cmp_le_i32_e32 vcc, 0, v252
	v_fmamk_f32 v246, v246, 0x3e38aa3b, v254
	s_nop 0
	v_cndmask_b32_e32 v246, v69, v246, vcc
	v_fmamk_f32 v255, v255, 0x3fb8aa3b, v190
	v_cmp_le_i32_e32 vcc, 0, v68
	v_fmamk_f32 v247, v247, 0x3e38aa3b, v255
	s_nop 0
	v_cndmask_b32_e32 v247, v69, v247, vcc
	s_branch .Lbm3_Ag1_max
.Lbm3_Ag1_skip:
	s_bfe_u32 s29, s48, 0x40008
	s_cmp_eq_u32 s29, 0
	s_cbranch_scc1 .Lbm3_Ag2_skip
	s_waitcnt vmcnt(8)
	v_mfma_f32_16x16x32_fp8_fp8 v[76:79], v[2:3], v[110:111], 0
	v_mfma_f32_16x16x32_fp8_fp8 v[182:185], v[6:7], v[110:111], 0
	v_mfma_f32_16x16x32_fp8_fp8 v[186:189], v[12:13], v[110:111], 0
	v_mfma_f32_16x16x32_fp8_fp8 v[244:247], v[16:17], v[110:111], 0
	v_mfma_f32_16x16x32_fp8_fp8 v[76:79], v[4:5], v[112:113], v[76:79]
	v_mfma_f32_16x16x32_fp8_fp8 v[182:185], v[8:9], v[112:113], v[182:185]
	v_mfma_f32_16x16x32_fp8_fp8 v[186:189], v[14:15], v[112:113], v[186:189]
	v_mfma_f32_16x16x32_fp8_fp8 v[244:247], v[18:19], v[112:113], v[244:247]
	s_mov_b64 s[4:5], 0
	s_bitcmp1_b32 s29, 0
	s_cselect_b64 s[6:7], s[10:11], 0
	s_or_b64 s[4:5], s[4:5], s[6:7]
	s_bitcmp1_b32 s29, 1
	s_cselect_b64 s[6:7], s[12:13], 0
	s_or_b64 s[4:5], s[4:5], s[6:7]
	s_bitcmp1_b32 s29, 2
	s_cselect_b64 s[6:7], s[54:55], 0
	s_or_b64 s[4:5], s[4:5], s[6:7]
	s_bitcmp1_b32 s29, 3
	s_cselect_b64 s[6:7], s[70:71], 0
	s_or_b64 s[4:5], s[4:5], s[6:7]
	s_cmp_eq_u32 s50, 1
	s_cbranch_scc1 .Lbm3_Ag2_near
	v_add_f32_e32 v190, v81, v202
	v_cndmask_b32_e64 v190, v69, v190, s[4:5]
	v_fmamk_f32 v76, v76, 0x3e38aa3b, v190
	v_fmamk_f32 v77, v77, 0x3e38aa3b, v190
	v_fmamk_f32 v78, v78, 0x3e38aa3b, v190
	v_fmamk_f32 v79, v79, 0x3e38aa3b, v190
	v_fmamk_f32 v182, v182, 0x3e38aa3b, v190
	v_fmamk_f32 v183, v183, 0x3e38aa3b, v190
	v_fmamk_f32 v184, v184, 0x3e38aa3b, v190
	v_fmamk_f32 v185, v185, 0x3e38aa3b, v190
	v_fmamk_f32 v186, v186, 0x3e38aa3b, v190
	v_fmamk_f32 v187, v187, 0x3e38aa3b, v190
	v_fmamk_f32 v188, v188, 0x3e38aa3b, v190
	v_fmamk_f32 v189, v189, 0x3e38aa3b, v190
	v_fmamk_f32 v244, v244, 0x3e38aa3b, v190
	v_fmamk_f32 v245, v245, 0x3e38aa3b, v190
	v_fmamk_f32 v246, v246, 0x3e38aa3b, v190
	v_fmamk_f32 v247, v247, 0x3e38aa3b, v190

.Lbm3_Ag2_near:
	s_lshl_b32 s9, s38, 6
	s_sub_i32 s9, s47, s9
	s_add_i32 s9, s9, 8
	v_add_u32_e32 v104, s9, v83
	v_cndmask_b32_e64 v190, v69, v202, s[4:5]
	v_mov_b32_e32 v252, v104
	v_min_u32_e32 v254, 0x7f, v252
	v_lshl_add_u32 v254, v254, 2, v80
	ds_read_b32 v254, v254
	v_subrev_u32_e32 v68, 1, v104
	v_min_u32_e32 v255, 0x7f, v68
	v_lshl_add_u32 v255, v255, 2, v80
	ds_read_b32 v255, v255
	s_waitcnt lgkmcnt(0)
	v_fmamk_f32 v254, v254, 0x3fb8aa3b, v190
	v_cmp_le_i32_e32 vcc, 0, v252
	v_fmamk_f32 v76, v76, 0x3e38aa3b, v254
	s_nop 0
	v_cndmask_b32_e32 v76, v69, v76, vcc
	v_fmamk_f32 v255, v255, 0x3fb8aa3b, v190
	v_cmp_le_i32_e32 vcc, 0, v68
	v_fmamk_f32 v77, v77, 0x3e38aa3b, v255
	s_nop 0
	v_cndmask_b32_e32 v77, v69, v77, vcc
	v_subrev_u32_e32 v252, 2, v104
	v_min_u32_e32 v254, 0x7f, v252
	v_lshl_add_u32 v254, v254, 2, v80
	ds_read_b32 v254, v254
	v_subrev_u32_e32 v68, 3, v104
	v_min_u32_e32 v255, 0x7f, v68
	v_lshl_add_u32 v255, v255, 2, v80
	ds_read_b32 v255, v255
	s_waitcnt lgkmcnt(0)
	v_fmamk_f32 v254, v254, 0x3fb8aa3b, v190
	v_cmp_le_i32_e32 vcc, 0, v252
	v_fmamk_f32 v78, v78, 0x3e38aa3b, v254
	s_nop 0
	v_cndmask_b32_e32 v78, v69, v78, vcc
	v_fmamk_f32 v255, v255, 0x3fb8aa3b, v190
	v_cmp_le_i32_e32 vcc, 0, v68
	v_fmamk_f32 v79, v79, 0x3e38aa3b, v255
	s_nop 0
	v_cndmask_b32_e32 v79, v69, v79, vcc
	v_subrev_u32_e32 v252, 16, v104
	v_min_u32_e32 v254, 0x7f, v252
	v_lshl_add_u32 v254, v254, 2, v80
	ds_read_b32 v254, v254
	v_subrev_u32_e32 v68, 17, v104
	v_min_u32_e32 v255, 0x7f, v68
	v_lshl_add_u32 v255, v255, 2, v80
	ds_read_b32 v255, v255
	s_waitcnt lgkmcnt(0)
	v_fmamk_f32 v254, v254, 0x3fb8aa3b, v190
	v_cmp_le_i32_e32 vcc, 0, v252
	v_fmamk_f32 v182, v182, 0x3e38aa3b, v254
	s_nop 0
	v_cndmask_b32_e32 v182, v69, v182, vcc
	v_fmamk_f32 v255, v255, 0x3fb8aa3b, v190
	v_cmp_le_i32_e32 vcc, 0, v68
	v_fmamk_f32 v183, v183, 0x3e38aa3b, v255
	s_nop 0
	v_cndmask_b32_e32 v183, v69, v183, vcc
	v_subrev_u32_e32 v252, 18, v104
	v_min_u32_e32 v254, 0x7f, v252
	v_lshl_add_u32 v254, v254, 2, v80
	ds_read_b32 v254, v254
	v_subrev_u32_e32 v68, 19, v104
	v_min_u32_e32 v255, 0x7f, v68
	v_lshl_add_u32 v255, v255, 2, v80
	ds_read_b32 v255, v255
	s_waitcnt lgkmcnt(0)
	v_fmamk_f32 v254, v254, 0x3fb8aa3b, v190
	v_cmp_le_i32_e32 vcc, 0, v252
	v_fmamk_f32 v184, v184, 0x3e38aa3b, v254
	s_nop 0
	v_cndmask_b32_e32 v184, v69, v184, vcc
	v_fmamk_f32 v255, v255, 0x3fb8aa3b, v190
	v_cmp_le_i32_e32 vcc, 0, v68
	v_fmamk_f32 v185, v185, 0x3e38aa3b, v255
	s_nop 0
	v_cndmask_b32_e32 v185, v69, v185, vcc
	v_subrev_u32_e32 v252, 32, v104
	v_min_u32_e32 v254, 0x7f, v252
	v_lshl_add_u32 v254, v254, 2, v80
	ds_read_b32 v254, v254
	v_subrev_u32_e32 v68, 33, v104
	v_min_u32_e32 v255, 0x7f, v68
	v_lshl_add_u32 v255, v255, 2, v80
	ds_read_b32 v255, v255
	s_waitcnt lgkmcnt(0)
	v_fmamk_f32 v254, v254, 0x3fb8aa3b, v190
	v_cmp_le_i32_e32 vcc, 0, v252
	v_fmamk_f32 v186, v186, 0x3e38aa3b, v254
	s_nop 0
	v_cndmask_b32_e32 v186, v69, v186, vcc
	v_fmamk_f32 v255, v255, 0x3fb8aa3b, v190
	v_cmp_le_i32_e32 vcc, 0, v68
	v_fmamk_f32 v187, v187, 0x3e38aa3b, v255
	s_nop 0
	v_cndmask_b32_e32 v187, v69, v187, vcc
	v_subrev_u32_e32 v252, 34, v104
	v_min_u32_e32 v254, 0x7f, v252
	v_lshl_add_u32 v254, v254, 2, v80
	ds_read_b32 v254, v254
	v_subrev_u32_e32 v68, 35, v104
	v_min_u32_e32 v255, 0x7f, v68
	v_lshl_add_u32 v255, v255, 2, v80
	ds_read_b32 v255, v255
	s_waitcnt lgkmcnt(0)
	v_fmamk_f32 v254, v254, 0x3fb8aa3b, v190
	v_cmp_le_i32_e32 vcc, 0, v252
	v_fmamk_f32 v188, v188, 0x3e38aa3b, v254
	s_nop 0
	v_cndmask_b32_e32 v188, v69, v188, vcc
	v_fmamk_f32 v255, v255, 0x3fb8aa3b, v190
	v_cmp_le_i32_e32 vcc, 0, v68
	v_fmamk_f32 v189, v189, 0x3e38aa3b, v255
	s_nop 0
	v_cndmask_b32_e32 v189, v69, v189, vcc
	v_subrev_u32_e32 v252, 48, v104
	v_min_u32_e32 v254, 0x7f, v252
	v_lshl_add_u32 v254, v254, 2, v80
	ds_read_b32 v254, v254
	v_subrev_u32_e32 v68, 49, v104
	v_min_u32_e32 v255, 0x7f, v68
	v_lshl_add_u32 v255, v255, 2, v80
	ds_read_b32 v255, v255
	s_waitcnt lgkmcnt(0)
	v_fmamk_f32 v254, v254, 0x3fb8aa3b, v190
	v_cmp_le_i32_e32 vcc, 0, v252
	v_fmamk_f32 v244, v244, 0x3e38aa3b, v254
	s_nop 0
	v_cndmask_b32_e32 v244, v69, v244, vcc
	v_fmamk_f32 v255, v255, 0x3fb8aa3b, v190
	v_cmp_le_i32_e32 vcc, 0, v68
	v_fmamk_f32 v245, v245, 0x3e38aa3b, v255
	s_nop 0
	v_cndmask_b32_e32 v245, v69, v245, vcc
	v_subrev_u32_e32 v252, 50, v104
	v_min_u32_e32 v254, 0x7f, v252
	v_lshl_add_u32 v254, v254, 2, v80
	ds_read_b32 v254, v254
	v_subrev_u32_e32 v68, 51, v104
	v_min_u32_e32 v255, 0x7f, v68
	v_lshl_add_u32 v255, v255, 2, v80
	ds_read_b32 v255, v255
	s_waitcnt lgkmcnt(0)
	v_fmamk_f32 v254, v254, 0x3fb8aa3b, v190
	v_cmp_le_i32_e32 vcc, 0, v252
	v_fmamk_f32 v246, v246, 0x3e38aa3b, v254
	s_nop 0
	v_cndmask_b32_e32 v246, v69, v246, vcc
	v_fmamk_f32 v255, v255, 0x3fb8aa3b, v190
	v_cmp_le_i32_e32 vcc, 0, v68
	v_fmamk_f32 v247, v247, 0x3e38aa3b, v255
	s_nop 0
	v_cndmask_b32_e32 v247, v69, v247, vcc
	s_branch .Lbm3_Ag2_max
.Lbm3_Ag2_skip:
	s_bfe_u32 s29, s48, 0x4000c
	s_cmp_eq_u32 s29, 0
	s_cbranch_scc1 .Lbm3_Ag3_skip
	s_waitcnt vmcnt(8)
	v_mfma_f32_16x16x32_fp8_fp8 v[76:79], v[2:3], v[114:115], 0
	v_mfma_f32_16x16x32_fp8_fp8 v[182:185], v[6:7], v[114:115], 0
	v_mfma_f32_16x16x32_fp8_fp8 v[186:189], v[12:13], v[114:115], 0
	v_mfma_f32_16x16x32_fp8_fp8 v[244:247], v[16:17], v[114:115], 0
	v_mfma_f32_16x16x32_fp8_fp8 v[76:79], v[4:5], v[116:117], v[76:79]
	v_mfma_f32_16x16x32_fp8_fp8 v[182:185], v[8:9], v[116:117], v[182:185]
	v_mfma_f32_16x16x32_fp8_fp8 v[186:189], v[14:15], v[116:117], v[186:189]
	v_mfma_f32_16x16x32_fp8_fp8 v[244:247], v[18:19], v[116:117], v[244:247]
	s_mov_b64 s[4:5], 0
	s_bitcmp1_b32 s29, 0
	s_cselect_b64 s[6:7], s[10:11], 0
	s_or_b64 s[4:5], s[4:5], s[6:7]
	s_bitcmp1_b32 s29, 1
	s_cselect_b64 s[6:7], s[12:13], 0
	s_or_b64 s[4:5], s[4:5], s[6:7]
	s_bitcmp1_b32 s29, 2
	s_cselect_b64 s[6:7], s[54:55], 0
	s_or_b64 s[4:5], s[4:5], s[6:7]
	s_bitcmp1_b32 s29, 3
	s_cselect_b64 s[6:7], s[70:71], 0
	s_or_b64 s[4:5], s[4:5], s[6:7]
	s_cmp_eq_u32 s50, 1
	s_cbranch_scc1 .Lbm3_Ag3_near
	v_add_f32_e32 v190, v81, v203
	v_cndmask_b32_e64 v190, v69, v190, s[4:5]
	v_fmamk_f32 v76, v76, 0x3e38aa3b, v190
	v_fmamk_f32 v77, v77, 0x3e38aa3b, v190
	v_fmamk_f32 v78, v78, 0x3e38aa3b, v190
	v_fmamk_f32 v79, v79, 0x3e38aa3b, v190
	v_fmamk_f32 v182, v182, 0x3e38aa3b, v190
	v_fmamk_f32 v183, v183, 0x3e38aa3b, v190
	v_fmamk_f32 v184, v184, 0x3e38aa3b, v190
	v_fmamk_f32 v185, v185, 0x3e38aa3b, v190
	v_fmamk_f32 v186, v186, 0x3e38aa3b, v190
	v_fmamk_f32 v187, v187, 0x3e38aa3b, v190
	v_fmamk_f32 v188, v188, 0x3e38aa3b, v190
	v_fmamk_f32 v189, v189, 0x3e38aa3b, v190
	v_fmamk_f32 v244, v244, 0x3e38aa3b, v190
	v_fmamk_f32 v245, v245, 0x3e38aa3b, v190
	v_fmamk_f32 v246, v246, 0x3e38aa3b, v190
	v_fmamk_f32 v247, v247, 0x3e38aa3b, v190

.Lbm3_Ag3_near:
	s_lshl_b32 s9, s38, 6
	s_sub_i32 s9, s47, s9
	s_add_i32 s9, s9, 12
	v_add_u32_e32 v104, s9, v83
	v_cndmask_b32_e64 v190, v69, v203, s[4:5]
	v_mov_b32_e32 v252, v104
	v_min_u32_e32 v254, 0x7f, v252
	v_lshl_add_u32 v254, v254, 2, v80
	ds_read_b32 v254, v254
	v_subrev_u32_e32 v68, 1, v104
	v_min_u32_e32 v255, 0x7f, v68
	v_lshl_add_u32 v255, v255, 2, v80
	ds_read_b32 v255, v255
	s_waitcnt lgkmcnt(0)
	v_fmamk_f32 v254, v254, 0x3fb8aa3b, v190
	v_cmp_le_i32_e32 vcc, 0, v252
	v_fmamk_f32 v76, v76, 0x3e38aa3b, v254
	s_nop 0
	v_cndmask_b32_e32 v76, v69, v76, vcc
	v_fmamk_f32 v255, v255, 0x3fb8aa3b, v190
	v_cmp_le_i32_e32 vcc, 0, v68
	v_fmamk_f32 v77, v77, 0x3e38aa3b, v255
	s_nop 0
	v_cndmask_b32_e32 v77, v69, v77, vcc
	v_subrev_u32_e32 v252, 2, v104
	v_min_u32_e32 v254, 0x7f, v252
	v_lshl_add_u32 v254, v254, 2, v80
	ds_read_b32 v254, v254
	v_subrev_u32_e32 v68, 3, v104
	v_min_u32_e32 v255, 0x7f, v68
	v_lshl_add_u32 v255, v255, 2, v80
	ds_read_b32 v255, v255
	s_waitcnt lgkmcnt(0)
	v_fmamk_f32 v254, v254, 0x3fb8aa3b, v190
	v_cmp_le_i32_e32 vcc, 0, v252
	v_fmamk_f32 v78, v78, 0x3e38aa3b, v254
	s_nop 0
	v_cndmask_b32_e32 v78, v69, v78, vcc
	v_fmamk_f32 v255, v255, 0x3fb8aa3b, v190
	v_cmp_le_i32_e32 vcc, 0, v68
	v_fmamk_f32 v79, v79, 0x3e38aa3b, v255
	s_nop 0
	v_cndmask_b32_e32 v79, v69, v79, vcc
	v_subrev_u32_e32 v252, 16, v104
	v_min_u32_e32 v254, 0x7f, v252
	v_lshl_add_u32 v254, v254, 2, v80
	ds_read_b32 v254, v254
	v_subrev_u32_e32 v68, 17, v104
	v_min_u32_e32 v255, 0x7f, v68
	v_lshl_add_u32 v255, v255, 2, v80
	ds_read_b32 v255, v255
	s_waitcnt lgkmcnt(0)
	v_fmamk_f32 v254, v254, 0x3fb8aa3b, v190
	v_cmp_le_i32_e32 vcc, 0, v252
	v_fmamk_f32 v182, v182, 0x3e38aa3b, v254
	s_nop 0
	v_cndmask_b32_e32 v182, v69, v182, vcc
	v_fmamk_f32 v255, v255, 0x3fb8aa3b, v190
	v_cmp_le_i32_e32 vcc, 0, v68
	v_fmamk_f32 v183, v183, 0x3e38aa3b, v255
	s_nop 0
	v_cndmask_b32_e32 v183, v69, v183, vcc
	v_subrev_u32_e32 v252, 18, v104
	v_min_u32_e32 v254, 0x7f, v252
	v_lshl_add_u32 v254, v254, 2, v80
	ds_read_b32 v254, v254
	v_subrev_u32_e32 v68, 19, v104
	v_min_u32_e32 v255, 0x7f, v68
	v_lshl_add_u32 v255, v255, 2, v80
	ds_read_b32 v255, v255
	s_waitcnt lgkmcnt(0)
	v_fmamk_f32 v254, v254, 0x3fb8aa3b, v190
	v_cmp_le_i32_e32 vcc, 0, v252
	v_fmamk_f32 v184, v184, 0x3e38aa3b, v254
	s_nop 0
	v_cndmask_b32_e32 v184, v69, v184, vcc
	v_fmamk_f32 v255, v255, 0x3fb8aa3b, v190
	v_cmp_le_i32_e32 vcc, 0, v68
	v_fmamk_f32 v185, v185, 0x3e38aa3b, v255
	s_nop 0
	v_cndmask_b32_e32 v185, v69, v185, vcc
	v_subrev_u32_e32 v252, 32, v104
	v_min_u32_e32 v254, 0x7f, v252
	v_lshl_add_u32 v254, v254, 2, v80
	ds_read_b32 v254, v254
	v_subrev_u32_e32 v68, 33, v104
	v_min_u32_e32 v255, 0x7f, v68
	v_lshl_add_u32 v255, v255, 2, v80
	ds_read_b32 v255, v255
	s_waitcnt lgkmcnt(0)
	v_fmamk_f32 v254, v254, 0x3fb8aa3b, v190
	v_cmp_le_i32_e32 vcc, 0, v252
	v_fmamk_f32 v186, v186, 0x3e38aa3b, v254
	s_nop 0
	v_cndmask_b32_e32 v186, v69, v186, vcc
	v_fmamk_f32 v255, v255, 0x3fb8aa3b, v190
	v_cmp_le_i32_e32 vcc, 0, v68
	v_fmamk_f32 v187, v187, 0x3e38aa3b, v255
	s_nop 0
	v_cndmask_b32_e32 v187, v69, v187, vcc
	v_subrev_u32_e32 v252, 34, v104
	v_min_u32_e32 v254, 0x7f, v252
	v_lshl_add_u32 v254, v254, 2, v80
	ds_read_b32 v254, v254
	v_subrev_u32_e32 v68, 35, v104
	v_min_u32_e32 v255, 0x7f, v68
	v_lshl_add_u32 v255, v255, 2, v80
	ds_read_b32 v255, v255
	s_waitcnt lgkmcnt(0)
	v_fmamk_f32 v254, v254, 0x3fb8aa3b, v190
	v_cmp_le_i32_e32 vcc, 0, v252
	v_fmamk_f32 v188, v188, 0x3e38aa3b, v254
	s_nop 0
	v_cndmask_b32_e32 v188, v69, v188, vcc
	v_fmamk_f32 v255, v255, 0x3fb8aa3b, v190
	v_cmp_le_i32_e32 vcc, 0, v68
	v_fmamk_f32 v189, v189, 0x3e38aa3b, v255
	s_nop 0
	v_cndmask_b32_e32 v189, v69, v189, vcc
	v_subrev_u32_e32 v252, 48, v104
	v_min_u32_e32 v254, 0x7f, v252
	v_lshl_add_u32 v254, v254, 2, v80
	ds_read_b32 v254, v254
	v_subrev_u32_e32 v68, 49, v104
	v_min_u32_e32 v255, 0x7f, v68
	v_lshl_add_u32 v255, v255, 2, v80
	ds_read_b32 v255, v255
	s_waitcnt lgkmcnt(0)
	v_fmamk_f32 v254, v254, 0x3fb8aa3b, v190
	v_cmp_le_i32_e32 vcc, 0, v252
	v_fmamk_f32 v244, v244, 0x3e38aa3b, v254
	s_nop 0
	v_cndmask_b32_e32 v244, v69, v244, vcc
	v_fmamk_f32 v255, v255, 0x3fb8aa3b, v190
	v_cmp_le_i32_e32 vcc, 0, v68
	v_fmamk_f32 v245, v245, 0x3e38aa3b, v255
	s_nop 0
	v_cndmask_b32_e32 v245, v69, v245, vcc
	v_subrev_u32_e32 v252, 50, v104
	v_min_u32_e32 v254, 0x7f, v252
	v_lshl_add_u32 v254, v254, 2, v80
	ds_read_b32 v254, v254
	v_subrev_u32_e32 v68, 51, v104
	v_min_u32_e32 v255, 0x7f, v68
	v_lshl_add_u32 v255, v255, 2, v80
	ds_read_b32 v255, v255
	s_waitcnt lgkmcnt(0)
	v_fmamk_f32 v254, v254, 0x3fb8aa3b, v190
	v_cmp_le_i32_e32 vcc, 0, v252
	v_fmamk_f32 v246, v246, 0x3e38aa3b, v254
	s_nop 0
	v_cndmask_b32_e32 v246, v69, v246, vcc
	v_fmamk_f32 v255, v255, 0x3fb8aa3b, v190
	v_cmp_le_i32_e32 vcc, 0, v68
	v_fmamk_f32 v247, v247, 0x3e38aa3b, v255
	s_nop 0
	v_cndmask_b32_e32 v247, v69, v247, vcc
	s_branch .Lbm3_Ag3_max
.Lbm3_Ag3_skip:
	v_mov_b32_e32 v253, 0
	s_mov_b32 s38, s27
	s_mov_b32 s48, s8
	s_waitcnt lgkmcnt(0)
	v_readfirstlane_b32 s9, v191
	s_add_i32 s35, s35, 1
	s_and_b32 s27, s9, 0xffff
	s_lshr_b32 s8, s9, 16
	s_cmp_lt_i32 s35, s25
	s_cbranch_scc1 .Lbm3_blkB
	s_branch .Lbm3_done
.Lbm3_blkB:
	s_lshl_b32 s29, s38, 12
	s_add_u32 s30, s62, s29
	s_addc_u32 s31, s63, 0
	global_load_dwordx4 v[118:121], v82, s[30:31]
	global_load_dwordx4 v[122:125], v82, s[30:31] offset:1024
	global_load_dwordx4 v[126:129], v82, s[30:31] offset:2048
	global_load_dwordx4 v[130:133], v82, s[30:31] offset:3072
	s_lshl_b32 s29, s27, 12
	s_add_u32 s30, s40, s29
	s_addc_u32 s31, s41, 0
	global_load_dwordx4 v[2:5], v82, s[30:31]
	global_load_dwordx4 v[6:9], v82, s[30:31] offset:1024
	global_load_dwordx4 v[12:15], v82, s[30:31] offset:2048
	global_load_dwordx4 v[16:19], v82, s[30:31] offset:3072
	s_add_i32 s50, s35, 2
	s_add_i32 s9, s25, -1
	s_min_i32 s50, s50, s9
	s_lshl_b32 s9, s50, 2
	s_add_i32 s9, s9, s46
	v_mov_b32_e32 v191, s9
	ds_read_b32 v191, v191 offset:16384
	s_cmp_ge_i32 s38, s21
	s_cselect_b32 s50, 1, 0
	s_bfe_u32 s29, s48, 0x40000
	s_cmp_eq_u32 s29, 0
	s_cbranch_scc1 .Lbm3_Bg0_skip
	s_waitcnt vmcnt(8)
	v_mfma_f32_16x16x32_fp8_fp8 v[76:79], v[176:177], v[100:101], 0
	v_mfma_f32_16x16x32_fp8_fp8 v[182:185], v[204:205], v[100:101], 0
	v_mfma_f32_16x16x32_fp8_fp8 v[186:189], v[208:209], v[100:101], 0
	v_mfma_f32_16x16x32_fp8_fp8 v[244:247], v[248:249], v[100:101], 0
	v_mfma_f32_16x16x32_fp8_fp8 v[76:79], v[178:179], v[102:103], v[76:79]
	v_mfma_f32_16x16x32_fp8_fp8 v[182:185], v[206:207], v[102:103], v[182:185]
	v_mfma_f32_16x16x32_fp8_fp8 v[186:189], v[210:211], v[102:103], v[186:189]
	v_mfma_f32_16x16x32_fp8_fp8 v[244:247], v[250:251], v[102:103], v[244:247]
	s_mov_b64 s[4:5], 0
	s_bitcmp1_b32 s29, 0
	s_cselect_b64 s[6:7], s[10:11], 0
	s_or_b64 s[4:5], s[4:5], s[6:7]
	s_bitcmp1_b32 s29, 1
	s_cselect_b64 s[6:7], s[12:13], 0
	s_or_b64 s[4:5], s[4:5], s[6:7]
	s_bitcmp1_b32 s29, 2
	s_cselect_b64 s[6:7], s[54:55], 0
	s_or_b64 s[4:5], s[4:5], s[6:7]
	s_bitcmp1_b32 s29, 3
	s_cselect_b64 s[6:7], s[70:71], 0
	s_or_b64 s[4:5], s[4:5], s[6:7]
	s_cmp_eq_u32 s50, 1
	s_cbranch_scc1 .Lbm3_Bg0_near
	v_add_f32_e32 v190, v81, v174
	v_cndmask_b32_e64 v190, v69, v190, s[4:5]
	v_fmamk_f32 v76, v76, 0x3e38aa3b, v190
	v_fmamk_f32 v77, v77, 0x3e38aa3b, v190
	v_fmamk_f32 v78, v78, 0x3e38aa3b, v190
	v_fmamk_f32 v79, v79, 0x3e38aa3b, v190
	v_fmamk_f32 v182, v182, 0x3e38aa3b, v190
	v_fmamk_f32 v183, v183, 0x3e38aa3b, v190
	v_fmamk_f32 v184, v184, 0x3e38aa3b, v190
	v_fmamk_f32 v185, v185, 0x3e38aa3b, v190
	v_fmamk_f32 v186, v186, 0x3e38aa3b, v190
	v_fmamk_f32 v187, v187, 0x3e38aa3b, v190
	v_fmamk_f32 v188, v188, 0x3e38aa3b, v190
	v_fmamk_f32 v189, v189, 0x3e38aa3b, v190
	v_fmamk_f32 v244, v244, 0x3e38aa3b, v190
	v_fmamk_f32 v245, v245, 0x3e38aa3b, v190
	v_fmamk_f32 v246, v246, 0x3e38aa3b, v190
	v_fmamk_f32 v247, v247, 0x3e38aa3b, v190

.Lbm3_Bg0_skip:
	s_bfe_u32 s29, s48, 0x40004
	s_cmp_eq_u32 s29, 0
	s_cbranch_scc1 .Lbm3_Bg1_skip
	s_waitcnt vmcnt(8)
	v_mfma_f32_16x16x32_fp8_fp8 v[76:79], v[176:177], v[106:107], 0
	v_mfma_f32_16x16x32_fp8_fp8 v[182:185], v[204:205], v[106:107], 0
	v_mfma_f32_16x16x32_fp8_fp8 v[186:189], v[208:209], v[106:107], 0
	v_mfma_f32_16x16x32_fp8_fp8 v[244:247], v[248:249], v[106:107], 0
	v_mfma_f32_16x16x32_fp8_fp8 v[76:79], v[178:179], v[108:109], v[76:79]
	v_mfma_f32_16x16x32_fp8_fp8 v[182:185], v[206:207], v[108:109], v[182:185]
	v_mfma_f32_16x16x32_fp8_fp8 v[186:189], v[210:211], v[108:109], v[186:189]
	v_mfma_f32_16x16x32_fp8_fp8 v[244:247], v[250:251], v[108:109], v[244:247]
	s_mov_b64 s[4:5], 0
	s_bitcmp1_b32 s29, 0
	s_cselect_b64 s[6:7], s[10:11], 0
	s_or_b64 s[4:5], s[4:5], s[6:7]
	s_bitcmp1_b32 s29, 1
	s_cselect_b64 s[6:7], s[12:13], 0
	s_or_b64 s[4:5], s[4:5], s[6:7]
	s_bitcmp1_b32 s29, 2
	s_cselect_b64 s[6:7], s[54:55], 0
	s_or_b64 s[4:5], s[4:5], s[6:7]
	s_bitcmp1_b32 s29, 3
	s_cselect_b64 s[6:7], s[70:71], 0
	s_or_b64 s[4:5], s[4:5], s[6:7]
	s_cmp_eq_u32 s50, 1
	s_cbranch_scc1 .Lbm3_Bg1_near
	v_add_f32_e32 v190, v81, v175
	v_cndmask_b32_e64 v190, v69, v190, s[4:5]
	v_fmamk_f32 v76, v76, 0x3e38aa3b, v190
	v_fmamk_f32 v77, v77, 0x3e38aa3b, v190
	v_fmamk_f32 v78, v78, 0x3e38aa3b, v190
	v_fmamk_f32 v79, v79, 0x3e38aa3b, v190
	v_fmamk_f32 v182, v182, 0x3e38aa3b, v190
	v_fmamk_f32 v183, v183, 0x3e38aa3b, v190
	v_fmamk_f32 v184, v184, 0x3e38aa3b, v190
	v_fmamk_f32 v185, v185, 0x3e38aa3b, v190
	v_fmamk_f32 v186, v186, 0x3e38aa3b, v190
	v_fmamk_f32 v187, v187, 0x3e38aa3b, v190
	v_fmamk_f32 v188, v188, 0x3e38aa3b, v190
	v_fmamk_f32 v189, v189, 0x3e38aa3b, v190
	v_fmamk_f32 v244, v244, 0x3e38aa3b, v190
	v_fmamk_f32 v245, v245, 0x3e38aa3b, v190
	v_fmamk_f32 v246, v246, 0x3e38aa3b, v190
	v_fmamk_f32 v247, v247, 0x3e38aa3b, v190

.Lbm3_Bg1_skip:
	s_bfe_u32 s29, s48, 0x40008
	s_cmp_eq_u32 s29, 0
	s_cbranch_scc1 .Lbm3_Bg2_skip
	s_waitcnt vmcnt(8)
	v_mfma_f32_16x16x32_fp8_fp8 v[76:79], v[176:177], v[110:111], 0
	v_mfma_f32_16x16x32_fp8_fp8 v[182:185], v[204:205], v[110:111], 0
	v_mfma_f32_16x16x32_fp8_fp8 v[186:189], v[208:209], v[110:111], 0
	v_mfma_f32_16x16x32_fp8_fp8 v[244:247], v[248:249], v[110:111], 0
	v_mfma_f32_16x16x32_fp8_fp8 v[76:79], v[178:179], v[112:113], v[76:79]
	v_mfma_f32_16x16x32_fp8_fp8 v[182:185], v[206:207], v[112:113], v[182:185]
	v_mfma_f32_16x16x32_fp8_fp8 v[186:189], v[210:211], v[112:113], v[186:189]
	v_mfma_f32_16x16x32_fp8_fp8 v[244:247], v[250:251], v[112:113], v[244:247]
	s_mov_b64 s[4:5], 0
	s_bitcmp1_b32 s29, 0
	s_cselect_b64 s[6:7], s[10:11], 0
	s_or_b64 s[4:5], s[4:5], s[6:7]
	s_bitcmp1_b32 s29, 1
	s_cselect_b64 s[6:7], s[12:13], 0
	s_or_b64 s[4:5], s[4:5], s[6:7]
	s_bitcmp1_b32 s29, 2
	s_cselect_b64 s[6:7], s[54:55], 0
	s_or_b64 s[4:5], s[4:5], s[6:7]
	s_bitcmp1_b32 s29, 3
	s_cselect_b64 s[6:7], s[70:71], 0
	s_or_b64 s[4:5], s[4:5], s[6:7]
	s_cmp_eq_u32 s50, 1
	s_cbranch_scc1 .Lbm3_Bg2_near
	v_add_f32_e32 v190, v81, v202
	v_cndmask_b32_e64 v190, v69, v190, s[4:5]
	v_fmamk_f32 v76, v76, 0x3e38aa3b, v190
	v_fmamk_f32 v77, v77, 0x3e38aa3b, v190
	v_fmamk_f32 v78, v78, 0x3e38aa3b, v190
	v_fmamk_f32 v79, v79, 0x3e38aa3b, v190
	v_fmamk_f32 v182, v182, 0x3e38aa3b, v190
	v_fmamk_f32 v183, v183, 0x3e38aa3b, v190
	v_fmamk_f32 v184, v184, 0x3e38aa3b, v190
	v_fmamk_f32 v185, v185, 0x3e38aa3b, v190
	v_fmamk_f32 v186, v186, 0x3e38aa3b, v190
	v_fmamk_f32 v187, v187, 0x3e38aa3b, v190
	v_fmamk_f32 v188, v188, 0x3e38aa3b, v190
	v_fmamk_f32 v189, v189, 0x3e38aa3b, v190
	v_fmamk_f32 v244, v244, 0x3e38aa3b, v190
	v_fmamk_f32 v245, v245, 0x3e38aa3b, v190
	v_fmamk_f32 v246, v246, 0x3e38aa3b, v190
	v_fmamk_f32 v247, v247, 0x3e38aa3b, v190

.Lbm3_Bg2_skip:
	s_bfe_u32 s29, s48, 0x4000c
	s_cmp_eq_u32 s29, 0
	s_cbranch_scc1 .Lbm3_Bg3_skip
	s_waitcnt vmcnt(8)
	v_mfma_f32_16x16x32_fp8_fp8 v[76:79], v[176:177], v[114:115], 0
	v_mfma_f32_16x16x32_fp8_fp8 v[182:185], v[204:205], v[114:115], 0
	v_mfma_f32_16x16x32_fp8_fp8 v[186:189], v[208:209], v[114:115], 0
	v_mfma_f32_16x16x32_fp8_fp8 v[244:247], v[248:249], v[114:115], 0
	v_mfma_f32_16x16x32_fp8_fp8 v[76:79], v[178:179], v[116:117], v[76:79]
	v_mfma_f32_16x16x32_fp8_fp8 v[182:185], v[206:207], v[116:117], v[182:185]
	v_mfma_f32_16x16x32_fp8_fp8 v[186:189], v[210:211], v[116:117], v[186:189]
	v_mfma_f32_16x16x32_fp8_fp8 v[244:247], v[250:251], v[116:117], v[244:247]
	s_mov_b64 s[4:5], 0
	s_bitcmp1_b32 s29, 0
	s_cselect_b64 s[6:7], s[10:11], 0
	s_or_b64 s[4:5], s[4:5], s[6:7]
	s_bitcmp1_b32 s29, 1
	s_cselect_b64 s[6:7], s[12:13], 0
	s_or_b64 s[4:5], s[4:5], s[6:7]
	s_bitcmp1_b32 s29, 2
	s_cselect_b64 s[6:7], s[54:55], 0
	s_or_b64 s[4:5], s[4:5], s[6:7]
	s_bitcmp1_b32 s29, 3
	s_cselect_b64 s[6:7], s[70:71], 0
	s_or_b64 s[4:5], s[4:5], s[6:7]
	s_cmp_eq_u32 s50, 1
	s_cbranch_scc1 .Lbm3_Bg3_near
	v_add_f32_e32 v190, v81, v203
	v_cndmask_b32_e64 v190, v69, v190, s[4:5]
	v_fmamk_f32 v76, v76, 0x3e38aa3b, v190
	v_fmamk_f32 v77, v77, 0x3e38aa3b, v190
	v_fmamk_f32 v78, v78, 0x3e38aa3b, v190
	v_fmamk_f32 v79, v79, 0x3e38aa3b, v190
	v_fmamk_f32 v182, v182, 0x3e38aa3b, v190
	v_fmamk_f32 v183, v183, 0x3e38aa3b, v190
	v_fmamk_f32 v184, v184, 0x3e38aa3b, v190
	v_fmamk_f32 v185, v185, 0x3e38aa3b, v190
	v_fmamk_f32 v186, v186, 0x3e38aa3b, v190
	v_fmamk_f32 v187, v187, 0x3e38aa3b, v190
	v_fmamk_f32 v188, v188, 0x3e38aa3b, v190
	v_fmamk_f32 v189, v189, 0x3e38aa3b, v190
	v_fmamk_f32 v244, v244, 0x3e38aa3b, v190
	v_fmamk_f32 v245, v245, 0x3e38aa3b, v190
	v_fmamk_f32 v246, v246, 0x3e38aa3b, v190
	v_fmamk_f32 v247, v247, 0x3e38aa3b, v190

.Lbm3_done:
	s_waitcnt vmcnt(0)
	v_and_b32_e32 v252, 15, v181
	v_lshrrev_b32_e32 v68, 4, v181
	v_lshrrev_b32_e32 v191, 2, v252
	v_add_u32_e32 v191, s23, v191
	v_lshlrev_b32_e32 v252, 8, v252
	v_lshl_add_u32 v252, v68, 4, v252
	v_add_u32_e32 v190, s46, v252
	v_mad_u64_u32 v[252:253], s[6:7], v191, v213, v[74:75]
	global_load_dword v12, v[252:253], off offset:4
	v_add_u32_e32 v68, 4, v191
	v_mad_u64_u32 v[252:253], s[6:7], v68, v213, v[74:75]
	global_load_dword v13, v[252:253], off offset:4
	v_add_u32_e32 v68, 8, v191
	v_mad_u64_u32 v[252:253], s[6:7], v68, v213, v[74:75]
	global_load_dword v14, v[252:253], off offset:4
	v_add_u32_e32 v68, 12, v191
	v_mad_u64_u32 v[252:253], s[6:7], v68, v213, v[74:75]
	global_load_dword v15, v[252:253], off offset:4
	v_mov_b32_e32 v105, v70
	s_nop 1
	v_permlane16_swap_b32_e32 v70, v105
	s_nop 0
	v_add_f32_e32 v70, v70, v105
	v_mov_b32_e32 v105, v70
	s_nop 1
	v_permlane32_swap_b32_e32 v70, v105
	s_nop 0
	v_add_f32_e32 v70, v70, v105
	v_max_f32_e32 v70, 0xda24260, v70
	v_mov_b32_e32 v105, v71
	s_nop 1
	v_permlane16_swap_b32_e32 v71, v105
	s_nop 0
	v_add_f32_e32 v71, v71, v105
	v_mov_b32_e32 v105, v71
	s_nop 1
	v_permlane32_swap_b32_e32 v71, v105
	s_nop 0
	v_add_f32_e32 v71, v71, v105
	v_max_f32_e32 v71, 0xda24260, v71
	v_mov_b32_e32 v105, v72
	s_nop 1
	v_permlane16_swap_b32_e32 v72, v105
	s_nop 0
	v_add_f32_e32 v72, v72, v105
	v_mov_b32_e32 v105, v72
	s_nop 1
	v_permlane32_swap_b32_e32 v72, v105
	s_nop 0
	v_add_f32_e32 v72, v72, v105
	v_max_f32_e32 v72, 0xda24260, v72
	v_mov_b32_e32 v105, v73
	s_nop 1
	v_permlane16_swap_b32_e32 v73, v105
	s_nop 0
	v_add_f32_e32 v73, v73, v105
	v_mov_b32_e32 v105, v73
	s_nop 1
	v_permlane32_swap_b32_e32 v73, v105
	s_nop 0
	v_add_f32_e32 v73, v73, v105
	v_max_f32_e32 v73, 0xda24260, v73
	s_waitcnt vmcnt(0)
	v_div_scale_f32 v2, s[6:7], v70, v70, v12
	v_rcp_f32_e32 v3, v2
	s_nop 0
	v_fma_f32 v4, -v2, v3, 1.0
	v_fmac_f32_e32 v3, v4, v3
	v_div_scale_f32 v4, vcc, v12, v70, v12
	v_mul_f32_e32 v5, v4, v3
	v_fma_f32 v6, -v2, v5, v4
	v_fmac_f32_e32 v5, v6, v3
	v_fma_f32 v2, -v2, v5, v4
	v_div_fmas_f32 v2, v2, v3, v5
	v_div_fixup_f32 v254, v2, v70, v12
	ds_read_b128 v[16:19], v190 offset:0
	s_waitcnt lgkmcnt(0)
	v_pk_fma_f32 v[20:21], v[20:21], v[254:255], v[16:17] op_sel_hi:[1,0,1]
	v_pk_fma_f32 v[22:23], v[22:23], v[254:255], v[18:19] op_sel_hi:[1,0,1]
	ds_write_b128 v190, v[20:23] offset:0
	ds_read_b128 v[16:19], v190 offset:64
	s_waitcnt lgkmcnt(0)
	v_pk_fma_f32 v[24:25], v[24:25], v[254:255], v[16:17] op_sel_hi:[1,0,1]
	v_pk_fma_f32 v[26:27], v[26:27], v[254:255], v[18:19] op_sel_hi:[1,0,1]
	ds_write_b128 v190, v[24:27] offset:64
	ds_read_b128 v[16:19], v190 offset:128
	s_waitcnt lgkmcnt(0)
	v_pk_fma_f32 v[28:29], v[28:29], v[254:255], v[16:17] op_sel_hi:[1,0,1]
	v_pk_fma_f32 v[30:31], v[30:31], v[254:255], v[18:19] op_sel_hi:[1,0,1]
	ds_write_b128 v190, v[28:31] offset:128
	ds_read_b128 v[16:19], v190 offset:192
	s_waitcnt lgkmcnt(0)
	v_pk_fma_f32 v[32:33], v[32:33], v[254:255], v[16:17] op_sel_hi:[1,0,1]
	v_pk_fma_f32 v[34:35], v[34:35], v[254:255], v[18:19] op_sel_hi:[1,0,1]
	ds_write_b128 v190, v[32:35] offset:192
	v_div_scale_f32 v2, s[6:7], v71, v71, v13
	v_rcp_f32_e32 v3, v2
	s_nop 0
	v_fma_f32 v4, -v2, v3, 1.0
	v_fmac_f32_e32 v3, v4, v3
	v_div_scale_f32 v4, vcc, v13, v71, v13
	v_mul_f32_e32 v5, v4, v3
	v_fma_f32 v6, -v2, v5, v4
	v_fmac_f32_e32 v5, v6, v3
	v_fma_f32 v2, -v2, v5, v4
	v_div_fmas_f32 v2, v2, v3, v5
	v_div_fixup_f32 v254, v2, v71, v13
	ds_read_b128 v[16:19], v190 offset:4096
	s_waitcnt lgkmcnt(0)
	v_pk_fma_f32 v[36:37], v[36:37], v[254:255], v[16:17] op_sel_hi:[1,0,1]
	v_pk_fma_f32 v[38:39], v[38:39], v[254:255], v[18:19] op_sel_hi:[1,0,1]
	ds_write_b128 v190, v[36:39] offset:4096
	ds_read_b128 v[16:19], v190 offset:4160
	s_waitcnt lgkmcnt(0)
	v_pk_fma_f32 v[40:41], v[40:41], v[254:255], v[16:17] op_sel_hi:[1,0,1]
	v_pk_fma_f32 v[42:43], v[42:43], v[254:255], v[18:19] op_sel_hi:[1,0,1]
	ds_write_b128 v190, v[40:43] offset:4160
	ds_read_b128 v[16:19], v190 offset:4224
	s_waitcnt lgkmcnt(0)
	v_pk_fma_f32 v[44:45], v[44:45], v[254:255], v[16:17] op_sel_hi:[1,0,1]
	v_pk_fma_f32 v[46:47], v[46:47], v[254:255], v[18:19] op_sel_hi:[1,0,1]
	ds_write_b128 v190, v[44:47] offset:4224
	ds_read_b128 v[16:19], v190 offset:4288
	s_waitcnt lgkmcnt(0)
	v_pk_fma_f32 v[48:49], v[48:49], v[254:255], v[16:17] op_sel_hi:[1,0,1]
	v_pk_fma_f32 v[50:51], v[50:51], v[254:255], v[18:19] op_sel_hi:[1,0,1]
	ds_write_b128 v190, v[48:51] offset:4288
	v_div_scale_f32 v2, s[6:7], v72, v72, v14
	v_rcp_f32_e32 v3, v2
	s_nop 0
	v_fma_f32 v4, -v2, v3, 1.0
	v_fmac_f32_e32 v3, v4, v3
	v_div_scale_f32 v4, vcc, v14, v72, v14
	v_mul_f32_e32 v5, v4, v3
	v_fma_f32 v6, -v2, v5, v4
	v_fmac_f32_e32 v5, v6, v3
	v_fma_f32 v2, -v2, v5, v4
	v_div_fmas_f32 v2, v2, v3, v5
	v_div_fixup_f32 v254, v2, v72, v14
	ds_read_b128 v[16:19], v190 offset:8192
	s_waitcnt lgkmcnt(0)
	v_pk_fma_f32 v[52:53], v[52:53], v[254:255], v[16:17] op_sel_hi:[1,0,1]
	v_pk_fma_f32 v[54:55], v[54:55], v[254:255], v[18:19] op_sel_hi:[1,0,1]
	ds_write_b128 v190, v[52:55] offset:8192
	ds_read_b128 v[16:19], v190 offset:8256
	s_waitcnt lgkmcnt(0)
	v_pk_fma_f32 v[56:57], v[56:57], v[254:255], v[16:17] op_sel_hi:[1,0,1]
	v_pk_fma_f32 v[58:59], v[58:59], v[254:255], v[18:19] op_sel_hi:[1,0,1]
	ds_write_b128 v190, v[56:59] offset:8256
	ds_read_b128 v[16:19], v190 offset:8320
	s_waitcnt lgkmcnt(0)
	v_pk_fma_f32 v[60:61], v[60:61], v[254:255], v[16:17] op_sel_hi:[1,0,1]
	v_pk_fma_f32 v[62:63], v[62:63], v[254:255], v[18:19] op_sel_hi:[1,0,1]
	ds_write_b128 v190, v[60:63] offset:8320
	ds_read_b128 v[16:19], v190 offset:8384
	s_waitcnt lgkmcnt(0)
	v_pk_fma_f32 v[64:65], v[64:65], v[254:255], v[16:17] op_sel_hi:[1,0,1]
	v_pk_fma_f32 v[66:67], v[66:67], v[254:255], v[18:19] op_sel_hi:[1,0,1]
	ds_write_b128 v190, v[64:67] offset:8384
	v_div_scale_f32 v2, s[6:7], v73, v73, v15
	v_rcp_f32_e32 v3, v2
	s_nop 0
	v_fma_f32 v4, -v2, v3, 1.0
	v_fmac_f32_e32 v3, v4, v3
	v_div_scale_f32 v4, vcc, v15, v73, v15
	v_mul_f32_e32 v5, v4, v3
	v_fma_f32 v6, -v2, v5, v4
	v_fmac_f32_e32 v5, v6, v3
	v_fma_f32 v2, -v2, v5, v4
	v_div_fmas_f32 v2, v2, v3, v5
	v_div_fixup_f32 v254, v2, v73, v15
	ds_read_b128 v[16:19], v190 offset:12288
	s_waitcnt lgkmcnt(0)
	v_pk_fma_f32 v[84:85], v[84:85], v[254:255], v[16:17] op_sel_hi:[1,0,1]
	v_pk_fma_f32 v[86:87], v[86:87], v[254:255], v[18:19] op_sel_hi:[1,0,1]
	ds_write_b128 v190, v[84:87] offset:12288
	ds_read_b128 v[16:19], v190 offset:12352
	s_waitcnt lgkmcnt(0)
	v_pk_fma_f32 v[88:89], v[88:89], v[254:255], v[16:17] op_sel_hi:[1,0,1]
	v_pk_fma_f32 v[90:91], v[90:91], v[254:255], v[18:19] op_sel_hi:[1,0,1]
	ds_write_b128 v190, v[88:91] offset:12352
	ds_read_b128 v[16:19], v190 offset:12416
	s_waitcnt lgkmcnt(0)
	v_pk_fma_f32 v[92:93], v[92:93], v[254:255], v[16:17] op_sel_hi:[1,0,1]
	v_pk_fma_f32 v[94:95], v[94:95], v[254:255], v[18:19] op_sel_hi:[1,0,1]
	ds_write_b128 v190, v[92:95] offset:12416
	ds_read_b128 v[16:19], v190 offset:12480
	s_waitcnt lgkmcnt(0)
	v_pk_fma_f32 v[96:97], v[96:97], v[254:255], v[16:17] op_sel_hi:[1,0,1]
	v_pk_fma_f32 v[98:99], v[98:99], v[254:255], v[18:19] op_sel_hi:[1,0,1]
	ds_write_b128 v190, v[96:99] offset:12480
	v_mov_b32_e32 v174, 0x3727c5ac
	v_mov_b32_e32 v175, 0xe0000
	v_mov_b32_e32 v176, 0x200
	v_mov_b32_e32 v177, 0
	v_mov_b32_e32 v178, 0x1ff
	v_mov_b32_e32 v179, 0
	v_mov_b32_e32 v202, 0xe1000
	v_mov_b32_e32 v203, 0xffff
	v_mov_b32_e32 v204, 1
	v_mov_b32_e32 v205, 0x7f800000
	v_mov_b32_e32 v206, 0x7fc00000
	v_mov_b32_e32 v207, 0xff800000
	v_mov_b32_e32 v209, 0x1e000
	v_mov_b32_e32 v210, 0x24000
	v_mov_b32_e32 v211, 0x2a000
	v_mov_b32_e32 v208, v181
	s_waitcnt lgkmcnt(0)
	s_branch .LBB0_2088
